# v28 (all K-loop LDS-DMA in scalar-base form, segment-4 bases rebuilt with SALU) + loop-invariant LDS read bases hoisted: no VALU left in K-loop load segments
# speedup vs baseline: 1.0067x; 1.0001x over previous
; #define PG8_STAGE(bufoff, gbase, voff) do { _Pragma("unroll") for (int _i = 0; _i < 2; ++_i) \
;         __builtin_amdgcn_global_load_lds((const unsigned*)((const char*)(gbase) + (voff)[_i]), (PG8_LAS unsigned*)(lds + (bufoff) + ldsw + _i * 8192), 16, 0, 0); } while (0)
; #define PG8_LDA(dst, b, h) do { _Pragma("unroll") for (int m = 0; m < 4; ++m) _Pragma("unroll") for (int k = 0; k < 2; ++k) dst[m][k] = *(const PG8_LAS bf16x8*)(lds + PG8_SA(b, h) + aoff + m * 2048 + k * 1024); } while (0)
; #define PG8_LDB(dst, b, h) do { _Pragma("unroll") for (int n = 0; n < 2; ++n) _Pragma("unroll") for (int k = 0; k < 2; ++k) dst[n][k] = *(const PG8_LAS bf16x8*)(lds + PG8_SB(b, h) + boff + n * 2048 + k * 1024); } while (0)
; #define PG8_WAIT_V(n) asm volatile("s_waitcnt vmcnt(" #n ")" ::: "memory")
; #define PG8_WAIT_L(n) asm volatile("s_waitcnt lgkmcnt(" #n ")" ::: "memory")
; #define PG8_BAR __builtin_amdgcn_s_barrier()
; #define PG8_SCHED __builtin_amdgcn_sched_barrier(0)
; template <class Epi, class Sched, bool ALIGN_EPI = false, bool SP2 = false, bool F16 = false>
; __device__ __forceinline__ void gemm_phase(PG8_LAS unsigned char* lds, const Gemm g, const Sched& S, const Epi& E) {
;     ...
;         for (int t = 0; t < nt; t += 2) {
;             const bool last = (t == nt - 2);
;             const char* a1 = cA + (size_t)(t + 1) * kstep;
;             const char* a2 = last ? nA : cA + (size_t)(t + 2) * kstep; const char* b2 = last ? nB : cB + (size_t)(t + 2) * kstep;
;             const char* a3 = a2 + kstep; const char* b3 = b2 + kstep;
;             if (last && has_next) S.a_ready(nxt);
;             if constexpr (SP2) {
;             PG8_LDB(B0, 0, 0); PG8_LDB(B1, 0, 1); PG8_SCHED; PG8_LDA(At, 0, 0); PG8_STAGE(PG8_SA(1, 1), a1 + hstepA, voffA);
;             PG8_WAIT_V(8); PG8_WAIT_L(0); PG8_BAR; PG8_MMA(0, 0, At, B0); PG8_MMA(0, 1, At, B1); PG8_BAR; PG8_SCHED;
;             PG8_LDA(At, 0, 1); PG8_STAGE(PG8_SB(0, 0), b2, voffB); PG8_STAGE(PG8_SB(0, 1), b2 + hstepB, voffB); PG8_STAGE(PG8_SA(0, 0), a2, voffA);
;             PG8_WAIT_V(8); PG8_WAIT_L(0); PG8_BAR; PG8_MMA(1, 0, At, B0); PG8_MMA(1, 1, At, B1); PG8_BAR; PG8_SCHED;
.LBB0_308:
	s_andn2_b64 vcc, exec, s[4:5]
	s_waitcnt vmcnt(0)
	s_cbranch_vccnz .Lzk_gu
	s_add_u32 s52, s52, 0x80
	s_addc_u32 s53, s53, 0
	s_add_u32 s80, s54, 0x100
	s_addc_u32 s81, s55, 0
	s_mov_b32 s54, 0
	v_add_u32_e32 v139, 0x10000, v165
	v_add_u32_e32 v141, 0x14000, v165
	v_add_u32_e32 v143, 0x18000, v165
	v_add_u32_e32 v145, 0x1c000, v165
.Lpk_gu:
	s_add_i32 s82, s54, 2
	s_add_u32 s83, s52, 0x80
	s_addc_u32 s55, s53, 0
	s_add_i32 vcc_lo, 0, 0x10000
	s_cmp_eq_u32 s74, s54
	s_cselect_b32 s55, s39, s55
	s_cselect_b32 s54, s38, s83
	s_cselect_b32 s95, s47, s81
	s_cselect_b32 s94, s46, s80
	s_add_i32 s83, 0, 0x14000
	ds_read_b128 v[130:133], v139
	ds_read_b128 v[134:137], v139 offset:1024
	ds_read_b128 v[152:155], v139 offset:2048
	ds_read_b128 v[156:159], v139 offset:3072
	ds_read_b128 v[160:163], v141
	ds_read_b128 v[166:169], v141 offset:1024
	ds_read_b128 v[184:187], v141 offset:2048
	ds_read_b128 v[188:191], v141 offset:3072
	s_add_i32 m0, s22, 0xc000
	ds_read_b128 v[192:195], v183
	ds_read_b128 v[204:207], v183 offset:1024
	ds_read_b128 v[208:211], v183 offset:2048
	ds_read_b128 v[212:215], v183 offset:3072
	ds_read_b128 v[216:219], v183 offset:4096
	ds_read_b128 v[220:223], v183 offset:5120
	ds_read_b128 v[224:227], v183 offset:6144
	ds_read_b128 v[228:231], v183 offset:7168
	global_load_lds_dwordx4 v148, s[52:53]
	s_add_i32 m0, s22, 0xe000
	s_nop 0
	global_load_lds_dwordx4 v150, s[52:53]
	s_waitcnt vmcnt(8)
	s_waitcnt lgkmcnt(0)
	s_setprio 1
	s_barrier
	v_mfma_f32_16x16x32_f16 v[122:125], v[130:133], v[192:195], 0
	v_mfma_f32_16x16x32_f16 v[114:117], v[152:155], v[192:195], 0
	v_mfma_f32_16x16x32_f16 v[106:109], v[130:133], v[208:211], 0
	v_mfma_f32_16x16x32_f16 v[98:101], v[152:155], v[208:211], 0
	v_mfma_f32_16x16x32_f16 v[90:93], v[130:133], v[216:219], 0
	v_mfma_f32_16x16x32_f16 v[82:85], v[152:155], v[216:219], 0
	v_mfma_f32_16x16x32_f16 v[74:77], v[130:133], v[224:227], 0
	v_mfma_f32_16x16x32_f16 v[66:69], v[152:155], v[224:227], 0
	v_mfma_f32_16x16x32_f16 v[122:125], v[134:137], v[204:207], v[122:125]
	v_mfma_f32_16x16x32_f16 v[114:117], v[156:159], v[204:207], v[114:117]
	v_mfma_f32_16x16x32_f16 v[106:109], v[134:137], v[212:215], v[106:109]
	v_mfma_f32_16x16x32_f16 v[98:101], v[156:159], v[212:215], v[98:101]
	v_mfma_f32_16x16x32_f16 v[90:93], v[134:137], v[220:223], v[90:93]
	v_mfma_f32_16x16x32_f16 v[82:85], v[156:159], v[220:223], v[82:85]
	v_mfma_f32_16x16x32_f16 v[74:77], v[134:137], v[228:231], v[74:77]
	v_mfma_f32_16x16x32_f16 v[66:69], v[156:159], v[228:231], v[66:69]
	v_mfma_f32_16x16x32_f16 v[126:129], v[160:163], v[192:195], 0
	v_mfma_f32_16x16x32_f16 v[118:121], v[184:187], v[192:195], 0
	v_mfma_f32_16x16x32_f16 v[110:113], v[160:163], v[208:211], 0
	v_mfma_f32_16x16x32_f16 v[102:105], v[184:187], v[208:211], 0
	v_mfma_f32_16x16x32_f16 v[94:97], v[160:163], v[216:219], 0
	v_mfma_f32_16x16x32_f16 v[86:89], v[184:187], v[216:219], 0
	v_mfma_f32_16x16x32_f16 v[78:81], v[160:163], v[224:227], 0
	v_mfma_f32_16x16x32_f16 v[70:73], v[184:187], v[224:227], 0
	v_mfma_f32_16x16x32_f16 v[126:129], v[166:169], v[204:207], v[126:129]
	v_mfma_f32_16x16x32_f16 v[118:121], v[188:191], v[204:207], v[118:121]
	v_mfma_f32_16x16x32_f16 v[110:113], v[166:169], v[212:215], v[110:113]
	v_mfma_f32_16x16x32_f16 v[102:105], v[188:191], v[212:215], v[102:105]
	v_mfma_f32_16x16x32_f16 v[94:97], v[166:169], v[220:223], v[94:97]
	v_mfma_f32_16x16x32_f16 v[86:89], v[188:191], v[220:223], v[86:89]
	v_mfma_f32_16x16x32_f16 v[78:81], v[166:169], v[228:231], v[78:81]
	v_mfma_f32_16x16x32_f16 v[70:73], v[188:191], v[228:231], v[70:73]
	s_barrier
	s_setprio 0
	s_add_i32 vcc_lo, vcc_lo, s2
	s_mov_b32 m0, vcc_lo
	s_nop 0
	global_load_lds_dwordx4 v142, s[94:95]
	ds_read_b128 v[192:195], v183 offset:16384
	ds_read_b128 v[204:207], v183 offset:17408
	ds_read_b128 v[208:211], v183 offset:18432
	ds_read_b128 v[212:215], v183 offset:19456
	ds_read_b128 v[216:219], v183 offset:20480
	ds_read_b128 v[220:223], v183 offset:21504
	ds_read_b128 v[224:227], v183 offset:22528
	ds_read_b128 v[228:231], v183 offset:23552
	s_add_i32 m0, vcc_lo, 0x2000
	s_nop 0
	global_load_lds_dwordx4 v138, s[94:95]
	s_add_i32 s83, s83, s2
	s_add_u32 s94, s94, s48
	s_addc_u32 s95, s95, 0
	s_mov_b32 m0, s83
	s_nop 0
	global_load_lds_dwordx4 v142, s[94:95]
	s_add_i32 m0, s83, 0x2000
	s_nop 0
	global_load_lds_dwordx4 v138, s[94:95]
	s_mov_b32 m0, s22
	s_nop 0
	global_load_lds_dwordx4 v144, s[54:55]
	s_mov_b32 m0, s33
	s_nop 0
	global_load_lds_dwordx4 v140, s[54:55]
	s_waitcnt vmcnt(8)
	s_waitcnt lgkmcnt(0)
	s_setprio 1
	s_barrier
	v_mfma_f32_16x16x32_f16 v[58:61], v[130:133], v[192:195], 0
	v_mfma_f32_16x16x32_f16 v[50:53], v[152:155], v[192:195], 0
	v_mfma_f32_16x16x32_f16 v[42:45], v[130:133], v[208:211], 0
	v_mfma_f32_16x16x32_f16 v[34:37], v[152:155], v[208:211], 0
	v_mfma_f32_16x16x32_f16 v[26:29], v[130:133], v[216:219], 0
	v_mfma_f32_16x16x32_f16 v[18:21], v[152:155], v[216:219], 0
	v_mfma_f32_16x16x32_f16 v[10:13], v[130:133], v[224:227], 0
	v_mfma_f32_16x16x32_f16 v[6:9], v[152:155], v[224:227], 0
	v_mfma_f32_16x16x32_f16 v[58:61], v[134:137], v[204:207], v[58:61]
	v_mfma_f32_16x16x32_f16 v[50:53], v[156:159], v[204:207], v[50:53]
	v_mfma_f32_16x16x32_f16 v[42:45], v[134:137], v[212:215], v[42:45]
	v_mfma_f32_16x16x32_f16 v[34:37], v[156:159], v[212:215], v[34:37]
	v_mfma_f32_16x16x32_f16 v[26:29], v[134:137], v[220:223], v[26:29]
	v_mfma_f32_16x16x32_f16 v[18:21], v[156:159], v[220:223], v[18:21]
	v_mfma_f32_16x16x32_f16 v[10:13], v[134:137], v[228:231], v[10:13]
	v_mfma_f32_16x16x32_f16 v[6:9], v[156:159], v[228:231], v[6:9]
	v_mfma_f32_16x16x32_f16 v[62:65], v[160:163], v[192:195], 0
	v_mfma_f32_16x16x32_f16 v[54:57], v[184:187], v[192:195], 0
	v_mfma_f32_16x16x32_f16 v[46:49], v[160:163], v[208:211], 0
	v_mfma_f32_16x16x32_f16 v[38:41], v[184:187], v[208:211], 0
	v_mfma_f32_16x16x32_f16 v[30:33], v[160:163], v[216:219], 0
	v_mfma_f32_16x16x32_f16 v[22:25], v[184:187], v[216:219], 0
	v_mfma_f32_16x16x32_f16 v[14:17], v[160:163], v[224:227], 0
	v_mfma_f32_16x16x32_f16 v[2:5], v[184:187], v[224:227], 0
	v_mfma_f32_16x16x32_f16 v[62:65], v[166:169], v[204:207], v[62:65]
	v_mfma_f32_16x16x32_f16 v[54:57], v[188:191], v[204:207], v[54:57]
	v_mfma_f32_16x16x32_f16 v[46:49], v[166:169], v[212:215], v[46:49]
	v_mfma_f32_16x16x32_f16 v[38:41], v[188:191], v[212:215], v[38:41]
	v_mfma_f32_16x16x32_f16 v[30:33], v[166:169], v[220:223], v[30:33]
	v_mfma_f32_16x16x32_f16 v[22:25], v[188:191], v[220:223], v[22:25]
	v_mfma_f32_16x16x32_f16 v[14:17], v[166:169], v[228:231], v[14:17]
	v_mfma_f32_16x16x32_f16 v[2:5], v[188:191], v[228:231], v[2:5]
	s_barrier
; #define PG8_STAGE(bufoff, gbase, voff) do { _Pragma("unroll") for (int _i = 0; _i < 2; ++_i) \
;         __builtin_amdgcn_global_load_lds((const unsigned*)((const char*)(gbase) + (voff)[_i]), (PG8_LAS unsigned*)(lds + (bufoff) + ldsw + _i * 8192), 16, 0, 0); } while (0)
; #define PG8_LDA(dst, b, h) do { _Pragma("unroll") for (int m = 0; m < 4; ++m) _Pragma("unroll") for (int k = 0; k < 2; ++k) dst[m][k] = *(const PG8_LAS bf16x8*)(lds + PG8_SA(b, h) + aoff + m * 2048 + k * 1024); } while (0)
; #define PG8_LDB(dst, b, h) do { _Pragma("unroll") for (int n = 0; n < 2; ++n) _Pragma("unroll") for (int k = 0; k < 2; ++k) dst[n][k] = *(const PG8_LAS bf16x8*)(lds + PG8_SB(b, h) + boff + n * 2048 + k * 1024); } while (0)
; #define PG8_WAIT_V(n) asm volatile("s_waitcnt vmcnt(" #n ")" ::: "memory")
; #define PG8_WAIT_L(n) asm volatile("s_waitcnt lgkmcnt(" #n ")" ::: "memory")
; #define PG8_BAR __builtin_amdgcn_s_barrier()
; #define PG8_SCHED __builtin_amdgcn_sched_barrier(0)
; template <class Epi, class Sched, bool ALIGN_EPI = false, bool SP2 = false, bool F16 = false>
; __device__ __forceinline__ void gemm_phase(PG8_LAS unsigned char* lds, const Gemm g, const Sched& S, const Epi& E) {
;     ...
;             PG8_LDB(B0, 1, 0); PG8_LDB(B1, 1, 1); PG8_SCHED; PG8_LDA(At, 1, 0); PG8_STAGE(PG8_SA(0, 1), a2 + hstepA, voffA);
;             PG8_WAIT_V(8); PG8_WAIT_L(0); PG8_BAR; PG8_MMA(0, 0, At, B0); PG8_MMA(0, 1, At, B1); PG8_BAR; PG8_SCHED;
;             PG8_LDA(At, 1, 1); PG8_STAGE(PG8_SB(1, 0), b3, voffB); PG8_STAGE(PG8_SB(1, 1), b3 + hstepB, voffB); PG8_STAGE(PG8_SA(1, 0), a3, voffA);
;             PG8_WAIT_V(8); PG8_WAIT_L(0); PG8_BAR; PG8_MMA(1, 0, At, B0); PG8_MMA(1, 1, At, B1); PG8_BAR; PG8_SCHED;
	s_setprio 0
	s_add_i32 s83, 0, 0x18000
	s_add_i32 s94, 0, 0x1c000
	ds_read_b128 v[130:133], v143
	ds_read_b128 v[134:137], v143 offset:1024
	ds_read_b128 v[152:155], v143 offset:2048
	ds_read_b128 v[156:159], v143 offset:3072
	ds_read_b128 v[160:163], v145
	ds_read_b128 v[166:169], v145 offset:1024
	ds_read_b128 v[184:187], v145 offset:2048
	ds_read_b128 v[188:191], v145 offset:3072
	s_add_u32 s54, s54, s8
	s_addc_u32 s55, s55, 0
	s_mov_b32 m0, s12
	ds_read_b128 v[192:195], v183 offset:32768
	ds_read_b128 v[204:207], v183 offset:33792
	ds_read_b128 v[208:211], v183 offset:34816
	ds_read_b128 v[212:215], v183 offset:35840
	ds_read_b128 v[216:219], v183 offset:36864
	ds_read_b128 v[220:223], v183 offset:37888
	ds_read_b128 v[224:227], v183 offset:38912
	ds_read_b128 v[228:231], v183 offset:39936
	global_load_lds_dwordx4 v144, s[54:55]
	s_mov_b32 m0, s13
	s_nop 0
	global_load_lds_dwordx4 v140, s[54:55]
	s_waitcnt vmcnt(8)
	s_waitcnt lgkmcnt(0)
	s_setprio 1
	s_barrier
	v_mfma_f32_16x16x32_f16 v[122:125], v[130:133], v[192:195], v[122:125]
	v_mfma_f32_16x16x32_f16 v[114:117], v[152:155], v[192:195], v[114:117]
	v_mfma_f32_16x16x32_f16 v[106:109], v[130:133], v[208:211], v[106:109]
	v_mfma_f32_16x16x32_f16 v[98:101], v[152:155], v[208:211], v[98:101]
	v_mfma_f32_16x16x32_f16 v[90:93], v[130:133], v[216:219], v[90:93]
	v_mfma_f32_16x16x32_f16 v[82:85], v[152:155], v[216:219], v[82:85]
	v_mfma_f32_16x16x32_f16 v[74:77], v[130:133], v[224:227], v[74:77]
	v_mfma_f32_16x16x32_f16 v[66:69], v[152:155], v[224:227], v[66:69]
	v_mfma_f32_16x16x32_f16 v[122:125], v[134:137], v[204:207], v[122:125]
	v_mfma_f32_16x16x32_f16 v[114:117], v[156:159], v[204:207], v[114:117]
	v_mfma_f32_16x16x32_f16 v[106:109], v[134:137], v[212:215], v[106:109]
	v_mfma_f32_16x16x32_f16 v[98:101], v[156:159], v[212:215], v[98:101]
	v_mfma_f32_16x16x32_f16 v[90:93], v[134:137], v[220:223], v[90:93]
	v_mfma_f32_16x16x32_f16 v[82:85], v[156:159], v[220:223], v[82:85]
	v_mfma_f32_16x16x32_f16 v[74:77], v[134:137], v[228:231], v[74:77]
	v_mfma_f32_16x16x32_f16 v[66:69], v[156:159], v[228:231], v[66:69]
	v_mfma_f32_16x16x32_f16 v[126:129], v[160:163], v[192:195], v[126:129]
	v_mfma_f32_16x16x32_f16 v[118:121], v[184:187], v[192:195], v[118:121]
	v_mfma_f32_16x16x32_f16 v[110:113], v[160:163], v[208:211], v[110:113]
	v_mfma_f32_16x16x32_f16 v[102:105], v[184:187], v[208:211], v[102:105]
	v_mfma_f32_16x16x32_f16 v[94:97], v[160:163], v[216:219], v[94:97]
	v_mfma_f32_16x16x32_f16 v[86:89], v[184:187], v[216:219], v[86:89]
	v_mfma_f32_16x16x32_f16 v[78:81], v[160:163], v[224:227], v[78:81]
	v_mfma_f32_16x16x32_f16 v[70:73], v[184:187], v[224:227], v[70:73]
	v_mfma_f32_16x16x32_f16 v[126:129], v[166:169], v[204:207], v[126:129]
	v_mfma_f32_16x16x32_f16 v[118:121], v[188:191], v[204:207], v[118:121]
	v_mfma_f32_16x16x32_f16 v[110:113], v[166:169], v[212:215], v[110:113]
	v_mfma_f32_16x16x32_f16 v[102:105], v[188:191], v[212:215], v[102:105]
	v_mfma_f32_16x16x32_f16 v[94:97], v[166:169], v[220:223], v[94:97]
	v_mfma_f32_16x16x32_f16 v[86:89], v[188:191], v[220:223], v[86:89]
	v_mfma_f32_16x16x32_f16 v[78:81], v[166:169], v[228:231], v[78:81]
	v_mfma_f32_16x16x32_f16 v[70:73], v[188:191], v[228:231], v[70:73]
	s_barrier
	s_setprio 0
	s_add_i32 s54, s83, s2
	s_add_i32 vcc_hi, s82, -2
	s_cmp_eq_u32 s74, vcc_hi
	s_cselect_b32 s99, s47, s81
	s_cselect_b32 s98, s46, s80
	s_add_u32 s98, s98, s92
	s_addc_u32 s99, s99, s93
	s_mov_b32 m0, s54
	s_nop 0
	global_load_lds_dwordx4 v142, s[98:99]
	ds_read_b128 v[192:195], v183 offset:49152
	ds_read_b128 v[204:207], v183 offset:50176
	ds_read_b128 v[208:211], v183 offset:51200
	ds_read_b128 v[212:215], v183 offset:52224
	ds_read_b128 v[216:219], v183 offset:53248
	ds_read_b128 v[220:223], v183 offset:54272
	ds_read_b128 v[224:227], v183 offset:55296
	ds_read_b128 v[228:231], v183 offset:56320
	s_add_i32 m0, s54, 0x2000
	s_nop 0
	global_load_lds_dwordx4 v138, s[98:99]
	s_add_i32 s54, s94, s2
	s_add_u32 s98, s98, s48
	s_addc_u32 s99, s99, 0
	s_mov_b32 m0, s54
	s_nop 0
	global_load_lds_dwordx4 v142, s[98:99]
	s_add_i32 m0, s54, 0x2000
	s_nop 0
	global_load_lds_dwordx4 v138, s[98:99]
	s_add_u32 s98, s52, 0x80
	s_addc_u32 s99, s53, 0
	s_cmp_eq_u32 s74, vcc_hi
	s_cselect_b32 s99, s39, s99
	s_cselect_b32 s98, s38, s98
	s_add_u32 s98, s98, s92
	s_addc_u32 s99, s99, s93
	s_mov_b32 m0, s35
	s_nop 0
	global_load_lds_dwordx4 v144, s[98:99]
	s_mov_b32 m0, s59
	s_nop 0
	global_load_lds_dwordx4 v140, s[98:99]
	s_waitcnt vmcnt(8)
	s_waitcnt lgkmcnt(0)
	s_setprio 1
	s_barrier
	v_mfma_f32_16x16x32_f16 v[58:61], v[130:133], v[192:195], v[58:61]
	v_mfma_f32_16x16x32_f16 v[50:53], v[152:155], v[192:195], v[50:53]
	v_mfma_f32_16x16x32_f16 v[42:45], v[130:133], v[208:211], v[42:45]
	v_mfma_f32_16x16x32_f16 v[34:37], v[152:155], v[208:211], v[34:37]
	v_mfma_f32_16x16x32_f16 v[26:29], v[130:133], v[216:219], v[26:29]
	v_mfma_f32_16x16x32_f16 v[18:21], v[152:155], v[216:219], v[18:21]
	v_mfma_f32_16x16x32_f16 v[10:13], v[130:133], v[224:227], v[10:13]
	v_mfma_f32_16x16x32_f16 v[6:9], v[152:155], v[224:227], v[6:9]
	v_mfma_f32_16x16x32_f16 v[58:61], v[134:137], v[204:207], v[58:61]
	v_mfma_f32_16x16x32_f16 v[50:53], v[156:159], v[204:207], v[50:53]
	v_mfma_f32_16x16x32_f16 v[42:45], v[134:137], v[212:215], v[42:45]
	v_mfma_f32_16x16x32_f16 v[34:37], v[156:159], v[212:215], v[34:37]
	v_mfma_f32_16x16x32_f16 v[26:29], v[134:137], v[220:223], v[26:29]
	v_mfma_f32_16x16x32_f16 v[18:21], v[156:159], v[220:223], v[18:21]
	v_mfma_f32_16x16x32_f16 v[10:13], v[134:137], v[228:231], v[10:13]
	v_mfma_f32_16x16x32_f16 v[6:9], v[156:159], v[228:231], v[6:9]
	v_mfma_f32_16x16x32_f16 v[62:65], v[160:163], v[192:195], v[62:65]
	v_mfma_f32_16x16x32_f16 v[54:57], v[184:187], v[192:195], v[54:57]
	v_mfma_f32_16x16x32_f16 v[46:49], v[160:163], v[208:211], v[46:49]
	v_mfma_f32_16x16x32_f16 v[38:41], v[184:187], v[208:211], v[38:41]
	v_mfma_f32_16x16x32_f16 v[30:33], v[160:163], v[216:219], v[30:33]
	v_mfma_f32_16x16x32_f16 v[22:25], v[184:187], v[216:219], v[22:25]
	v_mfma_f32_16x16x32_f16 v[14:17], v[160:163], v[224:227], v[14:17]
	v_mfma_f32_16x16x32_f16 v[2:5], v[184:187], v[224:227], v[2:5]
	v_mfma_f32_16x16x32_f16 v[62:65], v[166:169], v[204:207], v[62:65]
	v_mfma_f32_16x16x32_f16 v[54:57], v[188:191], v[204:207], v[54:57]
	v_mfma_f32_16x16x32_f16 v[46:49], v[166:169], v[212:215], v[46:49]
	v_mfma_f32_16x16x32_f16 v[38:41], v[188:191], v[212:215], v[38:41]
	v_mfma_f32_16x16x32_f16 v[30:33], v[166:169], v[220:223], v[30:33]
	v_mfma_f32_16x16x32_f16 v[22:25], v[188:191], v[220:223], v[22:25]
	v_mfma_f32_16x16x32_f16 v[14:17], v[166:169], v[228:231], v[14:17]
	v_mfma_f32_16x16x32_f16 v[2:5], v[188:191], v[228:231], v[2:5]
	s_barrier
	s_setprio 0
	s_add_u32 s52, s52, 0x100
	s_addc_u32 s53, s53, 0
	s_add_u32 s80, s80, 0x100
	s_addc_u32 s81, s81, 0
	s_cmp_ge_u32 s82, s65
	s_mov_b32 s54, s82
	s_cbranch_scc1 .LBB0_311
; #define PG8_STAGE(bufoff, gbase, voff) do { _Pragma("unroll") for (int _i = 0; _i < 2; ++_i) \
;         __builtin_amdgcn_global_load_lds((const unsigned*)((const char*)(gbase) + (voff)[_i]), (PG8_LAS unsigned*)(lds + (bufoff) + ldsw + _i * 8192), 16, 0, 0); } while (0)
; #define PG8_LDA(dst, b, h) do { _Pragma("unroll") for (int m = 0; m < 4; ++m) _Pragma("unroll") for (int k = 0; k < 2; ++k) dst[m][k] = *(const PG8_LAS bf16x8*)(lds + PG8_SA(b, h) + aoff + m * 2048 + k * 1024); } while (0)
; #define PG8_LDB(dst, b, h) do { _Pragma("unroll") for (int n = 0; n < 2; ++n) _Pragma("unroll") for (int k = 0; k < 2; ++k) dst[n][k] = *(const PG8_LAS bf16x8*)(lds + PG8_SB(b, h) + boff + n * 2048 + k * 1024); } while (0)
; #define PG8_WAIT_V(n) asm volatile("s_waitcnt vmcnt(" #n ")" ::: "memory")
; #define PG8_WAIT_L(n) asm volatile("s_waitcnt lgkmcnt(" #n ")" ::: "memory")
; #define PG8_BAR __builtin_amdgcn_s_barrier()
; #define PG8_SCHED __builtin_amdgcn_sched_barrier(0)
; template <class Epi, class Sched, bool ALIGN_EPI = false, bool SP2 = false, bool F16 = false>
; __device__ __forceinline__ void gemm_phase(PG8_LAS unsigned char* lds, const Gemm g, const Sched& S, const Epi& E) {
;     ...
;             const bool last = (t == nt - 2);
;             const char* a1 = cA + (size_t)(t + 1) * kstep;
;             const char* a2 = last ? nA : cA + (size_t)(t + 2) * kstep; const char* b2 = last ? nB : cB + (size_t)(t + 2) * kstep;
;             const char* a3 = a2 + kstep; const char* b3 = b2 + kstep;
;             if (last && has_next) S.a_ready(nxt);
;             if constexpr (SP2) {
;             PG8_LDB(B0, 0, 0); PG8_LDB(B1, 0, 1); PG8_SCHED; PG8_LDA(At, 0, 0); PG8_STAGE(PG8_SA(1, 1), a1 + hstepA, voffA);
;             PG8_WAIT_V(8); PG8_WAIT_L(0); PG8_BAR; PG8_MMA(0, 0, At, B0); PG8_MMA(0, 1, At, B1); PG8_BAR; PG8_SCHED;
;             PG8_LDA(At, 0, 1); PG8_STAGE(PG8_SB(0, 0), b2, voffB); PG8_STAGE(PG8_SB(0, 1), b2 + hstepB, voffB); PG8_STAGE(PG8_SA(0, 0), a2, voffA);
;             PG8_WAIT_V(8); PG8_WAIT_L(0); PG8_BAR; PG8_MMA(1, 0, At, B0); PG8_MMA(1, 1, At, B1); PG8_BAR; PG8_SCHED;
.LBB0_310:
	s_add_i32 s82, s54, 2
	s_add_u32 s83, s52, 0x80
	s_addc_u32 s55, s53, 0
	s_add_i32 vcc_lo, 0, 0x10000
	s_cmp_eq_u32 s74, s54
	s_cselect_b32 s55, s39, s55
	s_cselect_b32 s54, s38, s83
	s_cselect_b32 s95, s47, s81
	s_cselect_b32 s94, s46, s80
	s_add_i32 s83, 0, 0x14000
	ds_read_b128 v[130:133], v139
	ds_read_b128 v[134:137], v139 offset:1024
	ds_read_b128 v[152:155], v139 offset:2048
	ds_read_b128 v[156:159], v139 offset:3072
	ds_read_b128 v[160:163], v141
	ds_read_b128 v[166:169], v141 offset:1024
	ds_read_b128 v[184:187], v141 offset:2048
	ds_read_b128 v[188:191], v141 offset:3072
	s_add_i32 m0, s22, 0xc000
	ds_read_b128 v[192:195], v183
	ds_read_b128 v[204:207], v183 offset:1024
	ds_read_b128 v[208:211], v183 offset:2048
	ds_read_b128 v[212:215], v183 offset:3072
	ds_read_b128 v[216:219], v183 offset:4096
	ds_read_b128 v[220:223], v183 offset:5120
	ds_read_b128 v[224:227], v183 offset:6144
	ds_read_b128 v[228:231], v183 offset:7168
	global_load_lds_dwordx4 v148, s[52:53]
	s_add_i32 m0, s22, 0xe000
	s_nop 0
	global_load_lds_dwordx4 v150, s[52:53]
	s_waitcnt vmcnt(8)
	s_waitcnt lgkmcnt(0)
	s_setprio 1
	s_barrier
	v_mfma_f32_16x16x32_f16 v[122:125], v[130:133], v[192:195], v[122:125]
	v_mfma_f32_16x16x32_f16 v[114:117], v[152:155], v[192:195], v[114:117]
	v_mfma_f32_16x16x32_f16 v[106:109], v[130:133], v[208:211], v[106:109]
	v_mfma_f32_16x16x32_f16 v[98:101], v[152:155], v[208:211], v[98:101]
	v_mfma_f32_16x16x32_f16 v[90:93], v[130:133], v[216:219], v[90:93]
	v_mfma_f32_16x16x32_f16 v[82:85], v[152:155], v[216:219], v[82:85]
	v_mfma_f32_16x16x32_f16 v[74:77], v[130:133], v[224:227], v[74:77]
	v_mfma_f32_16x16x32_f16 v[66:69], v[152:155], v[224:227], v[66:69]
	v_mfma_f32_16x16x32_f16 v[122:125], v[134:137], v[204:207], v[122:125]
	v_mfma_f32_16x16x32_f16 v[114:117], v[156:159], v[204:207], v[114:117]
	v_mfma_f32_16x16x32_f16 v[106:109], v[134:137], v[212:215], v[106:109]
	v_mfma_f32_16x16x32_f16 v[98:101], v[156:159], v[212:215], v[98:101]
	v_mfma_f32_16x16x32_f16 v[90:93], v[134:137], v[220:223], v[90:93]
	v_mfma_f32_16x16x32_f16 v[82:85], v[156:159], v[220:223], v[82:85]
	v_mfma_f32_16x16x32_f16 v[74:77], v[134:137], v[228:231], v[74:77]
	v_mfma_f32_16x16x32_f16 v[66:69], v[156:159], v[228:231], v[66:69]
	v_mfma_f32_16x16x32_f16 v[126:129], v[160:163], v[192:195], v[126:129]
	v_mfma_f32_16x16x32_f16 v[118:121], v[184:187], v[192:195], v[118:121]
	v_mfma_f32_16x16x32_f16 v[110:113], v[160:163], v[208:211], v[110:113]
	v_mfma_f32_16x16x32_f16 v[102:105], v[184:187], v[208:211], v[102:105]
	v_mfma_f32_16x16x32_f16 v[94:97], v[160:163], v[216:219], v[94:97]
	v_mfma_f32_16x16x32_f16 v[86:89], v[184:187], v[216:219], v[86:89]
	v_mfma_f32_16x16x32_f16 v[78:81], v[160:163], v[224:227], v[78:81]
	v_mfma_f32_16x16x32_f16 v[70:73], v[184:187], v[224:227], v[70:73]
	v_mfma_f32_16x16x32_f16 v[126:129], v[166:169], v[204:207], v[126:129]
	v_mfma_f32_16x16x32_f16 v[118:121], v[188:191], v[204:207], v[118:121]
	v_mfma_f32_16x16x32_f16 v[110:113], v[166:169], v[212:215], v[110:113]
	v_mfma_f32_16x16x32_f16 v[102:105], v[188:191], v[212:215], v[102:105]
	v_mfma_f32_16x16x32_f16 v[94:97], v[166:169], v[220:223], v[94:97]
	v_mfma_f32_16x16x32_f16 v[86:89], v[188:191], v[220:223], v[86:89]
	v_mfma_f32_16x16x32_f16 v[78:81], v[166:169], v[228:231], v[78:81]
	v_mfma_f32_16x16x32_f16 v[70:73], v[188:191], v[228:231], v[70:73]
	s_barrier
	s_setprio 0
	s_add_i32 vcc_lo, vcc_lo, s2
	s_mov_b32 m0, vcc_lo
	s_nop 0
	global_load_lds_dwordx4 v142, s[94:95]
	ds_read_b128 v[192:195], v183 offset:16384
	ds_read_b128 v[204:207], v183 offset:17408
	ds_read_b128 v[208:211], v183 offset:18432
	ds_read_b128 v[212:215], v183 offset:19456
	ds_read_b128 v[216:219], v183 offset:20480
	ds_read_b128 v[220:223], v183 offset:21504
	ds_read_b128 v[224:227], v183 offset:22528
	ds_read_b128 v[228:231], v183 offset:23552
	s_add_i32 m0, vcc_lo, 0x2000
	s_nop 0
	global_load_lds_dwordx4 v138, s[94:95]
	s_add_i32 s83, s83, s2
	s_add_u32 s94, s94, s48
	s_addc_u32 s95, s95, 0
	s_mov_b32 m0, s83
	s_nop 0
	global_load_lds_dwordx4 v142, s[94:95]
	s_add_i32 m0, s83, 0x2000
	s_nop 0
	global_load_lds_dwordx4 v138, s[94:95]
	s_mov_b32 m0, s22
	s_nop 0
	global_load_lds_dwordx4 v144, s[54:55]
	s_mov_b32 m0, s33
	s_nop 0
	global_load_lds_dwordx4 v140, s[54:55]
	s_waitcnt vmcnt(8)
	s_waitcnt lgkmcnt(0)
	s_setprio 1
	s_barrier
	v_mfma_f32_16x16x32_f16 v[58:61], v[130:133], v[192:195], v[58:61]
	v_mfma_f32_16x16x32_f16 v[50:53], v[152:155], v[192:195], v[50:53]
	v_mfma_f32_16x16x32_f16 v[42:45], v[130:133], v[208:211], v[42:45]
	v_mfma_f32_16x16x32_f16 v[34:37], v[152:155], v[208:211], v[34:37]
	v_mfma_f32_16x16x32_f16 v[26:29], v[130:133], v[216:219], v[26:29]
	v_mfma_f32_16x16x32_f16 v[18:21], v[152:155], v[216:219], v[18:21]
	v_mfma_f32_16x16x32_f16 v[10:13], v[130:133], v[224:227], v[10:13]
	v_mfma_f32_16x16x32_f16 v[6:9], v[152:155], v[224:227], v[6:9]
	v_mfma_f32_16x16x32_f16 v[58:61], v[134:137], v[204:207], v[58:61]
	v_mfma_f32_16x16x32_f16 v[50:53], v[156:159], v[204:207], v[50:53]
	v_mfma_f32_16x16x32_f16 v[42:45], v[134:137], v[212:215], v[42:45]
	v_mfma_f32_16x16x32_f16 v[34:37], v[156:159], v[212:215], v[34:37]
	v_mfma_f32_16x16x32_f16 v[26:29], v[134:137], v[220:223], v[26:29]
	v_mfma_f32_16x16x32_f16 v[18:21], v[156:159], v[220:223], v[18:21]
	v_mfma_f32_16x16x32_f16 v[10:13], v[134:137], v[228:231], v[10:13]
	v_mfma_f32_16x16x32_f16 v[6:9], v[156:159], v[228:231], v[6:9]
	v_mfma_f32_16x16x32_f16 v[62:65], v[160:163], v[192:195], v[62:65]
	v_mfma_f32_16x16x32_f16 v[54:57], v[184:187], v[192:195], v[54:57]
	v_mfma_f32_16x16x32_f16 v[46:49], v[160:163], v[208:211], v[46:49]
	v_mfma_f32_16x16x32_f16 v[38:41], v[184:187], v[208:211], v[38:41]
	v_mfma_f32_16x16x32_f16 v[30:33], v[160:163], v[216:219], v[30:33]
	v_mfma_f32_16x16x32_f16 v[22:25], v[184:187], v[216:219], v[22:25]
	v_mfma_f32_16x16x32_f16 v[14:17], v[160:163], v[224:227], v[14:17]
	v_mfma_f32_16x16x32_f16 v[2:5], v[184:187], v[224:227], v[2:5]
	v_mfma_f32_16x16x32_f16 v[62:65], v[166:169], v[204:207], v[62:65]
	v_mfma_f32_16x16x32_f16 v[54:57], v[188:191], v[204:207], v[54:57]
	v_mfma_f32_16x16x32_f16 v[46:49], v[166:169], v[212:215], v[46:49]
	v_mfma_f32_16x16x32_f16 v[38:41], v[188:191], v[212:215], v[38:41]
	v_mfma_f32_16x16x32_f16 v[30:33], v[166:169], v[220:223], v[30:33]
	v_mfma_f32_16x16x32_f16 v[22:25], v[188:191], v[220:223], v[22:25]
	v_mfma_f32_16x16x32_f16 v[14:17], v[166:169], v[228:231], v[14:17]
	v_mfma_f32_16x16x32_f16 v[2:5], v[188:191], v[228:231], v[2:5]
	s_barrier
; #define PG8_STAGE(bufoff, gbase, voff) do { _Pragma("unroll") for (int _i = 0; _i < 2; ++_i) \
;         __builtin_amdgcn_global_load_lds((const unsigned*)((const char*)(gbase) + (voff)[_i]), (PG8_LAS unsigned*)(lds + (bufoff) + ldsw + _i * 8192), 16, 0, 0); } while (0)
; #define PG8_LDA(dst, b, h) do { _Pragma("unroll") for (int m = 0; m < 4; ++m) _Pragma("unroll") for (int k = 0; k < 2; ++k) dst[m][k] = *(const PG8_LAS bf16x8*)(lds + PG8_SA(b, h) + aoff + m * 2048 + k * 1024); } while (0)
; #define PG8_LDB(dst, b, h) do { _Pragma("unroll") for (int n = 0; n < 2; ++n) _Pragma("unroll") for (int k = 0; k < 2; ++k) dst[n][k] = *(const PG8_LAS bf16x8*)(lds + PG8_SB(b, h) + boff + n * 2048 + k * 1024); } while (0)
; #define PG8_WAIT_V(n) asm volatile("s_waitcnt vmcnt(" #n ")" ::: "memory")
; #define PG8_WAIT_L(n) asm volatile("s_waitcnt lgkmcnt(" #n ")" ::: "memory")
; #define PG8_BAR __builtin_amdgcn_s_barrier()
; #define PG8_SCHED __builtin_amdgcn_sched_barrier(0)
; template <class Epi, class Sched, bool ALIGN_EPI = false, bool SP2 = false, bool F16 = false>
; __device__ __forceinline__ void gemm_phase(PG8_LAS unsigned char* lds, const Gemm g, const Sched& S, const Epi& E) {
;     ...
;             PG8_LDB(B0, 1, 0); PG8_LDB(B1, 1, 1); PG8_SCHED; PG8_LDA(At, 1, 0); PG8_STAGE(PG8_SA(0, 1), a2 + hstepA, voffA);
;             PG8_WAIT_V(8); PG8_WAIT_L(0); PG8_BAR; PG8_MMA(0, 0, At, B0); PG8_MMA(0, 1, At, B1); PG8_BAR; PG8_SCHED;
;             PG8_LDA(At, 1, 1); PG8_STAGE(PG8_SB(1, 0), b3, voffB); PG8_STAGE(PG8_SB(1, 1), b3 + hstepB, voffB); PG8_STAGE(PG8_SA(1, 0), a3, voffA);
;             PG8_WAIT_V(8); PG8_WAIT_L(0); PG8_BAR; PG8_MMA(1, 0, At, B0); PG8_MMA(1, 1, At, B1); PG8_BAR; PG8_SCHED;
	s_setprio 0
	s_add_i32 s83, 0, 0x18000
	s_add_i32 s94, 0, 0x1c000
	ds_read_b128 v[130:133], v143
	ds_read_b128 v[134:137], v143 offset:1024
	ds_read_b128 v[152:155], v143 offset:2048
	ds_read_b128 v[156:159], v143 offset:3072
	ds_read_b128 v[160:163], v145
	ds_read_b128 v[166:169], v145 offset:1024
	ds_read_b128 v[184:187], v145 offset:2048
	ds_read_b128 v[188:191], v145 offset:3072
	s_add_u32 s54, s54, s8
	s_addc_u32 s55, s55, 0
	s_mov_b32 m0, s12
	ds_read_b128 v[192:195], v183 offset:32768
	ds_read_b128 v[204:207], v183 offset:33792
	ds_read_b128 v[208:211], v183 offset:34816
	ds_read_b128 v[212:215], v183 offset:35840
	ds_read_b128 v[216:219], v183 offset:36864
	ds_read_b128 v[220:223], v183 offset:37888
	ds_read_b128 v[224:227], v183 offset:38912
	ds_read_b128 v[228:231], v183 offset:39936
	global_load_lds_dwordx4 v144, s[54:55]
	s_mov_b32 m0, s13
	s_nop 0
	global_load_lds_dwordx4 v140, s[54:55]
	s_waitcnt vmcnt(8)
	s_waitcnt lgkmcnt(0)
	s_setprio 1
	s_barrier
	v_mfma_f32_16x16x32_f16 v[122:125], v[130:133], v[192:195], v[122:125]
	v_mfma_f32_16x16x32_f16 v[114:117], v[152:155], v[192:195], v[114:117]
	v_mfma_f32_16x16x32_f16 v[106:109], v[130:133], v[208:211], v[106:109]
	v_mfma_f32_16x16x32_f16 v[98:101], v[152:155], v[208:211], v[98:101]
	v_mfma_f32_16x16x32_f16 v[90:93], v[130:133], v[216:219], v[90:93]
	v_mfma_f32_16x16x32_f16 v[82:85], v[152:155], v[216:219], v[82:85]
	v_mfma_f32_16x16x32_f16 v[74:77], v[130:133], v[224:227], v[74:77]
	v_mfma_f32_16x16x32_f16 v[66:69], v[152:155], v[224:227], v[66:69]
	v_mfma_f32_16x16x32_f16 v[122:125], v[134:137], v[204:207], v[122:125]
	v_mfma_f32_16x16x32_f16 v[114:117], v[156:159], v[204:207], v[114:117]
	v_mfma_f32_16x16x32_f16 v[106:109], v[134:137], v[212:215], v[106:109]
	v_mfma_f32_16x16x32_f16 v[98:101], v[156:159], v[212:215], v[98:101]
	v_mfma_f32_16x16x32_f16 v[90:93], v[134:137], v[220:223], v[90:93]
	v_mfma_f32_16x16x32_f16 v[82:85], v[156:159], v[220:223], v[82:85]
	v_mfma_f32_16x16x32_f16 v[74:77], v[134:137], v[228:231], v[74:77]
	v_mfma_f32_16x16x32_f16 v[66:69], v[156:159], v[228:231], v[66:69]
	v_mfma_f32_16x16x32_f16 v[126:129], v[160:163], v[192:195], v[126:129]
	v_mfma_f32_16x16x32_f16 v[118:121], v[184:187], v[192:195], v[118:121]
	v_mfma_f32_16x16x32_f16 v[110:113], v[160:163], v[208:211], v[110:113]
	v_mfma_f32_16x16x32_f16 v[102:105], v[184:187], v[208:211], v[102:105]
	v_mfma_f32_16x16x32_f16 v[94:97], v[160:163], v[216:219], v[94:97]
	v_mfma_f32_16x16x32_f16 v[86:89], v[184:187], v[216:219], v[86:89]
	v_mfma_f32_16x16x32_f16 v[78:81], v[160:163], v[224:227], v[78:81]
	v_mfma_f32_16x16x32_f16 v[70:73], v[184:187], v[224:227], v[70:73]
	v_mfma_f32_16x16x32_f16 v[126:129], v[166:169], v[204:207], v[126:129]
	v_mfma_f32_16x16x32_f16 v[118:121], v[188:191], v[204:207], v[118:121]
	v_mfma_f32_16x16x32_f16 v[110:113], v[166:169], v[212:215], v[110:113]
	v_mfma_f32_16x16x32_f16 v[102:105], v[188:191], v[212:215], v[102:105]
	v_mfma_f32_16x16x32_f16 v[94:97], v[166:169], v[220:223], v[94:97]
	v_mfma_f32_16x16x32_f16 v[86:89], v[188:191], v[220:223], v[86:89]
	v_mfma_f32_16x16x32_f16 v[78:81], v[166:169], v[228:231], v[78:81]
	v_mfma_f32_16x16x32_f16 v[70:73], v[188:191], v[228:231], v[70:73]
	s_barrier
	s_setprio 0
	s_add_i32 s54, s83, s2
	s_add_i32 vcc_hi, s82, -2
	s_cmp_eq_u32 s74, vcc_hi
	s_cselect_b32 s99, s47, s81
	s_cselect_b32 s98, s46, s80
	s_add_u32 s98, s98, s92
	s_addc_u32 s99, s99, s93
	s_mov_b32 m0, s54
	s_nop 0
	global_load_lds_dwordx4 v142, s[98:99]
	ds_read_b128 v[192:195], v183 offset:49152
	ds_read_b128 v[204:207], v183 offset:50176
	ds_read_b128 v[208:211], v183 offset:51200
	ds_read_b128 v[212:215], v183 offset:52224
	ds_read_b128 v[216:219], v183 offset:53248
	ds_read_b128 v[220:223], v183 offset:54272
	ds_read_b128 v[224:227], v183 offset:55296
	ds_read_b128 v[228:231], v183 offset:56320
	s_add_i32 m0, s54, 0x2000
	s_nop 0
	global_load_lds_dwordx4 v138, s[98:99]
	s_add_i32 s54, s94, s2
	s_add_u32 s98, s98, s48
	s_addc_u32 s99, s99, 0
	s_mov_b32 m0, s54
	s_nop 0
	global_load_lds_dwordx4 v142, s[98:99]
	s_add_i32 m0, s54, 0x2000
	s_nop 0
	global_load_lds_dwordx4 v138, s[98:99]
	s_add_u32 s98, s52, 0x80
	s_addc_u32 s99, s53, 0
	s_cmp_eq_u32 s74, vcc_hi
	s_cselect_b32 s99, s39, s99
	s_cselect_b32 s98, s38, s98
	s_add_u32 s98, s98, s92
	s_addc_u32 s99, s99, s93
	s_mov_b32 m0, s35
	s_nop 0
	global_load_lds_dwordx4 v144, s[98:99]
	s_mov_b32 m0, s59
	s_nop 0
	global_load_lds_dwordx4 v140, s[98:99]
	s_waitcnt vmcnt(8)
	s_waitcnt lgkmcnt(0)
	s_setprio 1
	s_barrier
	v_mfma_f32_16x16x32_f16 v[58:61], v[130:133], v[192:195], v[58:61]
	v_mfma_f32_16x16x32_f16 v[50:53], v[152:155], v[192:195], v[50:53]
	v_mfma_f32_16x16x32_f16 v[42:45], v[130:133], v[208:211], v[42:45]
	v_mfma_f32_16x16x32_f16 v[34:37], v[152:155], v[208:211], v[34:37]
	v_mfma_f32_16x16x32_f16 v[26:29], v[130:133], v[216:219], v[26:29]
	v_mfma_f32_16x16x32_f16 v[18:21], v[152:155], v[216:219], v[18:21]
	v_mfma_f32_16x16x32_f16 v[10:13], v[130:133], v[224:227], v[10:13]
	v_mfma_f32_16x16x32_f16 v[6:9], v[152:155], v[224:227], v[6:9]
	v_mfma_f32_16x16x32_f16 v[58:61], v[134:137], v[204:207], v[58:61]
	v_mfma_f32_16x16x32_f16 v[50:53], v[156:159], v[204:207], v[50:53]
	v_mfma_f32_16x16x32_f16 v[42:45], v[134:137], v[212:215], v[42:45]
	v_mfma_f32_16x16x32_f16 v[34:37], v[156:159], v[212:215], v[34:37]
	v_mfma_f32_16x16x32_f16 v[26:29], v[134:137], v[220:223], v[26:29]
	v_mfma_f32_16x16x32_f16 v[18:21], v[156:159], v[220:223], v[18:21]
	v_mfma_f32_16x16x32_f16 v[10:13], v[134:137], v[228:231], v[10:13]
	v_mfma_f32_16x16x32_f16 v[6:9], v[156:159], v[228:231], v[6:9]
	v_mfma_f32_16x16x32_f16 v[62:65], v[160:163], v[192:195], v[62:65]
	v_mfma_f32_16x16x32_f16 v[54:57], v[184:187], v[192:195], v[54:57]
	v_mfma_f32_16x16x32_f16 v[46:49], v[160:163], v[208:211], v[46:49]
	v_mfma_f32_16x16x32_f16 v[38:41], v[184:187], v[208:211], v[38:41]
	v_mfma_f32_16x16x32_f16 v[30:33], v[160:163], v[216:219], v[30:33]
	v_mfma_f32_16x16x32_f16 v[22:25], v[184:187], v[216:219], v[22:25]
	v_mfma_f32_16x16x32_f16 v[14:17], v[160:163], v[224:227], v[14:17]
	v_mfma_f32_16x16x32_f16 v[2:5], v[184:187], v[224:227], v[2:5]
	v_mfma_f32_16x16x32_f16 v[62:65], v[166:169], v[204:207], v[62:65]
	v_mfma_f32_16x16x32_f16 v[54:57], v[188:191], v[204:207], v[54:57]
	v_mfma_f32_16x16x32_f16 v[46:49], v[166:169], v[212:215], v[46:49]
	v_mfma_f32_16x16x32_f16 v[38:41], v[188:191], v[212:215], v[38:41]
	v_mfma_f32_16x16x32_f16 v[30:33], v[166:169], v[220:223], v[30:33]
	v_mfma_f32_16x16x32_f16 v[22:25], v[188:191], v[220:223], v[22:25]
	v_mfma_f32_16x16x32_f16 v[14:17], v[166:169], v[228:231], v[14:17]
	v_mfma_f32_16x16x32_f16 v[2:5], v[188:191], v[228:231], v[2:5]
	s_barrier
	s_setprio 0
	s_add_u32 s52, s52, 0x100
	s_addc_u32 s53, s53, 0
	s_add_u32 s80, s80, 0x100
	s_addc_u32 s81, s81, 0
	s_cmp_ge_u32 s82, s65
	s_mov_b32 s54, s82
	s_cbranch_scc0 .LBB0_310

; #define PG8_STAGE(bufoff, gbase, voff) do { _Pragma("unroll") for (int _i = 0; _i < 2; ++_i) \
;         __builtin_amdgcn_global_load_lds((const unsigned*)((const char*)(gbase) + (voff)[_i]), (PG8_LAS unsigned*)(lds + (bufoff) + ldsw + _i * 8192), 16, 0, 0); } while (0)
; #define PG8_LDA(dst, b, h) do { _Pragma("unroll") for (int m = 0; m < 4; ++m) _Pragma("unroll") for (int k = 0; k < 2; ++k) dst[m][k] = *(const PG8_LAS bf16x8*)(lds + PG8_SA(b, h) + aoff + m * 2048 + k * 1024); } while (0)
; #define PG8_LDB(dst, b, h) do { _Pragma("unroll") for (int n = 0; n < 2; ++n) _Pragma("unroll") for (int k = 0; k < 2; ++k) dst[n][k] = *(const PG8_LAS bf16x8*)(lds + PG8_SB(b, h) + boff + n * 2048 + k * 1024); } while (0)
; #define PG8_WAIT_V(n) asm volatile("s_waitcnt vmcnt(" #n ")" ::: "memory")
; #define PG8_WAIT_L(n) asm volatile("s_waitcnt lgkmcnt(" #n ")" ::: "memory")
; #define PG8_BAR __builtin_amdgcn_s_barrier()
; #define PG8_SCHED __builtin_amdgcn_sched_barrier(0)
; template <class Epi, class Sched, bool ALIGN_EPI = false, bool SP2 = false, bool F16 = false>
; __device__ __forceinline__ void gemm_phase(PG8_LAS unsigned char* lds, const Gemm g, const Sched& S, const Epi& E) {
;     ...
;     for (;;) {
;         const bool has_next = S.next(ui + 1, nxt);
;         const char* nA = has_next ? (const char*)g.A + (size_t)nxt.pm * tstepA : cA; const char* nB = has_next ? (const char*)g.Bt + (size_t)nxt.pn * tstepB : cB;
;         for (int t = 0; t < nt; t += 2) {
;             const bool last = (t == nt - 2);
;             const char* a1 = cA + (size_t)(t + 1) * kstep;
;             const char* a2 = last ? nA : cA + (size_t)(t + 2) * kstep; const char* b2 = last ? nB : cB + (size_t)(t + 2) * kstep;
;             const char* a3 = a2 + kstep; const char* b3 = b2 + kstep;
;             if (last && has_next) S.a_ready(nxt);
;             if constexpr (SP2) {
;             PG8_LDB(B0, 0, 0); PG8_LDB(B1, 0, 1); PG8_SCHED; PG8_LDA(At, 0, 0); PG8_STAGE(PG8_SA(1, 1), a1 + hstepA, voffA);
;             PG8_WAIT_V(8); PG8_WAIT_L(0); PG8_BAR; PG8_MMA(0, 0, At, B0); PG8_MMA(0, 1, At, B1); PG8_BAR; PG8_SCHED;
;             PG8_LDA(At, 0, 1); PG8_STAGE(PG8_SB(0, 0), b2, voffB); PG8_STAGE(PG8_SB(0, 1), b2 + hstepB, voffB); PG8_STAGE(PG8_SA(0, 0), a2, voffA);
;             PG8_WAIT_V(8); PG8_WAIT_L(0); PG8_BAR; PG8_MMA(1, 0, At, B0); PG8_MMA(1, 1, At, B1); PG8_BAR; PG8_SCHED;
.LBB0_343:
	s_andn2_b64 vcc, exec, s[4:5]
	s_waitcnt vmcnt(0)
	s_cbranch_vccnz .Lzk_rs
	s_add_u32 s52, s52, 0x80
	s_addc_u32 s53, s53, 0
	s_add_u32 s79, s54, 0x100
	s_addc_u32 s80, s55, 0
	s_mov_b32 s54, 0
	v_add_u32_e32 v139, 0x10000, v158
	v_add_u32_e32 v141, 0x14000, v158
	v_add_u32_e32 v143, 0x18000, v158
	v_add_u32_e32 v157, 0x1c000, v158
.Lpk_rs:
	s_add_i32 s81, s54, 2
	s_add_u32 s82, s52, 0x80
	s_addc_u32 s55, s53, 0
	s_add_i32 s94, 0, 0x10000
	s_cmp_eq_u32 s74, s54
	s_cselect_b32 s55, s41, s55
	s_cselect_b32 s54, s40, s82
	s_cselect_b32 s83, s47, s80
	s_cselect_b32 s82, s46, s79
	s_add_i32 s95, 0, 0x14000
	ds_read_b128 v[130:133], v139
	ds_read_b128 v[134:137], v139 offset:1024
	ds_read_b128 v[148:151], v139 offset:2048
	ds_read_b128 v[152:155], v139 offset:3072
	ds_read_b128 v[162:165], v141
	ds_read_b128 v[166:169], v141 offset:1024
	ds_read_b128 v[170:173], v141 offset:2048
	ds_read_b128 v[182:185], v141 offset:3072
	s_add_i32 m0, s3, 0xc000
	ds_read_b128 v[186:189], v160
	ds_read_b128 v[190:193], v160 offset:1024
	ds_read_b128 v[194:197], v160 offset:2048
	ds_read_b128 v[204:207], v160 offset:3072
	ds_read_b128 v[208:211], v160 offset:4096
	ds_read_b128 v[212:215], v160 offset:5120
	ds_read_b128 v[216:219], v160 offset:6144
	ds_read_b128 v[220:223], v160 offset:7168
	global_load_lds_dwordx4 v144, s[52:53]
	s_add_i32 m0, s3, 0xe000
	s_nop 0
	global_load_lds_dwordx4 v146, s[52:53]
	s_waitcnt vmcnt(8)
	s_waitcnt lgkmcnt(0)
	s_setprio 1
	s_barrier
	v_mfma_f32_16x16x32_bf16 v[122:125], v[130:133], v[186:189], 0
	v_mfma_f32_16x16x32_bf16 v[126:129], v[148:151], v[186:189], 0
	v_mfma_f32_16x16x32_bf16 v[110:113], v[130:133], v[194:197], 0
	v_mfma_f32_16x16x32_bf16 v[106:109], v[148:151], v[194:197], 0
	v_mfma_f32_16x16x32_bf16 v[94:97], v[130:133], v[208:211], 0
	v_mfma_f32_16x16x32_bf16 v[90:93], v[148:151], v[208:211], 0
	v_mfma_f32_16x16x32_bf16 v[78:81], v[130:133], v[216:219], 0
	v_mfma_f32_16x16x32_bf16 v[74:77], v[148:151], v[216:219], 0
	v_mfma_f32_16x16x32_bf16 v[122:125], v[134:137], v[190:193], v[122:125]
	v_mfma_f32_16x16x32_bf16 v[126:129], v[152:155], v[190:193], v[126:129]
	v_mfma_f32_16x16x32_bf16 v[110:113], v[134:137], v[204:207], v[110:113]
	v_mfma_f32_16x16x32_bf16 v[106:109], v[152:155], v[204:207], v[106:109]
	v_mfma_f32_16x16x32_bf16 v[94:97], v[134:137], v[212:215], v[94:97]
	v_mfma_f32_16x16x32_bf16 v[90:93], v[152:155], v[212:215], v[90:93]
	v_mfma_f32_16x16x32_bf16 v[78:81], v[134:137], v[220:223], v[78:81]
	v_mfma_f32_16x16x32_bf16 v[74:77], v[152:155], v[220:223], v[74:77]
	v_mfma_f32_16x16x32_bf16 v[118:121], v[162:165], v[186:189], 0
	v_mfma_f32_16x16x32_bf16 v[114:117], v[170:173], v[186:189], 0
	v_mfma_f32_16x16x32_bf16 v[102:105], v[162:165], v[194:197], 0
	v_mfma_f32_16x16x32_bf16 v[98:101], v[170:173], v[194:197], 0
	v_mfma_f32_16x16x32_bf16 v[86:89], v[162:165], v[208:211], 0
	v_mfma_f32_16x16x32_bf16 v[82:85], v[170:173], v[208:211], 0
	v_mfma_f32_16x16x32_bf16 v[70:73], v[162:165], v[216:219], 0
	v_mfma_f32_16x16x32_bf16 v[66:69], v[170:173], v[216:219], 0
	v_mfma_f32_16x16x32_bf16 v[118:121], v[166:169], v[190:193], v[118:121]
	v_mfma_f32_16x16x32_bf16 v[114:117], v[182:185], v[190:193], v[114:117]
	v_mfma_f32_16x16x32_bf16 v[102:105], v[166:169], v[204:207], v[102:105]
	v_mfma_f32_16x16x32_bf16 v[98:101], v[182:185], v[204:207], v[98:101]
	v_mfma_f32_16x16x32_bf16 v[86:89], v[166:169], v[212:215], v[86:89]
	v_mfma_f32_16x16x32_bf16 v[82:85], v[182:185], v[212:215], v[82:85]
	v_mfma_f32_16x16x32_bf16 v[70:73], v[166:169], v[220:223], v[70:73]
	v_mfma_f32_16x16x32_bf16 v[66:69], v[182:185], v[220:223], v[66:69]
	s_barrier
	s_setprio 0
	s_add_i32 s94, s94, s2
	s_mov_b32 m0, s94
	s_nop 0
	global_load_lds_dwordx4 v174, s[82:83]
	ds_read_b128 v[186:189], v160 offset:16384
	ds_read_b128 v[190:193], v160 offset:17408
	ds_read_b128 v[194:197], v160 offset:18432
	ds_read_b128 v[204:207], v160 offset:19456
	ds_read_b128 v[208:211], v160 offset:20480
	ds_read_b128 v[212:215], v160 offset:21504
	ds_read_b128 v[216:219], v160 offset:22528
	ds_read_b128 v[220:223], v160 offset:23552
	s_add_i32 m0, s94, 0x2000
	s_nop 0
	global_load_lds_dwordx4 v142, s[82:83]
	s_add_i32 s94, s95, s2
	s_add_u32 s82, s82, s48
	s_addc_u32 s83, s83, 0
	s_mov_b32 m0, s94
	s_nop 0
	global_load_lds_dwordx4 v174, s[82:83]
	s_add_i32 m0, s94, 0x2000
	s_nop 0
	global_load_lds_dwordx4 v142, s[82:83]
	s_mov_b32 m0, s3
	s_nop 0
	global_load_lds_dwordx4 v138, s[54:55]
	s_mov_b32 m0, s12
	s_nop 0
	global_load_lds_dwordx4 v140, s[54:55]
	s_waitcnt vmcnt(8)
	s_waitcnt lgkmcnt(0)
	s_setprio 1
	s_barrier
	v_mfma_f32_16x16x32_bf16 v[62:65], v[130:133], v[186:189], 0
	v_mfma_f32_16x16x32_bf16 v[58:61], v[148:151], v[186:189], 0
	v_mfma_f32_16x16x32_bf16 v[46:49], v[130:133], v[194:197], 0
	v_mfma_f32_16x16x32_bf16 v[42:45], v[148:151], v[194:197], 0
	v_mfma_f32_16x16x32_bf16 v[30:33], v[130:133], v[208:211], 0
	v_mfma_f32_16x16x32_bf16 v[26:29], v[148:151], v[208:211], 0
	v_mfma_f32_16x16x32_bf16 v[14:17], v[130:133], v[216:219], 0
	v_mfma_f32_16x16x32_bf16 v[10:13], v[148:151], v[216:219], 0
	v_mfma_f32_16x16x32_bf16 v[62:65], v[134:137], v[190:193], v[62:65]
	v_mfma_f32_16x16x32_bf16 v[58:61], v[152:155], v[190:193], v[58:61]
	v_mfma_f32_16x16x32_bf16 v[46:49], v[134:137], v[204:207], v[46:49]
	v_mfma_f32_16x16x32_bf16 v[42:45], v[152:155], v[204:207], v[42:45]
	v_mfma_f32_16x16x32_bf16 v[30:33], v[134:137], v[212:215], v[30:33]
	v_mfma_f32_16x16x32_bf16 v[26:29], v[152:155], v[212:215], v[26:29]
	v_mfma_f32_16x16x32_bf16 v[14:17], v[134:137], v[220:223], v[14:17]
	v_mfma_f32_16x16x32_bf16 v[10:13], v[152:155], v[220:223], v[10:13]
	v_mfma_f32_16x16x32_bf16 v[54:57], v[162:165], v[186:189], 0
	v_mfma_f32_16x16x32_bf16 v[50:53], v[170:173], v[186:189], 0
	v_mfma_f32_16x16x32_bf16 v[38:41], v[162:165], v[194:197], 0
	v_mfma_f32_16x16x32_bf16 v[34:37], v[170:173], v[194:197], 0
	v_mfma_f32_16x16x32_bf16 v[22:25], v[162:165], v[208:211], 0
	v_mfma_f32_16x16x32_bf16 v[18:21], v[170:173], v[208:211], 0
	v_mfma_f32_16x16x32_bf16 v[6:9], v[162:165], v[216:219], 0
	v_mfma_f32_16x16x32_bf16 v[2:5], v[170:173], v[216:219], 0
	v_mfma_f32_16x16x32_bf16 v[54:57], v[166:169], v[190:193], v[54:57]
	v_mfma_f32_16x16x32_bf16 v[50:53], v[182:185], v[190:193], v[50:53]
	v_mfma_f32_16x16x32_bf16 v[38:41], v[166:169], v[204:207], v[38:41]
	v_mfma_f32_16x16x32_bf16 v[34:37], v[182:185], v[204:207], v[34:37]
	v_mfma_f32_16x16x32_bf16 v[22:25], v[166:169], v[212:215], v[22:25]
	v_mfma_f32_16x16x32_bf16 v[18:21], v[182:185], v[212:215], v[18:21]
	v_mfma_f32_16x16x32_bf16 v[6:9], v[166:169], v[220:223], v[6:9]
	v_mfma_f32_16x16x32_bf16 v[2:5], v[182:185], v[220:223], v[2:5]
	s_barrier
; #define PG8_STAGE(bufoff, gbase, voff) do { _Pragma("unroll") for (int _i = 0; _i < 2; ++_i) \
;         __builtin_amdgcn_global_load_lds((const unsigned*)((const char*)(gbase) + (voff)[_i]), (PG8_LAS unsigned*)(lds + (bufoff) + ldsw + _i * 8192), 16, 0, 0); } while (0)
; #define PG8_LDA(dst, b, h) do { _Pragma("unroll") for (int m = 0; m < 4; ++m) _Pragma("unroll") for (int k = 0; k < 2; ++k) dst[m][k] = *(const PG8_LAS bf16x8*)(lds + PG8_SA(b, h) + aoff + m * 2048 + k * 1024); } while (0)
; #define PG8_LDB(dst, b, h) do { _Pragma("unroll") for (int n = 0; n < 2; ++n) _Pragma("unroll") for (int k = 0; k < 2; ++k) dst[n][k] = *(const PG8_LAS bf16x8*)(lds + PG8_SB(b, h) + boff + n * 2048 + k * 1024); } while (0)
; #define PG8_WAIT_V(n) asm volatile("s_waitcnt vmcnt(" #n ")" ::: "memory")
; #define PG8_BAR __builtin_amdgcn_s_barrier()
; template <class Epi, class Sched, bool ALIGN_EPI = false, bool SP2 = false, bool F16 = false>
; __device__ __forceinline__ void gemm_phase(PG8_LAS unsigned char* lds, const Gemm g, const Sched& S, const Epi& E) {
;     ...
;             const char* a2 = last ? nA : cA + (size_t)(t + 2) * kstep; const char* b2 = last ? nB : cB + (size_t)(t + 2) * kstep;
;             const char* a3 = a2 + kstep; const char* b3 = b2 + kstep;
;             if (last && has_next) S.a_ready(nxt);
;             if constexpr (SP2) {
;             PG8_LDB(B0, 0, 0); PG8_LDB(B1, 0, 1); PG8_SCHED; PG8_LDA(At, 0, 0); PG8_STAGE(PG8_SA(1, 1), a1 + hstepA, voffA);
;             PG8_WAIT_V(8); PG8_WAIT_L(0); PG8_BAR; PG8_MMA(0, 0, At, B0); PG8_MMA(0, 1, At, B1); PG8_BAR; PG8_SCHED;
;             PG8_LDA(At, 0, 1); PG8_STAGE(PG8_SB(0, 0), b2, voffB); PG8_STAGE(PG8_SB(0, 1), b2 + hstepB, voffB); PG8_STAGE(PG8_SA(0, 0), a2, voffA);
;             PG8_WAIT_V(8); PG8_WAIT_L(0); PG8_BAR; PG8_MMA(1, 0, At, B0); PG8_MMA(1, 1, At, B1); PG8_BAR; PG8_SCHED;
;             PG8_LDB(B0, 1, 0); PG8_LDB(B1, 1, 1); PG8_SCHED; PG8_LDA(At, 1, 0); PG8_STAGE(PG8_SA(0, 1), a2 + hstepA, voffA);
;             PG8_WAIT_V(8); PG8_WAIT_L(0); PG8_BAR; PG8_MMA(0, 0, At, B0); PG8_MMA(0, 1, At, B1); PG8_BAR; PG8_SCHED;
;             PG8_LDA(At, 1, 1); PG8_STAGE(PG8_SB(1, 0), b3, voffB); PG8_STAGE(PG8_SB(1, 1), b3 + hstepB, voffB); PG8_STAGE(PG8_SA(1, 0), a3, voffA);
;             PG8_WAIT_V(8); PG8_WAIT_L(0); PG8_BAR; PG8_MMA(1, 0, At, B0); PG8_MMA(1, 1, At, B1); PG8_BAR; PG8_SCHED;
	s_setprio 0
	s_add_i32 s82, 0, 0x18000
	s_add_i32 s83, 0, 0x1c000
	ds_read_b128 v[130:133], v143
	ds_read_b128 v[134:137], v143 offset:1024
	ds_read_b128 v[148:151], v143 offset:2048
	ds_read_b128 v[152:155], v143 offset:3072
	ds_read_b128 v[162:165], v157
	ds_read_b128 v[166:169], v157 offset:1024
	ds_read_b128 v[170:173], v157 offset:2048
	ds_read_b128 v[182:185], v157 offset:3072
	s_add_u32 s54, s54, s8
	s_addc_u32 s55, s55, 0
	s_mov_b32 m0, s13
	ds_read_b128 v[186:189], v160 offset:32768
	ds_read_b128 v[190:193], v160 offset:33792
	ds_read_b128 v[194:197], v160 offset:34816
	ds_read_b128 v[204:207], v160 offset:35840
	ds_read_b128 v[208:211], v160 offset:36864
	ds_read_b128 v[212:215], v160 offset:37888
	ds_read_b128 v[216:219], v160 offset:38912
	ds_read_b128 v[220:223], v160 offset:39936
	global_load_lds_dwordx4 v138, s[54:55]
	s_mov_b32 m0, s22
	s_nop 0
	global_load_lds_dwordx4 v140, s[54:55]
	s_waitcnt vmcnt(8)
	s_waitcnt lgkmcnt(0)
	s_setprio 1
	s_barrier
	v_mfma_f32_16x16x32_bf16 v[122:125], v[130:133], v[186:189], v[122:125]
	v_mfma_f32_16x16x32_bf16 v[126:129], v[148:151], v[186:189], v[126:129]
	v_mfma_f32_16x16x32_bf16 v[110:113], v[130:133], v[194:197], v[110:113]
	v_mfma_f32_16x16x32_bf16 v[106:109], v[148:151], v[194:197], v[106:109]
	v_mfma_f32_16x16x32_bf16 v[94:97], v[130:133], v[208:211], v[94:97]
	v_mfma_f32_16x16x32_bf16 v[90:93], v[148:151], v[208:211], v[90:93]
	v_mfma_f32_16x16x32_bf16 v[78:81], v[130:133], v[216:219], v[78:81]
	v_mfma_f32_16x16x32_bf16 v[74:77], v[148:151], v[216:219], v[74:77]
	v_mfma_f32_16x16x32_bf16 v[122:125], v[134:137], v[190:193], v[122:125]
	v_mfma_f32_16x16x32_bf16 v[126:129], v[152:155], v[190:193], v[126:129]
	v_mfma_f32_16x16x32_bf16 v[110:113], v[134:137], v[204:207], v[110:113]
	v_mfma_f32_16x16x32_bf16 v[106:109], v[152:155], v[204:207], v[106:109]
	v_mfma_f32_16x16x32_bf16 v[94:97], v[134:137], v[212:215], v[94:97]
	v_mfma_f32_16x16x32_bf16 v[90:93], v[152:155], v[212:215], v[90:93]
	v_mfma_f32_16x16x32_bf16 v[78:81], v[134:137], v[220:223], v[78:81]
	v_mfma_f32_16x16x32_bf16 v[74:77], v[152:155], v[220:223], v[74:77]
	v_mfma_f32_16x16x32_bf16 v[118:121], v[162:165], v[186:189], v[118:121]
	v_mfma_f32_16x16x32_bf16 v[114:117], v[170:173], v[186:189], v[114:117]
	v_mfma_f32_16x16x32_bf16 v[102:105], v[162:165], v[194:197], v[102:105]
	v_mfma_f32_16x16x32_bf16 v[98:101], v[170:173], v[194:197], v[98:101]
	v_mfma_f32_16x16x32_bf16 v[86:89], v[162:165], v[208:211], v[86:89]
	v_mfma_f32_16x16x32_bf16 v[82:85], v[170:173], v[208:211], v[82:85]
	v_mfma_f32_16x16x32_bf16 v[70:73], v[162:165], v[216:219], v[70:73]
	v_mfma_f32_16x16x32_bf16 v[66:69], v[170:173], v[216:219], v[66:69]
	v_mfma_f32_16x16x32_bf16 v[118:121], v[166:169], v[190:193], v[118:121]
	v_mfma_f32_16x16x32_bf16 v[114:117], v[182:185], v[190:193], v[114:117]
	v_mfma_f32_16x16x32_bf16 v[102:105], v[166:169], v[204:207], v[102:105]
	v_mfma_f32_16x16x32_bf16 v[98:101], v[182:185], v[204:207], v[98:101]
	v_mfma_f32_16x16x32_bf16 v[86:89], v[166:169], v[212:215], v[86:89]
	v_mfma_f32_16x16x32_bf16 v[82:85], v[182:185], v[212:215], v[82:85]
	v_mfma_f32_16x16x32_bf16 v[70:73], v[166:169], v[220:223], v[70:73]
	v_mfma_f32_16x16x32_bf16 v[66:69], v[182:185], v[220:223], v[66:69]
	s_barrier
	s_setprio 0
	s_add_i32 s54, s82, s2
	s_add_i32 vcc_hi, s81, -2
	s_cmp_eq_u32 s74, vcc_hi
	s_cselect_b32 s99, s47, s80
	s_cselect_b32 s98, s46, s79
	s_add_u32 s98, s98, s92
	s_addc_u32 s99, s99, s93
	s_mov_b32 m0, s54
	s_nop 0
	global_load_lds_dwordx4 v174, s[98:99]
	ds_read_b128 v[186:189], v160 offset:49152
	ds_read_b128 v[190:193], v160 offset:50176
	ds_read_b128 v[194:197], v160 offset:51200
	ds_read_b128 v[204:207], v160 offset:52224
	ds_read_b128 v[208:211], v160 offset:53248
	ds_read_b128 v[212:215], v160 offset:54272
	ds_read_b128 v[216:219], v160 offset:55296
	ds_read_b128 v[220:223], v160 offset:56320
	s_add_i32 m0, s54, 0x2000
	s_nop 0
	global_load_lds_dwordx4 v142, s[98:99]
	s_add_i32 s54, s83, s2
	s_add_u32 s98, s98, s48
	s_addc_u32 s99, s99, 0
	s_mov_b32 m0, s54
	s_nop 0
	global_load_lds_dwordx4 v174, s[98:99]
	s_add_i32 m0, s54, 0x2000
	s_nop 0
	global_load_lds_dwordx4 v142, s[98:99]
	s_add_u32 s98, s52, 0x80
	s_addc_u32 s99, s53, 0
	s_cmp_eq_u32 s74, vcc_hi
	s_cselect_b32 s99, s41, s99
	s_cselect_b32 s98, s40, s98
	s_add_u32 s98, s98, s92
	s_addc_u32 s99, s99, s93
	s_mov_b32 m0, s33
	s_nop 0
	global_load_lds_dwordx4 v138, s[98:99]
	s_mov_b32 m0, s35
	s_nop 0
	global_load_lds_dwordx4 v140, s[98:99]
	s_waitcnt vmcnt(8)
	s_waitcnt lgkmcnt(0)
	s_setprio 1
	s_barrier
	v_mfma_f32_16x16x32_bf16 v[62:65], v[130:133], v[186:189], v[62:65]
	v_mfma_f32_16x16x32_bf16 v[58:61], v[148:151], v[186:189], v[58:61]
	v_mfma_f32_16x16x32_bf16 v[46:49], v[130:133], v[194:197], v[46:49]
	v_mfma_f32_16x16x32_bf16 v[42:45], v[148:151], v[194:197], v[42:45]
	v_mfma_f32_16x16x32_bf16 v[30:33], v[130:133], v[208:211], v[30:33]
	v_mfma_f32_16x16x32_bf16 v[26:29], v[148:151], v[208:211], v[26:29]
	v_mfma_f32_16x16x32_bf16 v[14:17], v[130:133], v[216:219], v[14:17]
	v_mfma_f32_16x16x32_bf16 v[10:13], v[148:151], v[216:219], v[10:13]
	v_mfma_f32_16x16x32_bf16 v[62:65], v[134:137], v[190:193], v[62:65]
	v_mfma_f32_16x16x32_bf16 v[58:61], v[152:155], v[190:193], v[58:61]
	v_mfma_f32_16x16x32_bf16 v[46:49], v[134:137], v[204:207], v[46:49]
	v_mfma_f32_16x16x32_bf16 v[42:45], v[152:155], v[204:207], v[42:45]
	v_mfma_f32_16x16x32_bf16 v[30:33], v[134:137], v[212:215], v[30:33]
	v_mfma_f32_16x16x32_bf16 v[26:29], v[152:155], v[212:215], v[26:29]
	v_mfma_f32_16x16x32_bf16 v[14:17], v[134:137], v[220:223], v[14:17]
	v_mfma_f32_16x16x32_bf16 v[10:13], v[152:155], v[220:223], v[10:13]
	v_mfma_f32_16x16x32_bf16 v[54:57], v[162:165], v[186:189], v[54:57]
	v_mfma_f32_16x16x32_bf16 v[50:53], v[170:173], v[186:189], v[50:53]
	v_mfma_f32_16x16x32_bf16 v[38:41], v[162:165], v[194:197], v[38:41]
	v_mfma_f32_16x16x32_bf16 v[34:37], v[170:173], v[194:197], v[34:37]
	v_mfma_f32_16x16x32_bf16 v[22:25], v[162:165], v[208:211], v[22:25]
	v_mfma_f32_16x16x32_bf16 v[18:21], v[170:173], v[208:211], v[18:21]
	v_mfma_f32_16x16x32_bf16 v[6:9], v[162:165], v[216:219], v[6:9]
	v_mfma_f32_16x16x32_bf16 v[2:5], v[170:173], v[216:219], v[2:5]
	v_mfma_f32_16x16x32_bf16 v[54:57], v[166:169], v[190:193], v[54:57]
	v_mfma_f32_16x16x32_bf16 v[50:53], v[182:185], v[190:193], v[50:53]
	v_mfma_f32_16x16x32_bf16 v[38:41], v[166:169], v[204:207], v[38:41]
	v_mfma_f32_16x16x32_bf16 v[34:37], v[182:185], v[204:207], v[34:37]
	v_mfma_f32_16x16x32_bf16 v[22:25], v[166:169], v[212:215], v[22:25]
	v_mfma_f32_16x16x32_bf16 v[18:21], v[182:185], v[212:215], v[18:21]
	v_mfma_f32_16x16x32_bf16 v[6:9], v[166:169], v[220:223], v[6:9]
	v_mfma_f32_16x16x32_bf16 v[2:5], v[182:185], v[220:223], v[2:5]
	s_barrier
	s_setprio 0
	s_add_u32 s52, s52, 0x100
	s_addc_u32 s53, s53, 0
	s_add_u32 s79, s79, 0x100
	s_addc_u32 s80, s80, 0
	s_cmp_ge_u32 s81, s65
	s_mov_b32 s54, s81
	s_cbranch_scc1 .LBB0_346
; #define PG8_STAGE(bufoff, gbase, voff) do { _Pragma("unroll") for (int _i = 0; _i < 2; ++_i) \
;         __builtin_amdgcn_global_load_lds((const unsigned*)((const char*)(gbase) + (voff)[_i]), (PG8_LAS unsigned*)(lds + (bufoff) + ldsw + _i * 8192), 16, 0, 0); } while (0)
; #define PG8_LDA(dst, b, h) do { _Pragma("unroll") for (int m = 0; m < 4; ++m) _Pragma("unroll") for (int k = 0; k < 2; ++k) dst[m][k] = *(const PG8_LAS bf16x8*)(lds + PG8_SA(b, h) + aoff + m * 2048 + k * 1024); } while (0)
; #define PG8_LDB(dst, b, h) do { _Pragma("unroll") for (int n = 0; n < 2; ++n) _Pragma("unroll") for (int k = 0; k < 2; ++k) dst[n][k] = *(const PG8_LAS bf16x8*)(lds + PG8_SB(b, h) + boff + n * 2048 + k * 1024); } while (0)
; #define PG8_WAIT_V(n) asm volatile("s_waitcnt vmcnt(" #n ")" ::: "memory")
; #define PG8_WAIT_L(n) asm volatile("s_waitcnt lgkmcnt(" #n ")" ::: "memory")
; #define PG8_BAR __builtin_amdgcn_s_barrier()
; #define PG8_SCHED __builtin_amdgcn_sched_barrier(0)
; template <class Epi, class Sched, bool ALIGN_EPI = false, bool SP2 = false, bool F16 = false>
; __device__ __forceinline__ void gemm_phase(PG8_LAS unsigned char* lds, const Gemm g, const Sched& S, const Epi& E) {
;     ...
;         for (int t = 0; t < nt; t += 2) {
;             const bool last = (t == nt - 2);
;             const char* a1 = cA + (size_t)(t + 1) * kstep;
;             const char* a2 = last ? nA : cA + (size_t)(t + 2) * kstep; const char* b2 = last ? nB : cB + (size_t)(t + 2) * kstep;
;             const char* a3 = a2 + kstep; const char* b3 = b2 + kstep;
;             if (last && has_next) S.a_ready(nxt);
;             if constexpr (SP2) {
;             PG8_LDB(B0, 0, 0); PG8_LDB(B1, 0, 1); PG8_SCHED; PG8_LDA(At, 0, 0); PG8_STAGE(PG8_SA(1, 1), a1 + hstepA, voffA);
;             PG8_WAIT_V(8); PG8_WAIT_L(0); PG8_BAR; PG8_MMA(0, 0, At, B0); PG8_MMA(0, 1, At, B1); PG8_BAR; PG8_SCHED;
;             PG8_LDA(At, 0, 1); PG8_STAGE(PG8_SB(0, 0), b2, voffB); PG8_STAGE(PG8_SB(0, 1), b2 + hstepB, voffB); PG8_STAGE(PG8_SA(0, 0), a2, voffA);
;             PG8_WAIT_V(8); PG8_WAIT_L(0); PG8_BAR; PG8_MMA(1, 0, At, B0); PG8_MMA(1, 1, At, B1); PG8_BAR; PG8_SCHED;
.LBB0_345:
	s_add_i32 s81, s54, 2
	s_add_u32 s82, s52, 0x80
	s_addc_u32 s55, s53, 0
	s_add_i32 s94, 0, 0x10000
	s_cmp_eq_u32 s74, s54
	s_cselect_b32 s55, s41, s55
	s_cselect_b32 s54, s40, s82
	s_cselect_b32 s83, s47, s80
	s_cselect_b32 s82, s46, s79
	s_add_i32 s95, 0, 0x14000
	ds_read_b128 v[130:133], v139
	ds_read_b128 v[134:137], v139 offset:1024
	ds_read_b128 v[148:151], v139 offset:2048
	ds_read_b128 v[152:155], v139 offset:3072
	ds_read_b128 v[162:165], v141
	ds_read_b128 v[166:169], v141 offset:1024
	ds_read_b128 v[170:173], v141 offset:2048
	ds_read_b128 v[182:185], v141 offset:3072
	s_add_i32 m0, s3, 0xc000
	ds_read_b128 v[186:189], v160
	ds_read_b128 v[190:193], v160 offset:1024
	ds_read_b128 v[194:197], v160 offset:2048
	ds_read_b128 v[204:207], v160 offset:3072
	ds_read_b128 v[208:211], v160 offset:4096
	ds_read_b128 v[212:215], v160 offset:5120
	ds_read_b128 v[216:219], v160 offset:6144
	ds_read_b128 v[220:223], v160 offset:7168
	global_load_lds_dwordx4 v144, s[52:53]
	s_add_i32 m0, s3, 0xe000
	s_nop 0
	global_load_lds_dwordx4 v146, s[52:53]
	s_waitcnt vmcnt(8)
	s_waitcnt lgkmcnt(0)
	s_setprio 1
	s_barrier
	v_mfma_f32_16x16x32_bf16 v[122:125], v[130:133], v[186:189], v[122:125]
	v_mfma_f32_16x16x32_bf16 v[126:129], v[148:151], v[186:189], v[126:129]
	v_mfma_f32_16x16x32_bf16 v[110:113], v[130:133], v[194:197], v[110:113]
	v_mfma_f32_16x16x32_bf16 v[106:109], v[148:151], v[194:197], v[106:109]
	v_mfma_f32_16x16x32_bf16 v[94:97], v[130:133], v[208:211], v[94:97]
	v_mfma_f32_16x16x32_bf16 v[90:93], v[148:151], v[208:211], v[90:93]
	v_mfma_f32_16x16x32_bf16 v[78:81], v[130:133], v[216:219], v[78:81]
	v_mfma_f32_16x16x32_bf16 v[74:77], v[148:151], v[216:219], v[74:77]
	v_mfma_f32_16x16x32_bf16 v[122:125], v[134:137], v[190:193], v[122:125]
	v_mfma_f32_16x16x32_bf16 v[126:129], v[152:155], v[190:193], v[126:129]
	v_mfma_f32_16x16x32_bf16 v[110:113], v[134:137], v[204:207], v[110:113]
	v_mfma_f32_16x16x32_bf16 v[106:109], v[152:155], v[204:207], v[106:109]
	v_mfma_f32_16x16x32_bf16 v[94:97], v[134:137], v[212:215], v[94:97]
	v_mfma_f32_16x16x32_bf16 v[90:93], v[152:155], v[212:215], v[90:93]
	v_mfma_f32_16x16x32_bf16 v[78:81], v[134:137], v[220:223], v[78:81]
	v_mfma_f32_16x16x32_bf16 v[74:77], v[152:155], v[220:223], v[74:77]
	v_mfma_f32_16x16x32_bf16 v[118:121], v[162:165], v[186:189], v[118:121]
	v_mfma_f32_16x16x32_bf16 v[114:117], v[170:173], v[186:189], v[114:117]
	v_mfma_f32_16x16x32_bf16 v[102:105], v[162:165], v[194:197], v[102:105]
	v_mfma_f32_16x16x32_bf16 v[98:101], v[170:173], v[194:197], v[98:101]
	v_mfma_f32_16x16x32_bf16 v[86:89], v[162:165], v[208:211], v[86:89]
	v_mfma_f32_16x16x32_bf16 v[82:85], v[170:173], v[208:211], v[82:85]
	v_mfma_f32_16x16x32_bf16 v[70:73], v[162:165], v[216:219], v[70:73]
	v_mfma_f32_16x16x32_bf16 v[66:69], v[170:173], v[216:219], v[66:69]
	v_mfma_f32_16x16x32_bf16 v[118:121], v[166:169], v[190:193], v[118:121]
	v_mfma_f32_16x16x32_bf16 v[114:117], v[182:185], v[190:193], v[114:117]
	v_mfma_f32_16x16x32_bf16 v[102:105], v[166:169], v[204:207], v[102:105]
	v_mfma_f32_16x16x32_bf16 v[98:101], v[182:185], v[204:207], v[98:101]
	v_mfma_f32_16x16x32_bf16 v[86:89], v[166:169], v[212:215], v[86:89]
	v_mfma_f32_16x16x32_bf16 v[82:85], v[182:185], v[212:215], v[82:85]
	v_mfma_f32_16x16x32_bf16 v[70:73], v[166:169], v[220:223], v[70:73]
	v_mfma_f32_16x16x32_bf16 v[66:69], v[182:185], v[220:223], v[66:69]
	s_barrier
	s_setprio 0
	s_add_i32 s94, s94, s2
	s_mov_b32 m0, s94
	s_nop 0
	global_load_lds_dwordx4 v174, s[82:83]
	ds_read_b128 v[186:189], v160 offset:16384
	ds_read_b128 v[190:193], v160 offset:17408
	ds_read_b128 v[194:197], v160 offset:18432
	ds_read_b128 v[204:207], v160 offset:19456
	ds_read_b128 v[208:211], v160 offset:20480
	ds_read_b128 v[212:215], v160 offset:21504
	ds_read_b128 v[216:219], v160 offset:22528
	ds_read_b128 v[220:223], v160 offset:23552
	s_add_i32 m0, s94, 0x2000
	s_nop 0
	global_load_lds_dwordx4 v142, s[82:83]
	s_add_i32 s94, s95, s2
	s_add_u32 s82, s82, s48
	s_addc_u32 s83, s83, 0
	s_mov_b32 m0, s94
	s_nop 0
	global_load_lds_dwordx4 v174, s[82:83]
	s_add_i32 m0, s94, 0x2000
	s_nop 0
	global_load_lds_dwordx4 v142, s[82:83]
	s_mov_b32 m0, s3
	s_nop 0
	global_load_lds_dwordx4 v138, s[54:55]
	s_mov_b32 m0, s12
	s_nop 0
	global_load_lds_dwordx4 v140, s[54:55]
	s_waitcnt vmcnt(8)
	s_waitcnt lgkmcnt(0)
	s_setprio 1
	s_barrier
	v_mfma_f32_16x16x32_bf16 v[62:65], v[130:133], v[186:189], v[62:65]
	v_mfma_f32_16x16x32_bf16 v[58:61], v[148:151], v[186:189], v[58:61]
	v_mfma_f32_16x16x32_bf16 v[46:49], v[130:133], v[194:197], v[46:49]
	v_mfma_f32_16x16x32_bf16 v[42:45], v[148:151], v[194:197], v[42:45]
	v_mfma_f32_16x16x32_bf16 v[30:33], v[130:133], v[208:211], v[30:33]
	v_mfma_f32_16x16x32_bf16 v[26:29], v[148:151], v[208:211], v[26:29]
	v_mfma_f32_16x16x32_bf16 v[14:17], v[130:133], v[216:219], v[14:17]
	v_mfma_f32_16x16x32_bf16 v[10:13], v[148:151], v[216:219], v[10:13]
	v_mfma_f32_16x16x32_bf16 v[62:65], v[134:137], v[190:193], v[62:65]
	v_mfma_f32_16x16x32_bf16 v[58:61], v[152:155], v[190:193], v[58:61]
	v_mfma_f32_16x16x32_bf16 v[46:49], v[134:137], v[204:207], v[46:49]
	v_mfma_f32_16x16x32_bf16 v[42:45], v[152:155], v[204:207], v[42:45]
	v_mfma_f32_16x16x32_bf16 v[30:33], v[134:137], v[212:215], v[30:33]
	v_mfma_f32_16x16x32_bf16 v[26:29], v[152:155], v[212:215], v[26:29]
	v_mfma_f32_16x16x32_bf16 v[14:17], v[134:137], v[220:223], v[14:17]
	v_mfma_f32_16x16x32_bf16 v[10:13], v[152:155], v[220:223], v[10:13]
	v_mfma_f32_16x16x32_bf16 v[54:57], v[162:165], v[186:189], v[54:57]
	v_mfma_f32_16x16x32_bf16 v[50:53], v[170:173], v[186:189], v[50:53]
	v_mfma_f32_16x16x32_bf16 v[38:41], v[162:165], v[194:197], v[38:41]
	v_mfma_f32_16x16x32_bf16 v[34:37], v[170:173], v[194:197], v[34:37]
	v_mfma_f32_16x16x32_bf16 v[22:25], v[162:165], v[208:211], v[22:25]
	v_mfma_f32_16x16x32_bf16 v[18:21], v[170:173], v[208:211], v[18:21]
	v_mfma_f32_16x16x32_bf16 v[6:9], v[162:165], v[216:219], v[6:9]
	v_mfma_f32_16x16x32_bf16 v[2:5], v[170:173], v[216:219], v[2:5]
	v_mfma_f32_16x16x32_bf16 v[54:57], v[166:169], v[190:193], v[54:57]
	v_mfma_f32_16x16x32_bf16 v[50:53], v[182:185], v[190:193], v[50:53]
	v_mfma_f32_16x16x32_bf16 v[38:41], v[166:169], v[204:207], v[38:41]
	v_mfma_f32_16x16x32_bf16 v[34:37], v[182:185], v[204:207], v[34:37]
	v_mfma_f32_16x16x32_bf16 v[22:25], v[166:169], v[212:215], v[22:25]
	v_mfma_f32_16x16x32_bf16 v[18:21], v[182:185], v[212:215], v[18:21]
	v_mfma_f32_16x16x32_bf16 v[6:9], v[166:169], v[220:223], v[6:9]
	v_mfma_f32_16x16x32_bf16 v[2:5], v[182:185], v[220:223], v[2:5]
	s_barrier
; #define PG8_STAGE(bufoff, gbase, voff) do { _Pragma("unroll") for (int _i = 0; _i < 2; ++_i) \
;         __builtin_amdgcn_global_load_lds((const unsigned*)((const char*)(gbase) + (voff)[_i]), (PG8_LAS unsigned*)(lds + (bufoff) + ldsw + _i * 8192), 16, 0, 0); } while (0)
; #define PG8_LDA(dst, b, h) do { _Pragma("unroll") for (int m = 0; m < 4; ++m) _Pragma("unroll") for (int k = 0; k < 2; ++k) dst[m][k] = *(const PG8_LAS bf16x8*)(lds + PG8_SA(b, h) + aoff + m * 2048 + k * 1024); } while (0)
; #define PG8_LDB(dst, b, h) do { _Pragma("unroll") for (int n = 0; n < 2; ++n) _Pragma("unroll") for (int k = 0; k < 2; ++k) dst[n][k] = *(const PG8_LAS bf16x8*)(lds + PG8_SB(b, h) + boff + n * 2048 + k * 1024); } while (0)
; #define PG8_WAIT_V(n) asm volatile("s_waitcnt vmcnt(" #n ")" ::: "memory")
; #define PG8_BAR __builtin_amdgcn_s_barrier()
; template <class Epi, class Sched, bool ALIGN_EPI = false, bool SP2 = false, bool F16 = false>
; __device__ __forceinline__ void gemm_phase(PG8_LAS unsigned char* lds, const Gemm g, const Sched& S, const Epi& E) {
;     ...
;             const char* a2 = last ? nA : cA + (size_t)(t + 2) * kstep; const char* b2 = last ? nB : cB + (size_t)(t + 2) * kstep;
;             const char* a3 = a2 + kstep; const char* b3 = b2 + kstep;
;             if (last && has_next) S.a_ready(nxt);
;             if constexpr (SP2) {
;             PG8_LDB(B0, 0, 0); PG8_LDB(B1, 0, 1); PG8_SCHED; PG8_LDA(At, 0, 0); PG8_STAGE(PG8_SA(1, 1), a1 + hstepA, voffA);
;             PG8_WAIT_V(8); PG8_WAIT_L(0); PG8_BAR; PG8_MMA(0, 0, At, B0); PG8_MMA(0, 1, At, B1); PG8_BAR; PG8_SCHED;
;             PG8_LDA(At, 0, 1); PG8_STAGE(PG8_SB(0, 0), b2, voffB); PG8_STAGE(PG8_SB(0, 1), b2 + hstepB, voffB); PG8_STAGE(PG8_SA(0, 0), a2, voffA);
;             PG8_WAIT_V(8); PG8_WAIT_L(0); PG8_BAR; PG8_MMA(1, 0, At, B0); PG8_MMA(1, 1, At, B1); PG8_BAR; PG8_SCHED;
;             PG8_LDB(B0, 1, 0); PG8_LDB(B1, 1, 1); PG8_SCHED; PG8_LDA(At, 1, 0); PG8_STAGE(PG8_SA(0, 1), a2 + hstepA, voffA);
;             PG8_WAIT_V(8); PG8_WAIT_L(0); PG8_BAR; PG8_MMA(0, 0, At, B0); PG8_MMA(0, 1, At, B1); PG8_BAR; PG8_SCHED;
;             PG8_LDA(At, 1, 1); PG8_STAGE(PG8_SB(1, 0), b3, voffB); PG8_STAGE(PG8_SB(1, 1), b3 + hstepB, voffB); PG8_STAGE(PG8_SA(1, 0), a3, voffA);
;             PG8_WAIT_V(8); PG8_WAIT_L(0); PG8_BAR; PG8_MMA(1, 0, At, B0); PG8_MMA(1, 1, At, B1); PG8_BAR; PG8_SCHED;
	s_setprio 0
	s_add_i32 s82, 0, 0x18000
	s_add_i32 s83, 0, 0x1c000
	ds_read_b128 v[130:133], v143
	ds_read_b128 v[134:137], v143 offset:1024
	ds_read_b128 v[148:151], v143 offset:2048
	ds_read_b128 v[152:155], v143 offset:3072
	ds_read_b128 v[162:165], v157
	ds_read_b128 v[166:169], v157 offset:1024
	ds_read_b128 v[170:173], v157 offset:2048
	ds_read_b128 v[182:185], v157 offset:3072
	s_add_u32 s54, s54, s8
	s_addc_u32 s55, s55, 0
	s_mov_b32 m0, s13
	ds_read_b128 v[186:189], v160 offset:32768
	ds_read_b128 v[190:193], v160 offset:33792
	ds_read_b128 v[194:197], v160 offset:34816
	ds_read_b128 v[204:207], v160 offset:35840
	ds_read_b128 v[208:211], v160 offset:36864
	ds_read_b128 v[212:215], v160 offset:37888
	ds_read_b128 v[216:219], v160 offset:38912
	ds_read_b128 v[220:223], v160 offset:39936
	global_load_lds_dwordx4 v138, s[54:55]
	s_mov_b32 m0, s22
	s_nop 0
	global_load_lds_dwordx4 v140, s[54:55]
	s_waitcnt vmcnt(8)
	s_waitcnt lgkmcnt(0)
	s_setprio 1
	s_barrier
	v_mfma_f32_16x16x32_bf16 v[122:125], v[130:133], v[186:189], v[122:125]
	v_mfma_f32_16x16x32_bf16 v[126:129], v[148:151], v[186:189], v[126:129]
	v_mfma_f32_16x16x32_bf16 v[110:113], v[130:133], v[194:197], v[110:113]
	v_mfma_f32_16x16x32_bf16 v[106:109], v[148:151], v[194:197], v[106:109]
	v_mfma_f32_16x16x32_bf16 v[94:97], v[130:133], v[208:211], v[94:97]
	v_mfma_f32_16x16x32_bf16 v[90:93], v[148:151], v[208:211], v[90:93]
	v_mfma_f32_16x16x32_bf16 v[78:81], v[130:133], v[216:219], v[78:81]
	v_mfma_f32_16x16x32_bf16 v[74:77], v[148:151], v[216:219], v[74:77]
	v_mfma_f32_16x16x32_bf16 v[122:125], v[134:137], v[190:193], v[122:125]
	v_mfma_f32_16x16x32_bf16 v[126:129], v[152:155], v[190:193], v[126:129]
	v_mfma_f32_16x16x32_bf16 v[110:113], v[134:137], v[204:207], v[110:113]
	v_mfma_f32_16x16x32_bf16 v[106:109], v[152:155], v[204:207], v[106:109]
	v_mfma_f32_16x16x32_bf16 v[94:97], v[134:137], v[212:215], v[94:97]
	v_mfma_f32_16x16x32_bf16 v[90:93], v[152:155], v[212:215], v[90:93]
	v_mfma_f32_16x16x32_bf16 v[78:81], v[134:137], v[220:223], v[78:81]
	v_mfma_f32_16x16x32_bf16 v[74:77], v[152:155], v[220:223], v[74:77]
	v_mfma_f32_16x16x32_bf16 v[118:121], v[162:165], v[186:189], v[118:121]
	v_mfma_f32_16x16x32_bf16 v[114:117], v[170:173], v[186:189], v[114:117]
	v_mfma_f32_16x16x32_bf16 v[102:105], v[162:165], v[194:197], v[102:105]
	v_mfma_f32_16x16x32_bf16 v[98:101], v[170:173], v[194:197], v[98:101]
	v_mfma_f32_16x16x32_bf16 v[86:89], v[162:165], v[208:211], v[86:89]
	v_mfma_f32_16x16x32_bf16 v[82:85], v[170:173], v[208:211], v[82:85]
	v_mfma_f32_16x16x32_bf16 v[70:73], v[162:165], v[216:219], v[70:73]
	v_mfma_f32_16x16x32_bf16 v[66:69], v[170:173], v[216:219], v[66:69]
	v_mfma_f32_16x16x32_bf16 v[118:121], v[166:169], v[190:193], v[118:121]
	v_mfma_f32_16x16x32_bf16 v[114:117], v[182:185], v[190:193], v[114:117]
	v_mfma_f32_16x16x32_bf16 v[102:105], v[166:169], v[204:207], v[102:105]
	v_mfma_f32_16x16x32_bf16 v[98:101], v[182:185], v[204:207], v[98:101]
	v_mfma_f32_16x16x32_bf16 v[86:89], v[166:169], v[212:215], v[86:89]
	v_mfma_f32_16x16x32_bf16 v[82:85], v[182:185], v[212:215], v[82:85]
	v_mfma_f32_16x16x32_bf16 v[70:73], v[166:169], v[220:223], v[70:73]
	v_mfma_f32_16x16x32_bf16 v[66:69], v[182:185], v[220:223], v[66:69]
	s_barrier
	s_setprio 0
	s_add_i32 s54, s82, s2
	s_add_i32 vcc_hi, s81, -2
	s_cmp_eq_u32 s74, vcc_hi
	s_cselect_b32 s99, s47, s80
	s_cselect_b32 s98, s46, s79
	s_add_u32 s98, s98, s92
	s_addc_u32 s99, s99, s93
	s_mov_b32 m0, s54
	s_nop 0
	global_load_lds_dwordx4 v174, s[98:99]
	ds_read_b128 v[186:189], v160 offset:49152
	ds_read_b128 v[190:193], v160 offset:50176
	ds_read_b128 v[194:197], v160 offset:51200
	ds_read_b128 v[204:207], v160 offset:52224
	ds_read_b128 v[208:211], v160 offset:53248
	ds_read_b128 v[212:215], v160 offset:54272
	ds_read_b128 v[216:219], v160 offset:55296
	ds_read_b128 v[220:223], v160 offset:56320
	s_add_i32 m0, s54, 0x2000
	s_nop 0
	global_load_lds_dwordx4 v142, s[98:99]
	s_add_i32 s54, s83, s2
	s_add_u32 s98, s98, s48
	s_addc_u32 s99, s99, 0
	s_mov_b32 m0, s54
	s_nop 0
	global_load_lds_dwordx4 v174, s[98:99]
	s_add_i32 m0, s54, 0x2000
	s_nop 0
	global_load_lds_dwordx4 v142, s[98:99]
	s_add_u32 s98, s52, 0x80
	s_addc_u32 s99, s53, 0
	s_cmp_eq_u32 s74, vcc_hi
	s_cselect_b32 s99, s41, s99
	s_cselect_b32 s98, s40, s98
	s_add_u32 s98, s98, s92
	s_addc_u32 s99, s99, s93
	s_mov_b32 m0, s33
	s_nop 0
	global_load_lds_dwordx4 v138, s[98:99]
	s_mov_b32 m0, s35
	s_nop 0
	global_load_lds_dwordx4 v140, s[98:99]
	s_waitcnt vmcnt(8)
	s_waitcnt lgkmcnt(0)
	s_setprio 1
	s_barrier
	v_mfma_f32_16x16x32_bf16 v[62:65], v[130:133], v[186:189], v[62:65]
	v_mfma_f32_16x16x32_bf16 v[58:61], v[148:151], v[186:189], v[58:61]
	v_mfma_f32_16x16x32_bf16 v[46:49], v[130:133], v[194:197], v[46:49]
	v_mfma_f32_16x16x32_bf16 v[42:45], v[148:151], v[194:197], v[42:45]
	v_mfma_f32_16x16x32_bf16 v[30:33], v[130:133], v[208:211], v[30:33]
	v_mfma_f32_16x16x32_bf16 v[26:29], v[148:151], v[208:211], v[26:29]
	v_mfma_f32_16x16x32_bf16 v[14:17], v[130:133], v[216:219], v[14:17]
	v_mfma_f32_16x16x32_bf16 v[10:13], v[148:151], v[216:219], v[10:13]
	v_mfma_f32_16x16x32_bf16 v[62:65], v[134:137], v[190:193], v[62:65]
	v_mfma_f32_16x16x32_bf16 v[58:61], v[152:155], v[190:193], v[58:61]
	v_mfma_f32_16x16x32_bf16 v[46:49], v[134:137], v[204:207], v[46:49]
	v_mfma_f32_16x16x32_bf16 v[42:45], v[152:155], v[204:207], v[42:45]
	v_mfma_f32_16x16x32_bf16 v[30:33], v[134:137], v[212:215], v[30:33]
	v_mfma_f32_16x16x32_bf16 v[26:29], v[152:155], v[212:215], v[26:29]
	v_mfma_f32_16x16x32_bf16 v[14:17], v[134:137], v[220:223], v[14:17]
	v_mfma_f32_16x16x32_bf16 v[10:13], v[152:155], v[220:223], v[10:13]
	v_mfma_f32_16x16x32_bf16 v[54:57], v[162:165], v[186:189], v[54:57]
	v_mfma_f32_16x16x32_bf16 v[50:53], v[170:173], v[186:189], v[50:53]
	v_mfma_f32_16x16x32_bf16 v[38:41], v[162:165], v[194:197], v[38:41]
	v_mfma_f32_16x16x32_bf16 v[34:37], v[170:173], v[194:197], v[34:37]
	v_mfma_f32_16x16x32_bf16 v[22:25], v[162:165], v[208:211], v[22:25]
	v_mfma_f32_16x16x32_bf16 v[18:21], v[170:173], v[208:211], v[18:21]
	v_mfma_f32_16x16x32_bf16 v[6:9], v[162:165], v[216:219], v[6:9]
	v_mfma_f32_16x16x32_bf16 v[2:5], v[170:173], v[216:219], v[2:5]
	v_mfma_f32_16x16x32_bf16 v[54:57], v[166:169], v[190:193], v[54:57]
	v_mfma_f32_16x16x32_bf16 v[50:53], v[182:185], v[190:193], v[50:53]
	v_mfma_f32_16x16x32_bf16 v[38:41], v[166:169], v[204:207], v[38:41]
	v_mfma_f32_16x16x32_bf16 v[34:37], v[182:185], v[204:207], v[34:37]
	v_mfma_f32_16x16x32_bf16 v[22:25], v[166:169], v[212:215], v[22:25]
	v_mfma_f32_16x16x32_bf16 v[18:21], v[182:185], v[212:215], v[18:21]
	v_mfma_f32_16x16x32_bf16 v[6:9], v[166:169], v[220:223], v[6:9]
	v_mfma_f32_16x16x32_bf16 v[2:5], v[182:185], v[220:223], v[2:5]
	s_barrier
	s_setprio 0
	s_add_u32 s52, s52, 0x100
	s_addc_u32 s53, s53, 0
	s_add_u32 s79, s79, 0x100
	s_addc_u32 s80, s80, 0
	s_cmp_ge_u32 s81, s65
	s_mov_b32 s54, s81
	s_cbranch_scc0 .LBB0_345

; #define PG8_STAGE(bufoff, gbase, voff) do { _Pragma("unroll") for (int _i = 0; _i < 2; ++_i) \
;         __builtin_amdgcn_global_load_lds((const unsigned*)((const char*)(gbase) + (voff)[_i]), (PG8_LAS unsigned*)(lds + (bufoff) + ldsw + _i * 8192), 16, 0, 0); } while (0)
; #define PG8_LDA(dst, b, h) do { _Pragma("unroll") for (int m = 0; m < 4; ++m) _Pragma("unroll") for (int k = 0; k < 2; ++k) dst[m][k] = *(const PG8_LAS bf16x8*)(lds + PG8_SA(b, h) + aoff + m * 2048 + k * 1024); } while (0)
; #define PG8_LDB(dst, b, h) do { _Pragma("unroll") for (int n = 0; n < 2; ++n) _Pragma("unroll") for (int k = 0; k < 2; ++k) dst[n][k] = *(const PG8_LAS bf16x8*)(lds + PG8_SB(b, h) + boff + n * 2048 + k * 1024); } while (0)
; #define PG8_WAIT_V(n) asm volatile("s_waitcnt vmcnt(" #n ")" ::: "memory")
; #define PG8_WAIT_L(n) asm volatile("s_waitcnt lgkmcnt(" #n ")" ::: "memory")
; #define PG8_BAR __builtin_amdgcn_s_barrier()
; #define PG8_SCHED __builtin_amdgcn_sched_barrier(0)
; template <class Epi, class Sched, bool ALIGN_EPI = false, bool SP2 = false, bool F16 = false>
; __device__ __forceinline__ void gemm_phase(PG8_LAS unsigned char* lds, const Gemm g, const Sched& S, const Epi& E) {
;     ...
;     for (;;) {
;         const bool has_next = S.next(ui + 1, nxt);
;         const char* nA = has_next ? (const char*)g.A + (size_t)nxt.pm * tstepA : cA; const char* nB = has_next ? (const char*)g.Bt + (size_t)nxt.pn * tstepB : cB;
;         for (int t = 0; t < nt; t += 2) {
;             const bool last = (t == nt - 2);
;             const char* a1 = cA + (size_t)(t + 1) * kstep;
;             const char* a2 = last ? nA : cA + (size_t)(t + 2) * kstep; const char* b2 = last ? nB : cB + (size_t)(t + 2) * kstep;
;             const char* a3 = a2 + kstep; const char* b3 = b2 + kstep;
;             if (last && has_next) S.a_ready(nxt);
;             if constexpr (SP2) {
;             PG8_LDB(B0, 0, 0); PG8_LDB(B1, 0, 1); PG8_SCHED; PG8_LDA(At, 0, 0); PG8_STAGE(PG8_SA(1, 1), a1 + hstepA, voffA);
;             PG8_WAIT_V(8); PG8_WAIT_L(0); PG8_BAR; PG8_MMA(0, 0, At, B0); PG8_MMA(0, 1, At, B1); PG8_BAR; PG8_SCHED;
;             PG8_LDA(At, 0, 1); PG8_STAGE(PG8_SB(0, 0), b2, voffB); PG8_STAGE(PG8_SB(0, 1), b2 + hstepB, voffB); PG8_STAGE(PG8_SA(0, 0), a2, voffA);
;             PG8_WAIT_V(8); PG8_WAIT_L(0); PG8_BAR; PG8_MMA(1, 0, At, B0); PG8_MMA(1, 1, At, B1); PG8_BAR; PG8_SCHED;
.LBB0_396:
	s_andn2_b64 vcc, exec, s[4:5]
	s_waitcnt vmcnt(0)
	s_cbranch_vccnz .Lzk_bf
	s_add_u32 s46, s78, 0x80
	s_addc_u32 s47, s79, 0
	s_add_u32 s13, s72, 0x100
	s_addc_u32 s24, s73, 0
	s_mov_b32 s72, 0
	v_add_u32_e32 v155, 0x10000, v163
	v_add_u32_e32 v157, 0x14000, v163
	v_add_u32_e32 v159, 0x18000, v163
	v_add_u32_e32 v161, 0x1c000, v163
.Lpk_bf:
	s_add_i32 s78, s72, 2
	s_add_u32 s79, s46, 0x80
	s_addc_u32 s73, s47, 0
	s_add_i32 vcc_lo, 0, 0x10000
	s_cmp_eq_u32 s74, s72
	s_cselect_b32 s73, s55, s73
	s_cselect_b32 s72, s54, s79
	s_cselect_b32 s95, s53, s24
	s_cselect_b32 s94, s52, s13
	s_add_i32 s79, 0, 0x14000
	ds_read_b128 v[130:133], v155
	ds_read_b128 v[134:137], v155 offset:1024
	ds_read_b128 v[138:141], v155 offset:2048
	ds_read_b128 v[142:145], v155 offset:3072
	ds_read_b128 v[146:149], v157
	ds_read_b128 v[150:153], v157 offset:1024
	ds_read_b128 v[182:185], v157 offset:2048
	ds_read_b128 v[186:189], v157 offset:3072
	s_add_i32 m0, s36, 0xc000
	ds_read_b128 v[190:193], v204
	ds_read_b128 v[194:197], v204 offset:1024
	ds_read_b128 v[206:209], v204 offset:2048
	ds_read_b128 v[210:213], v204 offset:3072
	ds_read_b128 v[214:217], v204 offset:4096
	ds_read_b128 v[218:221], v204 offset:5120
	ds_read_b128 v[222:225], v204 offset:6144
	ds_read_b128 v[226:229], v204 offset:7168
	global_load_lds_dwordx4 v168, s[46:47]
	s_add_i32 m0, s36, 0xe000
	s_nop 0
	global_load_lds_dwordx4 v170, s[46:47]
	s_waitcnt vmcnt(8)
	s_waitcnt lgkmcnt(0)
	s_setprio 1
	s_barrier
	v_mfma_f32_16x16x32_bf16 v[122:125], v[130:133], v[190:193], 0
	v_mfma_f32_16x16x32_bf16 v[126:129], v[138:141], v[190:193], 0
	v_mfma_f32_16x16x32_bf16 v[110:113], v[130:133], v[206:209], 0
	v_mfma_f32_16x16x32_bf16 v[106:109], v[138:141], v[206:209], 0
	v_mfma_f32_16x16x32_bf16 v[94:97], v[130:133], v[214:217], 0
	v_mfma_f32_16x16x32_bf16 v[90:93], v[138:141], v[214:217], 0
	v_mfma_f32_16x16x32_bf16 v[78:81], v[130:133], v[222:225], 0
	v_mfma_f32_16x16x32_bf16 v[74:77], v[138:141], v[222:225], 0
	v_mfma_f32_16x16x32_bf16 v[122:125], v[134:137], v[194:197], v[122:125]
	v_mfma_f32_16x16x32_bf16 v[126:129], v[142:145], v[194:197], v[126:129]
	v_mfma_f32_16x16x32_bf16 v[110:113], v[134:137], v[210:213], v[110:113]
	v_mfma_f32_16x16x32_bf16 v[106:109], v[142:145], v[210:213], v[106:109]
	v_mfma_f32_16x16x32_bf16 v[94:97], v[134:137], v[218:221], v[94:97]
	v_mfma_f32_16x16x32_bf16 v[90:93], v[142:145], v[218:221], v[90:93]
	v_mfma_f32_16x16x32_bf16 v[78:81], v[134:137], v[226:229], v[78:81]
	v_mfma_f32_16x16x32_bf16 v[74:77], v[142:145], v[226:229], v[74:77]
	v_mfma_f32_16x16x32_bf16 v[118:121], v[146:149], v[190:193], 0
	v_mfma_f32_16x16x32_bf16 v[114:117], v[182:185], v[190:193], 0
	v_mfma_f32_16x16x32_bf16 v[102:105], v[146:149], v[206:209], 0
	v_mfma_f32_16x16x32_bf16 v[98:101], v[182:185], v[206:209], 0
	v_mfma_f32_16x16x32_bf16 v[86:89], v[146:149], v[214:217], 0
	v_mfma_f32_16x16x32_bf16 v[82:85], v[182:185], v[214:217], 0
	v_mfma_f32_16x16x32_bf16 v[70:73], v[146:149], v[222:225], 0
	v_mfma_f32_16x16x32_bf16 v[66:69], v[182:185], v[222:225], 0
	v_mfma_f32_16x16x32_bf16 v[118:121], v[150:153], v[194:197], v[118:121]
	v_mfma_f32_16x16x32_bf16 v[114:117], v[186:189], v[194:197], v[114:117]
	v_mfma_f32_16x16x32_bf16 v[102:105], v[150:153], v[210:213], v[102:105]
	v_mfma_f32_16x16x32_bf16 v[98:101], v[186:189], v[210:213], v[98:101]
	v_mfma_f32_16x16x32_bf16 v[86:89], v[150:153], v[218:221], v[86:89]
	v_mfma_f32_16x16x32_bf16 v[82:85], v[186:189], v[218:221], v[82:85]
	v_mfma_f32_16x16x32_bf16 v[70:73], v[150:153], v[226:229], v[70:73]
	v_mfma_f32_16x16x32_bf16 v[66:69], v[186:189], v[226:229], v[66:69]
	s_barrier
	s_setprio 0
	s_add_i32 vcc_lo, vcc_lo, s75
	s_mov_b32 m0, vcc_lo
	s_nop 0
	global_load_lds_dwordx4 v156, s[94:95]
	ds_read_b128 v[190:193], v204 offset:16384
	ds_read_b128 v[194:197], v204 offset:17408
	ds_read_b128 v[206:209], v204 offset:18432
	ds_read_b128 v[210:213], v204 offset:19456
	ds_read_b128 v[214:217], v204 offset:20480
	ds_read_b128 v[218:221], v204 offset:21504
	ds_read_b128 v[222:225], v204 offset:22528
	ds_read_b128 v[226:229], v204 offset:23552
	s_add_i32 m0, vcc_lo, 0x2000
	s_nop 0
	global_load_lds_dwordx4 v160, s[94:95]
	s_add_i32 s79, s79, s75
	s_add_u32 s94, s94, s48
	s_addc_u32 s95, s95, 0
	s_mov_b32 m0, s79
	s_nop 0
	global_load_lds_dwordx4 v156, s[94:95]
	s_add_i32 m0, s79, 0x2000
	s_nop 0
	global_load_lds_dwordx4 v160, s[94:95]
	s_mov_b32 m0, s36
	s_nop 0
	global_load_lds_dwordx4 v154, s[72:73]
	s_mov_b32 m0, s37
	s_nop 0
	global_load_lds_dwordx4 v158, s[72:73]
	s_waitcnt vmcnt(8)
	s_waitcnt lgkmcnt(0)
	s_setprio 1
	s_barrier
; #define PG8_STAGE(bufoff, gbase, voff) do { _Pragma("unroll") for (int _i = 0; _i < 2; ++_i) \
;         __builtin_amdgcn_global_load_lds((const unsigned*)((const char*)(gbase) + (voff)[_i]), (PG8_LAS unsigned*)(lds + (bufoff) + ldsw + _i * 8192), 16, 0, 0); } while (0)
; #define PG8_LDA(dst, b, h) do { _Pragma("unroll") for (int m = 0; m < 4; ++m) _Pragma("unroll") for (int k = 0; k < 2; ++k) dst[m][k] = *(const PG8_LAS bf16x8*)(lds + PG8_SA(b, h) + aoff + m * 2048 + k * 1024); } while (0)
; #define PG8_LDB(dst, b, h) do { _Pragma("unroll") for (int n = 0; n < 2; ++n) _Pragma("unroll") for (int k = 0; k < 2; ++k) dst[n][k] = *(const PG8_LAS bf16x8*)(lds + PG8_SB(b, h) + boff + n * 2048 + k * 1024); } while (0)
; #define PG8_WAIT_V(n) asm volatile("s_waitcnt vmcnt(" #n ")" ::: "memory")
; #define PG8_WAIT_L(n) asm volatile("s_waitcnt lgkmcnt(" #n ")" ::: "memory")
; #define PG8_BAR __builtin_amdgcn_s_barrier()
; #define PG8_SCHED __builtin_amdgcn_sched_barrier(0)
; template <class Epi, class Sched, bool ALIGN_EPI = false, bool SP2 = false, bool F16 = false>
; __device__ __forceinline__ void gemm_phase(PG8_LAS unsigned char* lds, const Gemm g, const Sched& S, const Epi& E) {
;     ...
;             PG8_WAIT_V(8); PG8_WAIT_L(0); PG8_BAR; PG8_MMA(1, 0, At, B0); PG8_MMA(1, 1, At, B1); PG8_BAR; PG8_SCHED;
;             PG8_LDB(B0, 1, 0); PG8_LDB(B1, 1, 1); PG8_SCHED; PG8_LDA(At, 1, 0); PG8_STAGE(PG8_SA(0, 1), a2 + hstepA, voffA);
;             PG8_WAIT_V(8); PG8_WAIT_L(0); PG8_BAR; PG8_MMA(0, 0, At, B0); PG8_MMA(0, 1, At, B1); PG8_BAR; PG8_SCHED;
	v_mfma_f32_16x16x32_bf16 v[62:65], v[130:133], v[190:193], 0
	v_mfma_f32_16x16x32_bf16 v[58:61], v[138:141], v[190:193], 0
	v_mfma_f32_16x16x32_bf16 v[46:49], v[130:133], v[206:209], 0
	v_mfma_f32_16x16x32_bf16 v[42:45], v[138:141], v[206:209], 0
	v_mfma_f32_16x16x32_bf16 v[30:33], v[130:133], v[214:217], 0
	v_mfma_f32_16x16x32_bf16 v[26:29], v[138:141], v[214:217], 0
	v_mfma_f32_16x16x32_bf16 v[14:17], v[130:133], v[222:225], 0
	v_mfma_f32_16x16x32_bf16 v[10:13], v[138:141], v[222:225], 0
	v_mfma_f32_16x16x32_bf16 v[62:65], v[134:137], v[194:197], v[62:65]
	v_mfma_f32_16x16x32_bf16 v[58:61], v[142:145], v[194:197], v[58:61]
	v_mfma_f32_16x16x32_bf16 v[46:49], v[134:137], v[210:213], v[46:49]
	v_mfma_f32_16x16x32_bf16 v[42:45], v[142:145], v[210:213], v[42:45]
	v_mfma_f32_16x16x32_bf16 v[30:33], v[134:137], v[218:221], v[30:33]
	v_mfma_f32_16x16x32_bf16 v[26:29], v[142:145], v[218:221], v[26:29]
	v_mfma_f32_16x16x32_bf16 v[14:17], v[134:137], v[226:229], v[14:17]
	v_mfma_f32_16x16x32_bf16 v[10:13], v[142:145], v[226:229], v[10:13]
	v_mfma_f32_16x16x32_bf16 v[54:57], v[146:149], v[190:193], 0
	v_mfma_f32_16x16x32_bf16 v[50:53], v[182:185], v[190:193], 0
	v_mfma_f32_16x16x32_bf16 v[38:41], v[146:149], v[206:209], 0
	v_mfma_f32_16x16x32_bf16 v[34:37], v[182:185], v[206:209], 0
	v_mfma_f32_16x16x32_bf16 v[22:25], v[146:149], v[214:217], 0
	v_mfma_f32_16x16x32_bf16 v[18:21], v[182:185], v[214:217], 0
	v_mfma_f32_16x16x32_bf16 v[6:9], v[146:149], v[222:225], 0
	v_mfma_f32_16x16x32_bf16 v[2:5], v[182:185], v[222:225], 0
	v_mfma_f32_16x16x32_bf16 v[54:57], v[150:153], v[194:197], v[54:57]
	v_mfma_f32_16x16x32_bf16 v[50:53], v[186:189], v[194:197], v[50:53]
	v_mfma_f32_16x16x32_bf16 v[38:41], v[150:153], v[210:213], v[38:41]
	v_mfma_f32_16x16x32_bf16 v[34:37], v[186:189], v[210:213], v[34:37]
	v_mfma_f32_16x16x32_bf16 v[22:25], v[150:153], v[218:221], v[22:25]
	v_mfma_f32_16x16x32_bf16 v[18:21], v[186:189], v[218:221], v[18:21]
	v_mfma_f32_16x16x32_bf16 v[6:9], v[150:153], v[226:229], v[6:9]
	v_mfma_f32_16x16x32_bf16 v[2:5], v[186:189], v[226:229], v[2:5]
	s_barrier
	s_setprio 0
	s_add_i32 s79, 0, 0x18000
	s_add_i32 s94, 0, 0x1c000
	ds_read_b128 v[130:133], v159
	ds_read_b128 v[134:137], v159 offset:1024
	ds_read_b128 v[138:141], v159 offset:2048
	ds_read_b128 v[142:145], v159 offset:3072
	ds_read_b128 v[146:149], v161
	ds_read_b128 v[150:153], v161 offset:1024
	ds_read_b128 v[182:185], v161 offset:2048
	ds_read_b128 v[186:189], v161 offset:3072
	s_add_u32 s72, s72, s8
	s_addc_u32 s73, s73, 0
	s_mov_b32 m0, s35
	ds_read_b128 v[190:193], v204 offset:32768
	ds_read_b128 v[194:197], v204 offset:33792
	ds_read_b128 v[206:209], v204 offset:34816
	ds_read_b128 v[210:213], v204 offset:35840
	ds_read_b128 v[214:217], v204 offset:36864
	ds_read_b128 v[218:221], v204 offset:37888
	ds_read_b128 v[222:225], v204 offset:38912
	ds_read_b128 v[226:229], v204 offset:39936
	global_load_lds_dwordx4 v154, s[72:73]
	s_mov_b32 m0, s2
	s_nop 0
	global_load_lds_dwordx4 v158, s[72:73]
	s_waitcnt vmcnt(8)
	s_waitcnt lgkmcnt(0)
	s_setprio 1
	s_barrier
	v_mfma_f32_16x16x32_bf16 v[122:125], v[130:133], v[190:193], v[122:125]
	v_mfma_f32_16x16x32_bf16 v[126:129], v[138:141], v[190:193], v[126:129]
	v_mfma_f32_16x16x32_bf16 v[110:113], v[130:133], v[206:209], v[110:113]
	v_mfma_f32_16x16x32_bf16 v[106:109], v[138:141], v[206:209], v[106:109]
	v_mfma_f32_16x16x32_bf16 v[94:97], v[130:133], v[214:217], v[94:97]
	v_mfma_f32_16x16x32_bf16 v[90:93], v[138:141], v[214:217], v[90:93]
	v_mfma_f32_16x16x32_bf16 v[78:81], v[130:133], v[222:225], v[78:81]
	v_mfma_f32_16x16x32_bf16 v[74:77], v[138:141], v[222:225], v[74:77]
	v_mfma_f32_16x16x32_bf16 v[122:125], v[134:137], v[194:197], v[122:125]
	v_mfma_f32_16x16x32_bf16 v[126:129], v[142:145], v[194:197], v[126:129]
	v_mfma_f32_16x16x32_bf16 v[110:113], v[134:137], v[210:213], v[110:113]
	v_mfma_f32_16x16x32_bf16 v[106:109], v[142:145], v[210:213], v[106:109]
	v_mfma_f32_16x16x32_bf16 v[94:97], v[134:137], v[218:221], v[94:97]
	v_mfma_f32_16x16x32_bf16 v[90:93], v[142:145], v[218:221], v[90:93]
	v_mfma_f32_16x16x32_bf16 v[78:81], v[134:137], v[226:229], v[78:81]
	v_mfma_f32_16x16x32_bf16 v[74:77], v[142:145], v[226:229], v[74:77]
	v_mfma_f32_16x16x32_bf16 v[118:121], v[146:149], v[190:193], v[118:121]
	v_mfma_f32_16x16x32_bf16 v[114:117], v[182:185], v[190:193], v[114:117]
	v_mfma_f32_16x16x32_bf16 v[102:105], v[146:149], v[206:209], v[102:105]
	v_mfma_f32_16x16x32_bf16 v[98:101], v[182:185], v[206:209], v[98:101]
	v_mfma_f32_16x16x32_bf16 v[86:89], v[146:149], v[214:217], v[86:89]
	v_mfma_f32_16x16x32_bf16 v[82:85], v[182:185], v[214:217], v[82:85]
	v_mfma_f32_16x16x32_bf16 v[70:73], v[146:149], v[222:225], v[70:73]
	v_mfma_f32_16x16x32_bf16 v[66:69], v[182:185], v[222:225], v[66:69]
	v_mfma_f32_16x16x32_bf16 v[118:121], v[150:153], v[194:197], v[118:121]
	v_mfma_f32_16x16x32_bf16 v[114:117], v[186:189], v[194:197], v[114:117]
	v_mfma_f32_16x16x32_bf16 v[102:105], v[150:153], v[210:213], v[102:105]
	v_mfma_f32_16x16x32_bf16 v[98:101], v[186:189], v[210:213], v[98:101]
	v_mfma_f32_16x16x32_bf16 v[86:89], v[150:153], v[218:221], v[86:89]
	v_mfma_f32_16x16x32_bf16 v[82:85], v[186:189], v[218:221], v[82:85]
	v_mfma_f32_16x16x32_bf16 v[70:73], v[150:153], v[226:229], v[70:73]
	v_mfma_f32_16x16x32_bf16 v[66:69], v[186:189], v[226:229], v[66:69]
	s_barrier
; #define PG8_STAGE(bufoff, gbase, voff) do { _Pragma("unroll") for (int _i = 0; _i < 2; ++_i) \
;         __builtin_amdgcn_global_load_lds((const unsigned*)((const char*)(gbase) + (voff)[_i]), (PG8_LAS unsigned*)(lds + (bufoff) + ldsw + _i * 8192), 16, 0, 0); } while (0)
; #define PG8_LDA(dst, b, h) do { _Pragma("unroll") for (int m = 0; m < 4; ++m) _Pragma("unroll") for (int k = 0; k < 2; ++k) dst[m][k] = *(const PG8_LAS bf16x8*)(lds + PG8_SA(b, h) + aoff + m * 2048 + k * 1024); } while (0)
; #define PG8_WAIT_V(n) asm volatile("s_waitcnt vmcnt(" #n ")" ::: "memory")
; #define PG8_WAIT_L(n) asm volatile("s_waitcnt lgkmcnt(" #n ")" ::: "memory")
; #define PG8_BAR __builtin_amdgcn_s_barrier()
; template <class Epi, class Sched, bool ALIGN_EPI = false, bool SP2 = false, bool F16 = false>
; __device__ __forceinline__ void gemm_phase(PG8_LAS unsigned char* lds, const Gemm g, const Sched& S, const Epi& E) {
;     ...
;         for (int t = 0; t < nt; t += 2) {
;             const bool last = (t == nt - 2);
;             const char* a1 = cA + (size_t)(t + 1) * kstep;
;             const char* a2 = last ? nA : cA + (size_t)(t + 2) * kstep; const char* b2 = last ? nB : cB + (size_t)(t + 2) * kstep;
;             const char* a3 = a2 + kstep; const char* b3 = b2 + kstep;
;             if (last && has_next) S.a_ready(nxt);
;             if constexpr (SP2) {
;             PG8_LDB(B0, 0, 0); PG8_LDB(B1, 0, 1); PG8_SCHED; PG8_LDA(At, 0, 0); PG8_STAGE(PG8_SA(1, 1), a1 + hstepA, voffA);
;             PG8_WAIT_V(8); PG8_WAIT_L(0); PG8_BAR; PG8_MMA(0, 0, At, B0); PG8_MMA(0, 1, At, B1); PG8_BAR; PG8_SCHED;
;             PG8_LDA(At, 0, 1); PG8_STAGE(PG8_SB(0, 0), b2, voffB); PG8_STAGE(PG8_SB(0, 1), b2 + hstepB, voffB); PG8_STAGE(PG8_SA(0, 0), a2, voffA);
;             PG8_WAIT_V(8); PG8_WAIT_L(0); PG8_BAR; PG8_MMA(1, 0, At, B0); PG8_MMA(1, 1, At, B1); PG8_BAR; PG8_SCHED;
;             PG8_LDB(B0, 1, 0); PG8_LDB(B1, 1, 1); PG8_SCHED; PG8_LDA(At, 1, 0); PG8_STAGE(PG8_SA(0, 1), a2 + hstepA, voffA);
;             PG8_WAIT_V(8); PG8_WAIT_L(0); PG8_BAR; PG8_MMA(0, 0, At, B0); PG8_MMA(0, 1, At, B1); PG8_BAR; PG8_SCHED;
;             PG8_LDA(At, 1, 1); PG8_STAGE(PG8_SB(1, 0), b3, voffB); PG8_STAGE(PG8_SB(1, 1), b3 + hstepB, voffB); PG8_STAGE(PG8_SA(1, 0), a3, voffA);
;             PG8_WAIT_V(8); PG8_WAIT_L(0); PG8_BAR; PG8_MMA(1, 0, At, B0); PG8_MMA(1, 1, At, B1); PG8_BAR; PG8_SCHED;
	s_setprio 0
	s_add_i32 s72, s79, s75
	s_add_i32 vcc_hi, s78, -2
	s_cmp_eq_u32 s74, vcc_hi
	s_cselect_b32 s99, s53, s24
	s_cselect_b32 s98, s52, s13
	s_add_u32 s98, s98, s92
	s_addc_u32 s99, s99, s93
	s_mov_b32 m0, s72
	s_nop 0
	global_load_lds_dwordx4 v156, s[98:99]
	ds_read_b128 v[190:193], v204 offset:49152
	ds_read_b128 v[194:197], v204 offset:50176
	ds_read_b128 v[206:209], v204 offset:51200
	ds_read_b128 v[210:213], v204 offset:52224
	ds_read_b128 v[214:217], v204 offset:53248
	ds_read_b128 v[218:221], v204 offset:54272
	ds_read_b128 v[222:225], v204 offset:55296
	ds_read_b128 v[226:229], v204 offset:56320
	s_add_i32 m0, s72, 0x2000
	s_nop 0
	global_load_lds_dwordx4 v160, s[98:99]
	s_add_i32 s72, s94, s75
	s_add_u32 s98, s98, s48
	s_addc_u32 s99, s99, 0
	s_mov_b32 m0, s72
	s_nop 0
	global_load_lds_dwordx4 v156, s[98:99]
	s_add_i32 m0, s72, 0x2000
	s_nop 0
	global_load_lds_dwordx4 v160, s[98:99]
	s_add_u32 s98, s46, 0x80
	s_addc_u32 s99, s47, 0
	s_cmp_eq_u32 s74, vcc_hi
	s_cselect_b32 s99, s55, s99
	s_cselect_b32 s98, s54, s98
	s_add_u32 s98, s98, s92
	s_addc_u32 s99, s99, s93
	s_mov_b32 m0, s22
	s_nop 0
	global_load_lds_dwordx4 v154, s[98:99]
	s_mov_b32 m0, s23
	s_nop 0
	global_load_lds_dwordx4 v158, s[98:99]
	s_waitcnt vmcnt(8)
	s_waitcnt lgkmcnt(0)
	s_setprio 1
	s_barrier
	v_mfma_f32_16x16x32_bf16 v[62:65], v[130:133], v[190:193], v[62:65]
	v_mfma_f32_16x16x32_bf16 v[58:61], v[138:141], v[190:193], v[58:61]
	v_mfma_f32_16x16x32_bf16 v[46:49], v[130:133], v[206:209], v[46:49]
	v_mfma_f32_16x16x32_bf16 v[42:45], v[138:141], v[206:209], v[42:45]
	v_mfma_f32_16x16x32_bf16 v[30:33], v[130:133], v[214:217], v[30:33]
	v_mfma_f32_16x16x32_bf16 v[26:29], v[138:141], v[214:217], v[26:29]
	v_mfma_f32_16x16x32_bf16 v[14:17], v[130:133], v[222:225], v[14:17]
	v_mfma_f32_16x16x32_bf16 v[10:13], v[138:141], v[222:225], v[10:13]
	v_mfma_f32_16x16x32_bf16 v[62:65], v[134:137], v[194:197], v[62:65]
	v_mfma_f32_16x16x32_bf16 v[58:61], v[142:145], v[194:197], v[58:61]
	v_mfma_f32_16x16x32_bf16 v[46:49], v[134:137], v[210:213], v[46:49]
	v_mfma_f32_16x16x32_bf16 v[42:45], v[142:145], v[210:213], v[42:45]
	v_mfma_f32_16x16x32_bf16 v[30:33], v[134:137], v[218:221], v[30:33]
	v_mfma_f32_16x16x32_bf16 v[26:29], v[142:145], v[218:221], v[26:29]
	v_mfma_f32_16x16x32_bf16 v[14:17], v[134:137], v[226:229], v[14:17]
	v_mfma_f32_16x16x32_bf16 v[10:13], v[142:145], v[226:229], v[10:13]
	v_mfma_f32_16x16x32_bf16 v[54:57], v[146:149], v[190:193], v[54:57]
	v_mfma_f32_16x16x32_bf16 v[50:53], v[182:185], v[190:193], v[50:53]
	v_mfma_f32_16x16x32_bf16 v[38:41], v[146:149], v[206:209], v[38:41]
	v_mfma_f32_16x16x32_bf16 v[34:37], v[182:185], v[206:209], v[34:37]
	v_mfma_f32_16x16x32_bf16 v[22:25], v[146:149], v[214:217], v[22:25]
	v_mfma_f32_16x16x32_bf16 v[18:21], v[182:185], v[214:217], v[18:21]
	v_mfma_f32_16x16x32_bf16 v[6:9], v[146:149], v[222:225], v[6:9]
	v_mfma_f32_16x16x32_bf16 v[2:5], v[182:185], v[222:225], v[2:5]
	v_mfma_f32_16x16x32_bf16 v[54:57], v[150:153], v[194:197], v[54:57]
	v_mfma_f32_16x16x32_bf16 v[50:53], v[186:189], v[194:197], v[50:53]
	v_mfma_f32_16x16x32_bf16 v[38:41], v[150:153], v[210:213], v[38:41]
	v_mfma_f32_16x16x32_bf16 v[34:37], v[186:189], v[210:213], v[34:37]
	v_mfma_f32_16x16x32_bf16 v[22:25], v[150:153], v[218:221], v[22:25]
	v_mfma_f32_16x16x32_bf16 v[18:21], v[186:189], v[218:221], v[18:21]
	v_mfma_f32_16x16x32_bf16 v[6:9], v[150:153], v[226:229], v[6:9]
	v_mfma_f32_16x16x32_bf16 v[2:5], v[186:189], v[226:229], v[2:5]
	s_barrier
	s_setprio 0
	s_add_u32 s46, s46, 0x100
	s_addc_u32 s47, s47, 0
	s_add_u32 s13, s13, 0x100
	s_addc_u32 s24, s24, 0
	s_cmp_ge_u32 s78, s65
	s_mov_b32 s72, s78
	s_cbranch_scc1 .LBB0_399
.LBB0_398:
	s_add_i32 s78, s72, 2
	s_add_u32 s79, s46, 0x80
	s_addc_u32 s73, s47, 0
	s_add_i32 vcc_lo, 0, 0x10000
	s_cmp_eq_u32 s74, s72
	s_cselect_b32 s73, s55, s73
	s_cselect_b32 s72, s54, s79
	s_cselect_b32 s95, s53, s24
	s_cselect_b32 s94, s52, s13
	s_add_i32 s79, 0, 0x14000
	ds_read_b128 v[130:133], v155
	ds_read_b128 v[134:137], v155 offset:1024
	ds_read_b128 v[138:141], v155 offset:2048
	ds_read_b128 v[142:145], v155 offset:3072
	ds_read_b128 v[146:149], v157
	ds_read_b128 v[150:153], v157 offset:1024
	ds_read_b128 v[182:185], v157 offset:2048
	ds_read_b128 v[186:189], v157 offset:3072
	s_add_i32 m0, s36, 0xc000
	ds_read_b128 v[190:193], v204
	ds_read_b128 v[194:197], v204 offset:1024
	ds_read_b128 v[206:209], v204 offset:2048
	ds_read_b128 v[210:213], v204 offset:3072
	ds_read_b128 v[214:217], v204 offset:4096
	ds_read_b128 v[218:221], v204 offset:5120
	ds_read_b128 v[222:225], v204 offset:6144
	ds_read_b128 v[226:229], v204 offset:7168
	global_load_lds_dwordx4 v168, s[46:47]
	s_add_i32 m0, s36, 0xe000
	s_nop 0
	global_load_lds_dwordx4 v170, s[46:47]
	s_waitcnt vmcnt(8)
	s_waitcnt lgkmcnt(0)
	s_setprio 1
	s_barrier
; #define PG8_STAGE(bufoff, gbase, voff) do { _Pragma("unroll") for (int _i = 0; _i < 2; ++_i) \
;         __builtin_amdgcn_global_load_lds((const unsigned*)((const char*)(gbase) + (voff)[_i]), (PG8_LAS unsigned*)(lds + (bufoff) + ldsw + _i * 8192), 16, 0, 0); } while (0)
; #define PG8_LDA(dst, b, h) do { _Pragma("unroll") for (int m = 0; m < 4; ++m) _Pragma("unroll") for (int k = 0; k < 2; ++k) dst[m][k] = *(const PG8_LAS bf16x8*)(lds + PG8_SA(b, h) + aoff + m * 2048 + k * 1024); } while (0)
; #define PG8_WAIT_V(n) asm volatile("s_waitcnt vmcnt(" #n ")" ::: "memory")
; #define PG8_WAIT_L(n) asm volatile("s_waitcnt lgkmcnt(" #n ")" ::: "memory")
; #define PG8_BAR __builtin_amdgcn_s_barrier()
; #define PG8_SCHED __builtin_amdgcn_sched_barrier(0)
; template <class Epi, class Sched, bool ALIGN_EPI = false, bool SP2 = false, bool F16 = false>
; __device__ __forceinline__ void gemm_phase(PG8_LAS unsigned char* lds, const Gemm g, const Sched& S, const Epi& E) {
;     ...
;             PG8_WAIT_V(8); PG8_WAIT_L(0); PG8_BAR; PG8_MMA(0, 0, At, B0); PG8_MMA(0, 1, At, B1); PG8_BAR; PG8_SCHED;
;             PG8_LDA(At, 0, 1); PG8_STAGE(PG8_SB(0, 0), b2, voffB); PG8_STAGE(PG8_SB(0, 1), b2 + hstepB, voffB); PG8_STAGE(PG8_SA(0, 0), a2, voffA);
;             PG8_WAIT_V(8); PG8_WAIT_L(0); PG8_BAR; PG8_MMA(1, 0, At, B0); PG8_MMA(1, 1, At, B1); PG8_BAR; PG8_SCHED;
	v_mfma_f32_16x16x32_bf16 v[122:125], v[130:133], v[190:193], v[122:125]
	v_mfma_f32_16x16x32_bf16 v[126:129], v[138:141], v[190:193], v[126:129]
	v_mfma_f32_16x16x32_bf16 v[110:113], v[130:133], v[206:209], v[110:113]
	v_mfma_f32_16x16x32_bf16 v[106:109], v[138:141], v[206:209], v[106:109]
	v_mfma_f32_16x16x32_bf16 v[94:97], v[130:133], v[214:217], v[94:97]
	v_mfma_f32_16x16x32_bf16 v[90:93], v[138:141], v[214:217], v[90:93]
	v_mfma_f32_16x16x32_bf16 v[78:81], v[130:133], v[222:225], v[78:81]
	v_mfma_f32_16x16x32_bf16 v[74:77], v[138:141], v[222:225], v[74:77]
	v_mfma_f32_16x16x32_bf16 v[122:125], v[134:137], v[194:197], v[122:125]
	v_mfma_f32_16x16x32_bf16 v[126:129], v[142:145], v[194:197], v[126:129]
	v_mfma_f32_16x16x32_bf16 v[110:113], v[134:137], v[210:213], v[110:113]
	v_mfma_f32_16x16x32_bf16 v[106:109], v[142:145], v[210:213], v[106:109]
	v_mfma_f32_16x16x32_bf16 v[94:97], v[134:137], v[218:221], v[94:97]
	v_mfma_f32_16x16x32_bf16 v[90:93], v[142:145], v[218:221], v[90:93]
	v_mfma_f32_16x16x32_bf16 v[78:81], v[134:137], v[226:229], v[78:81]
	v_mfma_f32_16x16x32_bf16 v[74:77], v[142:145], v[226:229], v[74:77]
	v_mfma_f32_16x16x32_bf16 v[118:121], v[146:149], v[190:193], v[118:121]
	v_mfma_f32_16x16x32_bf16 v[114:117], v[182:185], v[190:193], v[114:117]
	v_mfma_f32_16x16x32_bf16 v[102:105], v[146:149], v[206:209], v[102:105]
	v_mfma_f32_16x16x32_bf16 v[98:101], v[182:185], v[206:209], v[98:101]
	v_mfma_f32_16x16x32_bf16 v[86:89], v[146:149], v[214:217], v[86:89]
	v_mfma_f32_16x16x32_bf16 v[82:85], v[182:185], v[214:217], v[82:85]
	v_mfma_f32_16x16x32_bf16 v[70:73], v[146:149], v[222:225], v[70:73]
	v_mfma_f32_16x16x32_bf16 v[66:69], v[182:185], v[222:225], v[66:69]
	v_mfma_f32_16x16x32_bf16 v[118:121], v[150:153], v[194:197], v[118:121]
	v_mfma_f32_16x16x32_bf16 v[114:117], v[186:189], v[194:197], v[114:117]
	v_mfma_f32_16x16x32_bf16 v[102:105], v[150:153], v[210:213], v[102:105]
	v_mfma_f32_16x16x32_bf16 v[98:101], v[186:189], v[210:213], v[98:101]
	v_mfma_f32_16x16x32_bf16 v[86:89], v[150:153], v[218:221], v[86:89]
	v_mfma_f32_16x16x32_bf16 v[82:85], v[186:189], v[218:221], v[82:85]
	v_mfma_f32_16x16x32_bf16 v[70:73], v[150:153], v[226:229], v[70:73]
	v_mfma_f32_16x16x32_bf16 v[66:69], v[186:189], v[226:229], v[66:69]
	s_barrier
	s_setprio 0
	s_add_i32 vcc_lo, vcc_lo, s75
	s_mov_b32 m0, vcc_lo
	s_nop 0
	global_load_lds_dwordx4 v156, s[94:95]
	ds_read_b128 v[190:193], v204 offset:16384
	ds_read_b128 v[194:197], v204 offset:17408
	ds_read_b128 v[206:209], v204 offset:18432
	ds_read_b128 v[210:213], v204 offset:19456
	ds_read_b128 v[214:217], v204 offset:20480
	ds_read_b128 v[218:221], v204 offset:21504
	ds_read_b128 v[222:225], v204 offset:22528
	ds_read_b128 v[226:229], v204 offset:23552
	s_add_i32 m0, vcc_lo, 0x2000
	s_nop 0
	global_load_lds_dwordx4 v160, s[94:95]
	s_add_i32 s79, s79, s75
	s_add_u32 s94, s94, s48
	s_addc_u32 s95, s95, 0
	s_mov_b32 m0, s79
	s_nop 0
	global_load_lds_dwordx4 v156, s[94:95]
	s_add_i32 m0, s79, 0x2000
	s_nop 0
	global_load_lds_dwordx4 v160, s[94:95]
	s_mov_b32 m0, s36
	s_nop 0
	global_load_lds_dwordx4 v154, s[72:73]
	s_mov_b32 m0, s37
	s_nop 0
	global_load_lds_dwordx4 v158, s[72:73]
	s_waitcnt vmcnt(8)
	s_waitcnt lgkmcnt(0)
	s_setprio 1
	s_barrier
	v_mfma_f32_16x16x32_bf16 v[62:65], v[130:133], v[190:193], v[62:65]
	v_mfma_f32_16x16x32_bf16 v[58:61], v[138:141], v[190:193], v[58:61]
	v_mfma_f32_16x16x32_bf16 v[46:49], v[130:133], v[206:209], v[46:49]
	v_mfma_f32_16x16x32_bf16 v[42:45], v[138:141], v[206:209], v[42:45]
	v_mfma_f32_16x16x32_bf16 v[30:33], v[130:133], v[214:217], v[30:33]
	v_mfma_f32_16x16x32_bf16 v[26:29], v[138:141], v[214:217], v[26:29]
	v_mfma_f32_16x16x32_bf16 v[14:17], v[130:133], v[222:225], v[14:17]
	v_mfma_f32_16x16x32_bf16 v[10:13], v[138:141], v[222:225], v[10:13]
	v_mfma_f32_16x16x32_bf16 v[62:65], v[134:137], v[194:197], v[62:65]
	v_mfma_f32_16x16x32_bf16 v[58:61], v[142:145], v[194:197], v[58:61]
	v_mfma_f32_16x16x32_bf16 v[46:49], v[134:137], v[210:213], v[46:49]
	v_mfma_f32_16x16x32_bf16 v[42:45], v[142:145], v[210:213], v[42:45]
	v_mfma_f32_16x16x32_bf16 v[30:33], v[134:137], v[218:221], v[30:33]
	v_mfma_f32_16x16x32_bf16 v[26:29], v[142:145], v[218:221], v[26:29]
	v_mfma_f32_16x16x32_bf16 v[14:17], v[134:137], v[226:229], v[14:17]
	v_mfma_f32_16x16x32_bf16 v[10:13], v[142:145], v[226:229], v[10:13]
	v_mfma_f32_16x16x32_bf16 v[54:57], v[146:149], v[190:193], v[54:57]
	v_mfma_f32_16x16x32_bf16 v[50:53], v[182:185], v[190:193], v[50:53]
	v_mfma_f32_16x16x32_bf16 v[38:41], v[146:149], v[206:209], v[38:41]
	v_mfma_f32_16x16x32_bf16 v[34:37], v[182:185], v[206:209], v[34:37]
	v_mfma_f32_16x16x32_bf16 v[22:25], v[146:149], v[214:217], v[22:25]
	v_mfma_f32_16x16x32_bf16 v[18:21], v[182:185], v[214:217], v[18:21]
	v_mfma_f32_16x16x32_bf16 v[6:9], v[146:149], v[222:225], v[6:9]
	v_mfma_f32_16x16x32_bf16 v[2:5], v[182:185], v[222:225], v[2:5]
	v_mfma_f32_16x16x32_bf16 v[54:57], v[150:153], v[194:197], v[54:57]
	v_mfma_f32_16x16x32_bf16 v[50:53], v[186:189], v[194:197], v[50:53]
	v_mfma_f32_16x16x32_bf16 v[38:41], v[150:153], v[210:213], v[38:41]
	v_mfma_f32_16x16x32_bf16 v[34:37], v[186:189], v[210:213], v[34:37]
	v_mfma_f32_16x16x32_bf16 v[22:25], v[150:153], v[218:221], v[22:25]
	v_mfma_f32_16x16x32_bf16 v[18:21], v[186:189], v[218:221], v[18:21]
	v_mfma_f32_16x16x32_bf16 v[6:9], v[150:153], v[226:229], v[6:9]
	v_mfma_f32_16x16x32_bf16 v[2:5], v[186:189], v[226:229], v[2:5]
	s_barrier
; #define PG8_STAGE(bufoff, gbase, voff) do { _Pragma("unroll") for (int _i = 0; _i < 2; ++_i) \
;         __builtin_amdgcn_global_load_lds((const unsigned*)((const char*)(gbase) + (voff)[_i]), (PG8_LAS unsigned*)(lds + (bufoff) + ldsw + _i * 8192), 16, 0, 0); } while (0)
; #define PG8_LDA(dst, b, h) do { _Pragma("unroll") for (int m = 0; m < 4; ++m) _Pragma("unroll") for (int k = 0; k < 2; ++k) dst[m][k] = *(const PG8_LAS bf16x8*)(lds + PG8_SA(b, h) + aoff + m * 2048 + k * 1024); } while (0)
; #define PG8_LDB(dst, b, h) do { _Pragma("unroll") for (int n = 0; n < 2; ++n) _Pragma("unroll") for (int k = 0; k < 2; ++k) dst[n][k] = *(const PG8_LAS bf16x8*)(lds + PG8_SB(b, h) + boff + n * 2048 + k * 1024); } while (0)
; #define PG8_WAIT_V(n) asm volatile("s_waitcnt vmcnt(" #n ")" ::: "memory")
; #define PG8_BAR __builtin_amdgcn_s_barrier()
; template <class Epi, class Sched, bool ALIGN_EPI = false, bool SP2 = false, bool F16 = false>
; __device__ __forceinline__ void gemm_phase(PG8_LAS unsigned char* lds, const Gemm g, const Sched& S, const Epi& E) {
;     ...
;             const char* a2 = last ? nA : cA + (size_t)(t + 2) * kstep; const char* b2 = last ? nB : cB + (size_t)(t + 2) * kstep;
;             const char* a3 = a2 + kstep; const char* b3 = b2 + kstep;
;             if (last && has_next) S.a_ready(nxt);
;             if constexpr (SP2) {
;             PG8_LDB(B0, 0, 0); PG8_LDB(B1, 0, 1); PG8_SCHED; PG8_LDA(At, 0, 0); PG8_STAGE(PG8_SA(1, 1), a1 + hstepA, voffA);
;             PG8_WAIT_V(8); PG8_WAIT_L(0); PG8_BAR; PG8_MMA(0, 0, At, B0); PG8_MMA(0, 1, At, B1); PG8_BAR; PG8_SCHED;
;             PG8_LDA(At, 0, 1); PG8_STAGE(PG8_SB(0, 0), b2, voffB); PG8_STAGE(PG8_SB(0, 1), b2 + hstepB, voffB); PG8_STAGE(PG8_SA(0, 0), a2, voffA);
;             PG8_WAIT_V(8); PG8_WAIT_L(0); PG8_BAR; PG8_MMA(1, 0, At, B0); PG8_MMA(1, 1, At, B1); PG8_BAR; PG8_SCHED;
;             PG8_LDB(B0, 1, 0); PG8_LDB(B1, 1, 1); PG8_SCHED; PG8_LDA(At, 1, 0); PG8_STAGE(PG8_SA(0, 1), a2 + hstepA, voffA);
;             PG8_WAIT_V(8); PG8_WAIT_L(0); PG8_BAR; PG8_MMA(0, 0, At, B0); PG8_MMA(0, 1, At, B1); PG8_BAR; PG8_SCHED;
;             PG8_LDA(At, 1, 1); PG8_STAGE(PG8_SB(1, 0), b3, voffB); PG8_STAGE(PG8_SB(1, 1), b3 + hstepB, voffB); PG8_STAGE(PG8_SA(1, 0), a3, voffA);
;             PG8_WAIT_V(8); PG8_WAIT_L(0); PG8_BAR; PG8_MMA(1, 0, At, B0); PG8_MMA(1, 1, At, B1); PG8_BAR; PG8_SCHED;
	s_setprio 0
	s_add_i32 s79, 0, 0x18000
	s_add_i32 s94, 0, 0x1c000
	ds_read_b128 v[130:133], v159
	ds_read_b128 v[134:137], v159 offset:1024
	ds_read_b128 v[138:141], v159 offset:2048
	ds_read_b128 v[142:145], v159 offset:3072
	ds_read_b128 v[146:149], v161
	ds_read_b128 v[150:153], v161 offset:1024
	ds_read_b128 v[182:185], v161 offset:2048
	ds_read_b128 v[186:189], v161 offset:3072
	s_add_u32 s72, s72, s8
	s_addc_u32 s73, s73, 0
	s_mov_b32 m0, s35
	ds_read_b128 v[190:193], v204 offset:32768
	ds_read_b128 v[194:197], v204 offset:33792
	ds_read_b128 v[206:209], v204 offset:34816
	ds_read_b128 v[210:213], v204 offset:35840
	ds_read_b128 v[214:217], v204 offset:36864
	ds_read_b128 v[218:221], v204 offset:37888
	ds_read_b128 v[222:225], v204 offset:38912
	ds_read_b128 v[226:229], v204 offset:39936
	global_load_lds_dwordx4 v154, s[72:73]
	s_mov_b32 m0, s2
	s_nop 0
	global_load_lds_dwordx4 v158, s[72:73]
	s_waitcnt vmcnt(8)
	s_waitcnt lgkmcnt(0)
	s_setprio 1
	s_barrier
	v_mfma_f32_16x16x32_bf16 v[122:125], v[130:133], v[190:193], v[122:125]
	v_mfma_f32_16x16x32_bf16 v[126:129], v[138:141], v[190:193], v[126:129]
	v_mfma_f32_16x16x32_bf16 v[110:113], v[130:133], v[206:209], v[110:113]
	v_mfma_f32_16x16x32_bf16 v[106:109], v[138:141], v[206:209], v[106:109]
	v_mfma_f32_16x16x32_bf16 v[94:97], v[130:133], v[214:217], v[94:97]
	v_mfma_f32_16x16x32_bf16 v[90:93], v[138:141], v[214:217], v[90:93]
	v_mfma_f32_16x16x32_bf16 v[78:81], v[130:133], v[222:225], v[78:81]
	v_mfma_f32_16x16x32_bf16 v[74:77], v[138:141], v[222:225], v[74:77]
	v_mfma_f32_16x16x32_bf16 v[122:125], v[134:137], v[194:197], v[122:125]
	v_mfma_f32_16x16x32_bf16 v[126:129], v[142:145], v[194:197], v[126:129]
	v_mfma_f32_16x16x32_bf16 v[110:113], v[134:137], v[210:213], v[110:113]
	v_mfma_f32_16x16x32_bf16 v[106:109], v[142:145], v[210:213], v[106:109]
	v_mfma_f32_16x16x32_bf16 v[94:97], v[134:137], v[218:221], v[94:97]
	v_mfma_f32_16x16x32_bf16 v[90:93], v[142:145], v[218:221], v[90:93]
	v_mfma_f32_16x16x32_bf16 v[78:81], v[134:137], v[226:229], v[78:81]
	v_mfma_f32_16x16x32_bf16 v[74:77], v[142:145], v[226:229], v[74:77]
	v_mfma_f32_16x16x32_bf16 v[118:121], v[146:149], v[190:193], v[118:121]
	v_mfma_f32_16x16x32_bf16 v[114:117], v[182:185], v[190:193], v[114:117]
	v_mfma_f32_16x16x32_bf16 v[102:105], v[146:149], v[206:209], v[102:105]
	v_mfma_f32_16x16x32_bf16 v[98:101], v[182:185], v[206:209], v[98:101]
	v_mfma_f32_16x16x32_bf16 v[86:89], v[146:149], v[214:217], v[86:89]
	v_mfma_f32_16x16x32_bf16 v[82:85], v[182:185], v[214:217], v[82:85]
	v_mfma_f32_16x16x32_bf16 v[70:73], v[146:149], v[222:225], v[70:73]
	v_mfma_f32_16x16x32_bf16 v[66:69], v[182:185], v[222:225], v[66:69]
	v_mfma_f32_16x16x32_bf16 v[118:121], v[150:153], v[194:197], v[118:121]
	v_mfma_f32_16x16x32_bf16 v[114:117], v[186:189], v[194:197], v[114:117]
	v_mfma_f32_16x16x32_bf16 v[102:105], v[150:153], v[210:213], v[102:105]
	v_mfma_f32_16x16x32_bf16 v[98:101], v[186:189], v[210:213], v[98:101]
	v_mfma_f32_16x16x32_bf16 v[86:89], v[150:153], v[218:221], v[86:89]
	v_mfma_f32_16x16x32_bf16 v[82:85], v[186:189], v[218:221], v[82:85]
	v_mfma_f32_16x16x32_bf16 v[70:73], v[150:153], v[226:229], v[70:73]
	v_mfma_f32_16x16x32_bf16 v[66:69], v[186:189], v[226:229], v[66:69]
	s_barrier
	s_setprio 0
	s_add_i32 s72, s79, s75
	s_add_i32 vcc_hi, s78, -2
	s_cmp_eq_u32 s74, vcc_hi
	s_cselect_b32 s99, s53, s24
	s_cselect_b32 s98, s52, s13
	s_add_u32 s98, s98, s92
	s_addc_u32 s99, s99, s93
	s_mov_b32 m0, s72
	s_nop 0
	global_load_lds_dwordx4 v156, s[98:99]
	ds_read_b128 v[190:193], v204 offset:49152
	ds_read_b128 v[194:197], v204 offset:50176
	ds_read_b128 v[206:209], v204 offset:51200
	ds_read_b128 v[210:213], v204 offset:52224
	ds_read_b128 v[214:217], v204 offset:53248
	ds_read_b128 v[218:221], v204 offset:54272
	ds_read_b128 v[222:225], v204 offset:55296
	ds_read_b128 v[226:229], v204 offset:56320
	s_add_i32 m0, s72, 0x2000
	s_nop 0
	global_load_lds_dwordx4 v160, s[98:99]
	s_add_i32 s72, s94, s75
	s_add_u32 s98, s98, s48
	s_addc_u32 s99, s99, 0
	s_mov_b32 m0, s72
	s_nop 0
	global_load_lds_dwordx4 v156, s[98:99]
	s_add_i32 m0, s72, 0x2000
	s_nop 0
	global_load_lds_dwordx4 v160, s[98:99]
	s_add_u32 s98, s46, 0x80
	s_addc_u32 s99, s47, 0
	s_cmp_eq_u32 s74, vcc_hi
	s_cselect_b32 s99, s55, s99
	s_cselect_b32 s98, s54, s98
	s_add_u32 s98, s98, s92
	s_addc_u32 s99, s99, s93
	s_mov_b32 m0, s22
	s_nop 0
	global_load_lds_dwordx4 v154, s[98:99]
	s_mov_b32 m0, s23
	s_nop 0
	global_load_lds_dwordx4 v158, s[98:99]
	s_waitcnt vmcnt(8)
	s_waitcnt lgkmcnt(0)
	s_setprio 1
	s_barrier
	v_mfma_f32_16x16x32_bf16 v[62:65], v[130:133], v[190:193], v[62:65]
	v_mfma_f32_16x16x32_bf16 v[58:61], v[138:141], v[190:193], v[58:61]
	v_mfma_f32_16x16x32_bf16 v[46:49], v[130:133], v[206:209], v[46:49]
	v_mfma_f32_16x16x32_bf16 v[42:45], v[138:141], v[206:209], v[42:45]
	v_mfma_f32_16x16x32_bf16 v[30:33], v[130:133], v[214:217], v[30:33]
	v_mfma_f32_16x16x32_bf16 v[26:29], v[138:141], v[214:217], v[26:29]
	v_mfma_f32_16x16x32_bf16 v[14:17], v[130:133], v[222:225], v[14:17]
	v_mfma_f32_16x16x32_bf16 v[10:13], v[138:141], v[222:225], v[10:13]
	v_mfma_f32_16x16x32_bf16 v[62:65], v[134:137], v[194:197], v[62:65]
	v_mfma_f32_16x16x32_bf16 v[58:61], v[142:145], v[194:197], v[58:61]
	v_mfma_f32_16x16x32_bf16 v[46:49], v[134:137], v[210:213], v[46:49]
	v_mfma_f32_16x16x32_bf16 v[42:45], v[142:145], v[210:213], v[42:45]
	v_mfma_f32_16x16x32_bf16 v[30:33], v[134:137], v[218:221], v[30:33]
	v_mfma_f32_16x16x32_bf16 v[26:29], v[142:145], v[218:221], v[26:29]
	v_mfma_f32_16x16x32_bf16 v[14:17], v[134:137], v[226:229], v[14:17]
	v_mfma_f32_16x16x32_bf16 v[10:13], v[142:145], v[226:229], v[10:13]
	v_mfma_f32_16x16x32_bf16 v[54:57], v[146:149], v[190:193], v[54:57]
	v_mfma_f32_16x16x32_bf16 v[50:53], v[182:185], v[190:193], v[50:53]
	v_mfma_f32_16x16x32_bf16 v[38:41], v[146:149], v[206:209], v[38:41]
	v_mfma_f32_16x16x32_bf16 v[34:37], v[182:185], v[206:209], v[34:37]
	v_mfma_f32_16x16x32_bf16 v[22:25], v[146:149], v[214:217], v[22:25]
	v_mfma_f32_16x16x32_bf16 v[18:21], v[182:185], v[214:217], v[18:21]
	v_mfma_f32_16x16x32_bf16 v[6:9], v[146:149], v[222:225], v[6:9]
	v_mfma_f32_16x16x32_bf16 v[2:5], v[182:185], v[222:225], v[2:5]
	v_mfma_f32_16x16x32_bf16 v[54:57], v[150:153], v[194:197], v[54:57]
	v_mfma_f32_16x16x32_bf16 v[50:53], v[186:189], v[194:197], v[50:53]
	v_mfma_f32_16x16x32_bf16 v[38:41], v[150:153], v[210:213], v[38:41]
	v_mfma_f32_16x16x32_bf16 v[34:37], v[186:189], v[210:213], v[34:37]
	v_mfma_f32_16x16x32_bf16 v[22:25], v[150:153], v[218:221], v[22:25]
	v_mfma_f32_16x16x32_bf16 v[18:21], v[186:189], v[218:221], v[18:21]
	v_mfma_f32_16x16x32_bf16 v[6:9], v[150:153], v[226:229], v[6:9]
	v_mfma_f32_16x16x32_bf16 v[2:5], v[186:189], v[226:229], v[2:5]
	s_barrier
	s_setprio 0
	s_add_u32 s46, s46, 0x100
	s_addc_u32 s47, s47, 0
	s_add_u32 s13, s13, 0x100
	s_addc_u32 s24, s24, 0
	s_cmp_ge_u32 s78, s65
	s_mov_b32 s72, s78
	s_cbranch_scc0 .LBB0_398

; #define PG8_STAGE(bufoff, gbase, voff) do { _Pragma("unroll") for (int _i = 0; _i < 2; ++_i) \
;         __builtin_amdgcn_global_load_lds((const unsigned*)((const char*)(gbase) + (voff)[_i]), (PG8_LAS unsigned*)(lds + (bufoff) + ldsw + _i * 8192), 16, 0, 0); } while (0)
; #define PG8_LDA(dst, b, h) do { _Pragma("unroll") for (int m = 0; m < 4; ++m) _Pragma("unroll") for (int k = 0; k < 2; ++k) dst[m][k] = *(const PG8_LAS bf16x8*)(lds + PG8_SA(b, h) + aoff + m * 2048 + k * 1024); } while (0)
; #define PG8_LDB(dst, b, h) do { _Pragma("unroll") for (int n = 0; n < 2; ++n) _Pragma("unroll") for (int k = 0; k < 2; ++k) dst[n][k] = *(const PG8_LAS bf16x8*)(lds + PG8_SB(b, h) + boff + n * 2048 + k * 1024); } while (0)
; #define PG8_WAIT_V(n) asm volatile("s_waitcnt vmcnt(" #n ")" ::: "memory")
; #define PG8_WAIT_L(n) asm volatile("s_waitcnt lgkmcnt(" #n ")" ::: "memory")
; #define PG8_BAR __builtin_amdgcn_s_barrier()
; #define PG8_SCHED __builtin_amdgcn_sched_barrier(0)
; template <class Epi, class Sched, bool ALIGN_EPI = false, bool SP2 = false, bool F16 = false>
; __device__ __forceinline__ void gemm_phase(PG8_LAS unsigned char* lds, const Gemm g, const Sched& S, const Epi& E) {
;     ...
;     for (;;) {
;         const bool has_next = S.next(ui + 1, nxt);
;         const char* nA = has_next ? (const char*)g.A + (size_t)nxt.pm * tstepA : cA; const char* nB = has_next ? (const char*)g.Bt + (size_t)nxt.pn * tstepB : cB;
;         for (int t = 0; t < nt; t += 2) {
;             const bool last = (t == nt - 2);
;             const char* a1 = cA + (size_t)(t + 1) * kstep;
;             const char* a2 = last ? nA : cA + (size_t)(t + 2) * kstep; const char* b2 = last ? nB : cB + (size_t)(t + 2) * kstep;
;             const char* a3 = a2 + kstep; const char* b3 = b2 + kstep;
;             if (last && has_next) S.a_ready(nxt);
;             if constexpr (SP2) {
;             PG8_LDB(B0, 0, 0); PG8_LDB(B1, 0, 1); PG8_SCHED; PG8_LDA(At, 0, 0); PG8_STAGE(PG8_SA(1, 1), a1 + hstepA, voffA);
;             PG8_WAIT_V(8); PG8_WAIT_L(0); PG8_BAR; PG8_MMA(0, 0, At, B0); PG8_MMA(0, 1, At, B1); PG8_BAR; PG8_SCHED;
;             PG8_LDA(At, 0, 1); PG8_STAGE(PG8_SB(0, 0), b2, voffB); PG8_STAGE(PG8_SB(0, 1), b2 + hstepB, voffB); PG8_STAGE(PG8_SA(0, 0), a2, voffA);
;             PG8_WAIT_V(8); PG8_WAIT_L(0); PG8_BAR; PG8_MMA(1, 0, At, B0); PG8_MMA(1, 1, At, B1); PG8_BAR; PG8_SCHED;
.LBB0_562:
	s_andn2_b64 vcc, exec, s[4:5]
	s_waitcnt vmcnt(0)
	s_cbranch_vccnz .Lzk_bh
	s_add_u32 s44, s72, 0x80
	s_addc_u32 s45, s73, 0
	s_add_u32 s24, s52, 0x100
	s_addc_u32 s72, s53, 0
	s_mov_b32 s52, 0
	v_add_u32_e32 v155, 0x10000, v163
	v_add_u32_e32 v157, 0x14000, v163
	v_add_u32_e32 v159, 0x18000, v163
	v_add_u32_e32 v161, 0x1c000, v163
.Lpk_bh:
	s_add_i32 s73, s52, 2
	s_add_u32 s82, s44, 0x80
	s_addc_u32 s53, s45, 0
	s_add_i32 s94, 0, 0x10000
	s_cmp_eq_u32 s74, s52
	s_cselect_b32 s53, s79, s53
	s_cselect_b32 s52, s78, s82
	s_cselect_b32 s83, s55, s72
	s_cselect_b32 s82, s54, s24
	s_add_i32 s95, 0, 0x14000
	ds_read_b128 v[130:133], v155
	ds_read_b128 v[134:137], v155 offset:1024
	ds_read_b128 v[138:141], v155 offset:2048
	ds_read_b128 v[142:145], v155 offset:3072
	ds_read_b128 v[146:149], v157
	ds_read_b128 v[150:153], v157 offset:1024
	ds_read_b128 v[182:185], v157 offset:2048
	ds_read_b128 v[186:189], v157 offset:3072
	s_add_i32 m0, s35, 0xc000
	ds_read_b128 v[190:193], v204
	ds_read_b128 v[194:197], v204 offset:1024
	ds_read_b128 v[206:209], v204 offset:2048
	ds_read_b128 v[210:213], v204 offset:3072
	ds_read_b128 v[214:217], v204 offset:4096
	ds_read_b128 v[218:221], v204 offset:5120
	ds_read_b128 v[222:225], v204 offset:6144
	ds_read_b128 v[226:229], v204 offset:7168
	global_load_lds_dwordx4 v168, s[44:45]
	s_add_i32 m0, s35, 0xe000
	s_nop 0
	global_load_lds_dwordx4 v170, s[44:45]
	s_waitcnt vmcnt(8)
	s_waitcnt lgkmcnt(0)
	s_setprio 1
	s_barrier
	v_mfma_f32_16x16x32_f16 v[122:125], v[130:133], v[190:193], 0
	v_mfma_f32_16x16x32_f16 v[126:129], v[138:141], v[190:193], 0
	v_mfma_f32_16x16x32_f16 v[110:113], v[130:133], v[206:209], 0
	v_mfma_f32_16x16x32_f16 v[106:109], v[138:141], v[206:209], 0
	v_mfma_f32_16x16x32_f16 v[94:97], v[130:133], v[214:217], 0
	v_mfma_f32_16x16x32_f16 v[90:93], v[138:141], v[214:217], 0
	v_mfma_f32_16x16x32_f16 v[78:81], v[130:133], v[222:225], 0
	v_mfma_f32_16x16x32_f16 v[74:77], v[138:141], v[222:225], 0
	v_mfma_f32_16x16x32_f16 v[122:125], v[134:137], v[194:197], v[122:125]
	v_mfma_f32_16x16x32_f16 v[126:129], v[142:145], v[194:197], v[126:129]
	v_mfma_f32_16x16x32_f16 v[110:113], v[134:137], v[210:213], v[110:113]
	v_mfma_f32_16x16x32_f16 v[106:109], v[142:145], v[210:213], v[106:109]
	v_mfma_f32_16x16x32_f16 v[94:97], v[134:137], v[218:221], v[94:97]
	v_mfma_f32_16x16x32_f16 v[90:93], v[142:145], v[218:221], v[90:93]
	v_mfma_f32_16x16x32_f16 v[78:81], v[134:137], v[226:229], v[78:81]
	v_mfma_f32_16x16x32_f16 v[74:77], v[142:145], v[226:229], v[74:77]
	v_mfma_f32_16x16x32_f16 v[118:121], v[146:149], v[190:193], 0
	v_mfma_f32_16x16x32_f16 v[114:117], v[182:185], v[190:193], 0
	v_mfma_f32_16x16x32_f16 v[102:105], v[146:149], v[206:209], 0
	v_mfma_f32_16x16x32_f16 v[98:101], v[182:185], v[206:209], 0
	v_mfma_f32_16x16x32_f16 v[86:89], v[146:149], v[214:217], 0
	v_mfma_f32_16x16x32_f16 v[82:85], v[182:185], v[214:217], 0
	v_mfma_f32_16x16x32_f16 v[70:73], v[146:149], v[222:225], 0
	v_mfma_f32_16x16x32_f16 v[66:69], v[182:185], v[222:225], 0
	v_mfma_f32_16x16x32_f16 v[118:121], v[150:153], v[194:197], v[118:121]
	v_mfma_f32_16x16x32_f16 v[114:117], v[186:189], v[194:197], v[114:117]
	v_mfma_f32_16x16x32_f16 v[102:105], v[150:153], v[210:213], v[102:105]
	v_mfma_f32_16x16x32_f16 v[98:101], v[186:189], v[210:213], v[98:101]
	v_mfma_f32_16x16x32_f16 v[86:89], v[150:153], v[218:221], v[86:89]
	v_mfma_f32_16x16x32_f16 v[82:85], v[186:189], v[218:221], v[82:85]
	v_mfma_f32_16x16x32_f16 v[70:73], v[150:153], v[226:229], v[70:73]
	v_mfma_f32_16x16x32_f16 v[66:69], v[186:189], v[226:229], v[66:69]
	s_barrier
	s_setprio 0
	s_add_i32 s94, s94, s75
	s_mov_b32 m0, s94
	s_nop 0
	global_load_lds_dwordx4 v156, s[82:83]
	ds_read_b128 v[190:193], v204 offset:16384
	ds_read_b128 v[194:197], v204 offset:17408
	ds_read_b128 v[206:209], v204 offset:18432
	ds_read_b128 v[210:213], v204 offset:19456
	ds_read_b128 v[214:217], v204 offset:20480
	ds_read_b128 v[218:221], v204 offset:21504
	ds_read_b128 v[222:225], v204 offset:22528
	ds_read_b128 v[226:229], v204 offset:23552
	s_add_i32 m0, s94, 0x2000
	s_nop 0
	global_load_lds_dwordx4 v160, s[82:83]
	s_add_i32 s94, s95, s75
	s_add_u32 s82, s82, s48
	s_addc_u32 s83, s83, 0
	s_mov_b32 m0, s94
	s_nop 0
	global_load_lds_dwordx4 v156, s[82:83]
	s_add_i32 m0, s94, 0x2000
	s_nop 0
	global_load_lds_dwordx4 v160, s[82:83]
	s_mov_b32 m0, s35
	s_nop 0
	global_load_lds_dwordx4 v154, s[52:53]
	s_mov_b32 m0, s2
	s_nop 0
	global_load_lds_dwordx4 v158, s[52:53]
	s_waitcnt vmcnt(8)
	s_waitcnt lgkmcnt(0)
	s_setprio 1
	s_barrier
	v_mfma_f32_16x16x32_f16 v[62:65], v[130:133], v[190:193], 0
	v_mfma_f32_16x16x32_f16 v[58:61], v[138:141], v[190:193], 0
	v_mfma_f32_16x16x32_f16 v[46:49], v[130:133], v[206:209], 0
	v_mfma_f32_16x16x32_f16 v[42:45], v[138:141], v[206:209], 0
	v_mfma_f32_16x16x32_f16 v[30:33], v[130:133], v[214:217], 0
	v_mfma_f32_16x16x32_f16 v[26:29], v[138:141], v[214:217], 0
	v_mfma_f32_16x16x32_f16 v[14:17], v[130:133], v[222:225], 0
	v_mfma_f32_16x16x32_f16 v[10:13], v[138:141], v[222:225], 0
	v_mfma_f32_16x16x32_f16 v[62:65], v[134:137], v[194:197], v[62:65]
	v_mfma_f32_16x16x32_f16 v[58:61], v[142:145], v[194:197], v[58:61]
	v_mfma_f32_16x16x32_f16 v[46:49], v[134:137], v[210:213], v[46:49]
	v_mfma_f32_16x16x32_f16 v[42:45], v[142:145], v[210:213], v[42:45]
	v_mfma_f32_16x16x32_f16 v[30:33], v[134:137], v[218:221], v[30:33]
	v_mfma_f32_16x16x32_f16 v[26:29], v[142:145], v[218:221], v[26:29]
	v_mfma_f32_16x16x32_f16 v[14:17], v[134:137], v[226:229], v[14:17]
	v_mfma_f32_16x16x32_f16 v[10:13], v[142:145], v[226:229], v[10:13]
	v_mfma_f32_16x16x32_f16 v[54:57], v[146:149], v[190:193], 0
	v_mfma_f32_16x16x32_f16 v[50:53], v[182:185], v[190:193], 0
	v_mfma_f32_16x16x32_f16 v[38:41], v[146:149], v[206:209], 0
	v_mfma_f32_16x16x32_f16 v[34:37], v[182:185], v[206:209], 0
	v_mfma_f32_16x16x32_f16 v[22:25], v[146:149], v[214:217], 0
	v_mfma_f32_16x16x32_f16 v[18:21], v[182:185], v[214:217], 0
	v_mfma_f32_16x16x32_f16 v[6:9], v[146:149], v[222:225], 0
	v_mfma_f32_16x16x32_f16 v[2:5], v[182:185], v[222:225], 0
	v_mfma_f32_16x16x32_f16 v[54:57], v[150:153], v[194:197], v[54:57]
	v_mfma_f32_16x16x32_f16 v[50:53], v[186:189], v[194:197], v[50:53]
	v_mfma_f32_16x16x32_f16 v[38:41], v[150:153], v[210:213], v[38:41]
	v_mfma_f32_16x16x32_f16 v[34:37], v[186:189], v[210:213], v[34:37]
	v_mfma_f32_16x16x32_f16 v[22:25], v[150:153], v[218:221], v[22:25]
	v_mfma_f32_16x16x32_f16 v[18:21], v[186:189], v[218:221], v[18:21]
	v_mfma_f32_16x16x32_f16 v[6:9], v[150:153], v[226:229], v[6:9]
	v_mfma_f32_16x16x32_f16 v[2:5], v[186:189], v[226:229], v[2:5]
	s_barrier
; #define PG8_STAGE(bufoff, gbase, voff) do { _Pragma("unroll") for (int _i = 0; _i < 2; ++_i) \
;         __builtin_amdgcn_global_load_lds((const unsigned*)((const char*)(gbase) + (voff)[_i]), (PG8_LAS unsigned*)(lds + (bufoff) + ldsw + _i * 8192), 16, 0, 0); } while (0)
; #define PG8_LDA(dst, b, h) do { _Pragma("unroll") for (int m = 0; m < 4; ++m) _Pragma("unroll") for (int k = 0; k < 2; ++k) dst[m][k] = *(const PG8_LAS bf16x8*)(lds + PG8_SA(b, h) + aoff + m * 2048 + k * 1024); } while (0)
; #define PG8_LDB(dst, b, h) do { _Pragma("unroll") for (int n = 0; n < 2; ++n) _Pragma("unroll") for (int k = 0; k < 2; ++k) dst[n][k] = *(const PG8_LAS bf16x8*)(lds + PG8_SB(b, h) + boff + n * 2048 + k * 1024); } while (0)
; #define PG8_WAIT_V(n) asm volatile("s_waitcnt vmcnt(" #n ")" ::: "memory")
; #define PG8_BAR __builtin_amdgcn_s_barrier()
; template <class Epi, class Sched, bool ALIGN_EPI = false, bool SP2 = false, bool F16 = false>
; __device__ __forceinline__ void gemm_phase(PG8_LAS unsigned char* lds, const Gemm g, const Sched& S, const Epi& E) {
;     ...
;             const char* a2 = last ? nA : cA + (size_t)(t + 2) * kstep; const char* b2 = last ? nB : cB + (size_t)(t + 2) * kstep;
;             const char* a3 = a2 + kstep; const char* b3 = b2 + kstep;
;             if (last && has_next) S.a_ready(nxt);
;             if constexpr (SP2) {
;             PG8_LDB(B0, 0, 0); PG8_LDB(B1, 0, 1); PG8_SCHED; PG8_LDA(At, 0, 0); PG8_STAGE(PG8_SA(1, 1), a1 + hstepA, voffA);
;             PG8_WAIT_V(8); PG8_WAIT_L(0); PG8_BAR; PG8_MMA(0, 0, At, B0); PG8_MMA(0, 1, At, B1); PG8_BAR; PG8_SCHED;
;             PG8_LDA(At, 0, 1); PG8_STAGE(PG8_SB(0, 0), b2, voffB); PG8_STAGE(PG8_SB(0, 1), b2 + hstepB, voffB); PG8_STAGE(PG8_SA(0, 0), a2, voffA);
;             PG8_WAIT_V(8); PG8_WAIT_L(0); PG8_BAR; PG8_MMA(1, 0, At, B0); PG8_MMA(1, 1, At, B1); PG8_BAR; PG8_SCHED;
;             PG8_LDB(B0, 1, 0); PG8_LDB(B1, 1, 1); PG8_SCHED; PG8_LDA(At, 1, 0); PG8_STAGE(PG8_SA(0, 1), a2 + hstepA, voffA);
;             PG8_WAIT_V(8); PG8_WAIT_L(0); PG8_BAR; PG8_MMA(0, 0, At, B0); PG8_MMA(0, 1, At, B1); PG8_BAR; PG8_SCHED;
;             PG8_LDA(At, 1, 1); PG8_STAGE(PG8_SB(1, 0), b3, voffB); PG8_STAGE(PG8_SB(1, 1), b3 + hstepB, voffB); PG8_STAGE(PG8_SA(1, 0), a3, voffA);
;             PG8_WAIT_V(8); PG8_WAIT_L(0); PG8_BAR; PG8_MMA(1, 0, At, B0); PG8_MMA(1, 1, At, B1); PG8_BAR; PG8_SCHED;
	s_setprio 0
	s_add_i32 s82, 0, 0x18000
	s_add_i32 s83, 0, 0x1c000
	ds_read_b128 v[130:133], v159
	ds_read_b128 v[134:137], v159 offset:1024
	ds_read_b128 v[138:141], v159 offset:2048
	ds_read_b128 v[142:145], v159 offset:3072
	ds_read_b128 v[146:149], v161
	ds_read_b128 v[150:153], v161 offset:1024
	ds_read_b128 v[182:185], v161 offset:2048
	ds_read_b128 v[186:189], v161 offset:3072
	s_add_u32 s52, s52, s8
	s_addc_u32 s53, s53, 0
	s_mov_b32 m0, s22
	ds_read_b128 v[190:193], v204 offset:32768
	ds_read_b128 v[194:197], v204 offset:33792
	ds_read_b128 v[206:209], v204 offset:34816
	ds_read_b128 v[210:213], v204 offset:35840
	ds_read_b128 v[214:217], v204 offset:36864
	ds_read_b128 v[218:221], v204 offset:37888
	ds_read_b128 v[222:225], v204 offset:38912
	ds_read_b128 v[226:229], v204 offset:39936
	global_load_lds_dwordx4 v154, s[52:53]
	s_mov_b32 m0, s23
	s_nop 0
	global_load_lds_dwordx4 v158, s[52:53]
	s_waitcnt vmcnt(8)
	s_waitcnt lgkmcnt(0)
	s_setprio 1
	s_barrier
	v_mfma_f32_16x16x32_f16 v[122:125], v[130:133], v[190:193], v[122:125]
	v_mfma_f32_16x16x32_f16 v[126:129], v[138:141], v[190:193], v[126:129]
	v_mfma_f32_16x16x32_f16 v[110:113], v[130:133], v[206:209], v[110:113]
	v_mfma_f32_16x16x32_f16 v[106:109], v[138:141], v[206:209], v[106:109]
	v_mfma_f32_16x16x32_f16 v[94:97], v[130:133], v[214:217], v[94:97]
	v_mfma_f32_16x16x32_f16 v[90:93], v[138:141], v[214:217], v[90:93]
	v_mfma_f32_16x16x32_f16 v[78:81], v[130:133], v[222:225], v[78:81]
	v_mfma_f32_16x16x32_f16 v[74:77], v[138:141], v[222:225], v[74:77]
	v_mfma_f32_16x16x32_f16 v[122:125], v[134:137], v[194:197], v[122:125]
	v_mfma_f32_16x16x32_f16 v[126:129], v[142:145], v[194:197], v[126:129]
	v_mfma_f32_16x16x32_f16 v[110:113], v[134:137], v[210:213], v[110:113]
	v_mfma_f32_16x16x32_f16 v[106:109], v[142:145], v[210:213], v[106:109]
	v_mfma_f32_16x16x32_f16 v[94:97], v[134:137], v[218:221], v[94:97]
	v_mfma_f32_16x16x32_f16 v[90:93], v[142:145], v[218:221], v[90:93]
	v_mfma_f32_16x16x32_f16 v[78:81], v[134:137], v[226:229], v[78:81]
	v_mfma_f32_16x16x32_f16 v[74:77], v[142:145], v[226:229], v[74:77]
	v_mfma_f32_16x16x32_f16 v[118:121], v[146:149], v[190:193], v[118:121]
	v_mfma_f32_16x16x32_f16 v[114:117], v[182:185], v[190:193], v[114:117]
	v_mfma_f32_16x16x32_f16 v[102:105], v[146:149], v[206:209], v[102:105]
	v_mfma_f32_16x16x32_f16 v[98:101], v[182:185], v[206:209], v[98:101]
	v_mfma_f32_16x16x32_f16 v[86:89], v[146:149], v[214:217], v[86:89]
	v_mfma_f32_16x16x32_f16 v[82:85], v[182:185], v[214:217], v[82:85]
	v_mfma_f32_16x16x32_f16 v[70:73], v[146:149], v[222:225], v[70:73]
	v_mfma_f32_16x16x32_f16 v[66:69], v[182:185], v[222:225], v[66:69]
	v_mfma_f32_16x16x32_f16 v[118:121], v[150:153], v[194:197], v[118:121]
	v_mfma_f32_16x16x32_f16 v[114:117], v[186:189], v[194:197], v[114:117]
	v_mfma_f32_16x16x32_f16 v[102:105], v[150:153], v[210:213], v[102:105]
	v_mfma_f32_16x16x32_f16 v[98:101], v[186:189], v[210:213], v[98:101]
	v_mfma_f32_16x16x32_f16 v[86:89], v[150:153], v[218:221], v[86:89]
	v_mfma_f32_16x16x32_f16 v[82:85], v[186:189], v[218:221], v[82:85]
	v_mfma_f32_16x16x32_f16 v[70:73], v[150:153], v[226:229], v[70:73]
	v_mfma_f32_16x16x32_f16 v[66:69], v[186:189], v[226:229], v[66:69]
	s_barrier
	s_setprio 0
	s_add_i32 s52, s82, s75
	s_add_i32 vcc_hi, s73, -2
	s_cmp_eq_u32 s74, vcc_hi
	s_cselect_b32 s99, s55, s72
	s_cselect_b32 s98, s54, s24
	s_add_u32 s98, s98, s92
	s_addc_u32 s99, s99, s93
	s_mov_b32 m0, s52
	s_nop 0
	global_load_lds_dwordx4 v156, s[98:99]
	ds_read_b128 v[190:193], v204 offset:49152
	ds_read_b128 v[194:197], v204 offset:50176
	ds_read_b128 v[206:209], v204 offset:51200
	ds_read_b128 v[210:213], v204 offset:52224
	ds_read_b128 v[214:217], v204 offset:53248
	ds_read_b128 v[218:221], v204 offset:54272
	ds_read_b128 v[222:225], v204 offset:55296
	ds_read_b128 v[226:229], v204 offset:56320
	s_add_i32 m0, s52, 0x2000
	s_nop 0
	global_load_lds_dwordx4 v160, s[98:99]
	s_add_i32 s52, s83, s75
	s_add_u32 s98, s98, s48
	s_addc_u32 s99, s99, 0
	s_mov_b32 m0, s52
	s_nop 0
	global_load_lds_dwordx4 v156, s[98:99]
	s_add_i32 m0, s52, 0x2000
	s_nop 0
	global_load_lds_dwordx4 v160, s[98:99]
	s_add_u32 s98, s44, 0x80
	s_addc_u32 s99, s45, 0
	s_cmp_eq_u32 s74, vcc_hi
	s_cselect_b32 s99, s79, s99
	s_cselect_b32 s98, s78, s98
	s_add_u32 s98, s98, s92
	s_addc_u32 s99, s99, s93
	s_mov_b32 m0, s61
	s_nop 0
	global_load_lds_dwordx4 v154, s[98:99]
	s_mov_b32 m0, s18
	s_nop 0
	global_load_lds_dwordx4 v158, s[98:99]
	s_waitcnt vmcnt(8)
	s_waitcnt lgkmcnt(0)
	s_setprio 1
	s_barrier
	v_mfma_f32_16x16x32_f16 v[62:65], v[130:133], v[190:193], v[62:65]
	v_mfma_f32_16x16x32_f16 v[58:61], v[138:141], v[190:193], v[58:61]
	v_mfma_f32_16x16x32_f16 v[46:49], v[130:133], v[206:209], v[46:49]
	v_mfma_f32_16x16x32_f16 v[42:45], v[138:141], v[206:209], v[42:45]
	v_mfma_f32_16x16x32_f16 v[30:33], v[130:133], v[214:217], v[30:33]
	v_mfma_f32_16x16x32_f16 v[26:29], v[138:141], v[214:217], v[26:29]
	v_mfma_f32_16x16x32_f16 v[14:17], v[130:133], v[222:225], v[14:17]
	v_mfma_f32_16x16x32_f16 v[10:13], v[138:141], v[222:225], v[10:13]
	v_mfma_f32_16x16x32_f16 v[62:65], v[134:137], v[194:197], v[62:65]
	v_mfma_f32_16x16x32_f16 v[58:61], v[142:145], v[194:197], v[58:61]
	v_mfma_f32_16x16x32_f16 v[46:49], v[134:137], v[210:213], v[46:49]
	v_mfma_f32_16x16x32_f16 v[42:45], v[142:145], v[210:213], v[42:45]
	v_mfma_f32_16x16x32_f16 v[30:33], v[134:137], v[218:221], v[30:33]
	v_mfma_f32_16x16x32_f16 v[26:29], v[142:145], v[218:221], v[26:29]
	v_mfma_f32_16x16x32_f16 v[14:17], v[134:137], v[226:229], v[14:17]
	v_mfma_f32_16x16x32_f16 v[10:13], v[142:145], v[226:229], v[10:13]
	v_mfma_f32_16x16x32_f16 v[54:57], v[146:149], v[190:193], v[54:57]
	v_mfma_f32_16x16x32_f16 v[50:53], v[182:185], v[190:193], v[50:53]
	v_mfma_f32_16x16x32_f16 v[38:41], v[146:149], v[206:209], v[38:41]
	v_mfma_f32_16x16x32_f16 v[34:37], v[182:185], v[206:209], v[34:37]
	v_mfma_f32_16x16x32_f16 v[22:25], v[146:149], v[214:217], v[22:25]
	v_mfma_f32_16x16x32_f16 v[18:21], v[182:185], v[214:217], v[18:21]
	v_mfma_f32_16x16x32_f16 v[6:9], v[146:149], v[222:225], v[6:9]
	v_mfma_f32_16x16x32_f16 v[2:5], v[182:185], v[222:225], v[2:5]
	v_mfma_f32_16x16x32_f16 v[54:57], v[150:153], v[194:197], v[54:57]
	v_mfma_f32_16x16x32_f16 v[50:53], v[186:189], v[194:197], v[50:53]
	v_mfma_f32_16x16x32_f16 v[38:41], v[150:153], v[210:213], v[38:41]
	v_mfma_f32_16x16x32_f16 v[34:37], v[186:189], v[210:213], v[34:37]
	v_mfma_f32_16x16x32_f16 v[22:25], v[150:153], v[218:221], v[22:25]
	v_mfma_f32_16x16x32_f16 v[18:21], v[186:189], v[218:221], v[18:21]
	v_mfma_f32_16x16x32_f16 v[6:9], v[150:153], v[226:229], v[6:9]
	v_mfma_f32_16x16x32_f16 v[2:5], v[186:189], v[226:229], v[2:5]
	s_barrier
	s_setprio 0
	s_add_u32 s44, s44, 0x100
	s_addc_u32 s45, s45, 0
	s_add_u32 s24, s24, 0x100
	s_addc_u32 s72, s72, 0
	s_cmp_ge_u32 s73, s65
	s_mov_b32 s52, s73
	s_cbranch_scc1 .LBB0_565
; #define PG8_STAGE(bufoff, gbase, voff) do { _Pragma("unroll") for (int _i = 0; _i < 2; ++_i) \
;         __builtin_amdgcn_global_load_lds((const unsigned*)((const char*)(gbase) + (voff)[_i]), (PG8_LAS unsigned*)(lds + (bufoff) + ldsw + _i * 8192), 16, 0, 0); } while (0)
; #define PG8_LDA(dst, b, h) do { _Pragma("unroll") for (int m = 0; m < 4; ++m) _Pragma("unroll") for (int k = 0; k < 2; ++k) dst[m][k] = *(const PG8_LAS bf16x8*)(lds + PG8_SA(b, h) + aoff + m * 2048 + k * 1024); } while (0)
; #define PG8_LDB(dst, b, h) do { _Pragma("unroll") for (int n = 0; n < 2; ++n) _Pragma("unroll") for (int k = 0; k < 2; ++k) dst[n][k] = *(const PG8_LAS bf16x8*)(lds + PG8_SB(b, h) + boff + n * 2048 + k * 1024); } while (0)
; #define PG8_WAIT_V(n) asm volatile("s_waitcnt vmcnt(" #n ")" ::: "memory")
; #define PG8_WAIT_L(n) asm volatile("s_waitcnt lgkmcnt(" #n ")" ::: "memory")
; #define PG8_BAR __builtin_amdgcn_s_barrier()
; #define PG8_SCHED __builtin_amdgcn_sched_barrier(0)
; template <class Epi, class Sched, bool ALIGN_EPI = false, bool SP2 = false, bool F16 = false>
; __device__ __forceinline__ void gemm_phase(PG8_LAS unsigned char* lds, const Gemm g, const Sched& S, const Epi& E) {
;     ...
;         for (int t = 0; t < nt; t += 2) {
;             const bool last = (t == nt - 2);
;             const char* a1 = cA + (size_t)(t + 1) * kstep;
;             const char* a2 = last ? nA : cA + (size_t)(t + 2) * kstep; const char* b2 = last ? nB : cB + (size_t)(t + 2) * kstep;
;             const char* a3 = a2 + kstep; const char* b3 = b2 + kstep;
;             if (last && has_next) S.a_ready(nxt);
;             if constexpr (SP2) {
;             PG8_LDB(B0, 0, 0); PG8_LDB(B1, 0, 1); PG8_SCHED; PG8_LDA(At, 0, 0); PG8_STAGE(PG8_SA(1, 1), a1 + hstepA, voffA);
;             PG8_WAIT_V(8); PG8_WAIT_L(0); PG8_BAR; PG8_MMA(0, 0, At, B0); PG8_MMA(0, 1, At, B1); PG8_BAR; PG8_SCHED;
;             PG8_LDA(At, 0, 1); PG8_STAGE(PG8_SB(0, 0), b2, voffB); PG8_STAGE(PG8_SB(0, 1), b2 + hstepB, voffB); PG8_STAGE(PG8_SA(0, 0), a2, voffA);
;             PG8_WAIT_V(8); PG8_WAIT_L(0); PG8_BAR; PG8_MMA(1, 0, At, B0); PG8_MMA(1, 1, At, B1); PG8_BAR; PG8_SCHED;
.LBB0_564:
	s_add_i32 s73, s52, 2
	s_add_u32 s82, s44, 0x80
	s_addc_u32 s53, s45, 0
	s_add_i32 s94, 0, 0x10000
	s_cmp_eq_u32 s74, s52
	s_cselect_b32 s53, s79, s53
	s_cselect_b32 s52, s78, s82
	s_cselect_b32 s83, s55, s72
	s_cselect_b32 s82, s54, s24
	s_add_i32 s95, 0, 0x14000
	ds_read_b128 v[130:133], v155
	ds_read_b128 v[134:137], v155 offset:1024
	ds_read_b128 v[138:141], v155 offset:2048
	ds_read_b128 v[142:145], v155 offset:3072
	ds_read_b128 v[146:149], v157
	ds_read_b128 v[150:153], v157 offset:1024
	ds_read_b128 v[182:185], v157 offset:2048
	ds_read_b128 v[186:189], v157 offset:3072
	s_add_i32 m0, s35, 0xc000
	ds_read_b128 v[190:193], v204
	ds_read_b128 v[194:197], v204 offset:1024
	ds_read_b128 v[206:209], v204 offset:2048
	ds_read_b128 v[210:213], v204 offset:3072
	ds_read_b128 v[214:217], v204 offset:4096
	ds_read_b128 v[218:221], v204 offset:5120
	ds_read_b128 v[222:225], v204 offset:6144
	ds_read_b128 v[226:229], v204 offset:7168
	global_load_lds_dwordx4 v168, s[44:45]
	s_add_i32 m0, s35, 0xe000
	s_nop 0
	global_load_lds_dwordx4 v170, s[44:45]
	s_waitcnt vmcnt(8)
	s_waitcnt lgkmcnt(0)
	s_setprio 1
	s_barrier
	v_mfma_f32_16x16x32_f16 v[122:125], v[130:133], v[190:193], v[122:125]
	v_mfma_f32_16x16x32_f16 v[126:129], v[138:141], v[190:193], v[126:129]
	v_mfma_f32_16x16x32_f16 v[110:113], v[130:133], v[206:209], v[110:113]
	v_mfma_f32_16x16x32_f16 v[106:109], v[138:141], v[206:209], v[106:109]
	v_mfma_f32_16x16x32_f16 v[94:97], v[130:133], v[214:217], v[94:97]
	v_mfma_f32_16x16x32_f16 v[90:93], v[138:141], v[214:217], v[90:93]
	v_mfma_f32_16x16x32_f16 v[78:81], v[130:133], v[222:225], v[78:81]
	v_mfma_f32_16x16x32_f16 v[74:77], v[138:141], v[222:225], v[74:77]
	v_mfma_f32_16x16x32_f16 v[122:125], v[134:137], v[194:197], v[122:125]
	v_mfma_f32_16x16x32_f16 v[126:129], v[142:145], v[194:197], v[126:129]
	v_mfma_f32_16x16x32_f16 v[110:113], v[134:137], v[210:213], v[110:113]
	v_mfma_f32_16x16x32_f16 v[106:109], v[142:145], v[210:213], v[106:109]
	v_mfma_f32_16x16x32_f16 v[94:97], v[134:137], v[218:221], v[94:97]
	v_mfma_f32_16x16x32_f16 v[90:93], v[142:145], v[218:221], v[90:93]
	v_mfma_f32_16x16x32_f16 v[78:81], v[134:137], v[226:229], v[78:81]
	v_mfma_f32_16x16x32_f16 v[74:77], v[142:145], v[226:229], v[74:77]
	v_mfma_f32_16x16x32_f16 v[118:121], v[146:149], v[190:193], v[118:121]
	v_mfma_f32_16x16x32_f16 v[114:117], v[182:185], v[190:193], v[114:117]
	v_mfma_f32_16x16x32_f16 v[102:105], v[146:149], v[206:209], v[102:105]
	v_mfma_f32_16x16x32_f16 v[98:101], v[182:185], v[206:209], v[98:101]
	v_mfma_f32_16x16x32_f16 v[86:89], v[146:149], v[214:217], v[86:89]
	v_mfma_f32_16x16x32_f16 v[82:85], v[182:185], v[214:217], v[82:85]
	v_mfma_f32_16x16x32_f16 v[70:73], v[146:149], v[222:225], v[70:73]
	v_mfma_f32_16x16x32_f16 v[66:69], v[182:185], v[222:225], v[66:69]
	v_mfma_f32_16x16x32_f16 v[118:121], v[150:153], v[194:197], v[118:121]
	v_mfma_f32_16x16x32_f16 v[114:117], v[186:189], v[194:197], v[114:117]
	v_mfma_f32_16x16x32_f16 v[102:105], v[150:153], v[210:213], v[102:105]
	v_mfma_f32_16x16x32_f16 v[98:101], v[186:189], v[210:213], v[98:101]
	v_mfma_f32_16x16x32_f16 v[86:89], v[150:153], v[218:221], v[86:89]
	v_mfma_f32_16x16x32_f16 v[82:85], v[186:189], v[218:221], v[82:85]
	v_mfma_f32_16x16x32_f16 v[70:73], v[150:153], v[226:229], v[70:73]
	v_mfma_f32_16x16x32_f16 v[66:69], v[186:189], v[226:229], v[66:69]
	s_barrier
	s_setprio 0
	s_add_i32 s94, s94, s75
	s_mov_b32 m0, s94
	s_nop 0
	global_load_lds_dwordx4 v156, s[82:83]
	ds_read_b128 v[190:193], v204 offset:16384
	ds_read_b128 v[194:197], v204 offset:17408
	ds_read_b128 v[206:209], v204 offset:18432
	ds_read_b128 v[210:213], v204 offset:19456
	ds_read_b128 v[214:217], v204 offset:20480
	ds_read_b128 v[218:221], v204 offset:21504
	ds_read_b128 v[222:225], v204 offset:22528
	ds_read_b128 v[226:229], v204 offset:23552
	s_add_i32 m0, s94, 0x2000
	s_nop 0
	global_load_lds_dwordx4 v160, s[82:83]
	s_add_i32 s94, s95, s75
	s_add_u32 s82, s82, s48
	s_addc_u32 s83, s83, 0
	s_mov_b32 m0, s94
	s_nop 0
	global_load_lds_dwordx4 v156, s[82:83]
	s_add_i32 m0, s94, 0x2000
	s_nop 0
	global_load_lds_dwordx4 v160, s[82:83]
	s_mov_b32 m0, s35
	s_nop 0
	global_load_lds_dwordx4 v154, s[52:53]
	s_mov_b32 m0, s2
	s_nop 0
	global_load_lds_dwordx4 v158, s[52:53]
	s_waitcnt vmcnt(8)
	s_waitcnt lgkmcnt(0)
	s_setprio 1
	s_barrier
	v_mfma_f32_16x16x32_f16 v[62:65], v[130:133], v[190:193], v[62:65]
	v_mfma_f32_16x16x32_f16 v[58:61], v[138:141], v[190:193], v[58:61]
	v_mfma_f32_16x16x32_f16 v[46:49], v[130:133], v[206:209], v[46:49]
	v_mfma_f32_16x16x32_f16 v[42:45], v[138:141], v[206:209], v[42:45]
	v_mfma_f32_16x16x32_f16 v[30:33], v[130:133], v[214:217], v[30:33]
	v_mfma_f32_16x16x32_f16 v[26:29], v[138:141], v[214:217], v[26:29]
	v_mfma_f32_16x16x32_f16 v[14:17], v[130:133], v[222:225], v[14:17]
	v_mfma_f32_16x16x32_f16 v[10:13], v[138:141], v[222:225], v[10:13]
	v_mfma_f32_16x16x32_f16 v[62:65], v[134:137], v[194:197], v[62:65]
	v_mfma_f32_16x16x32_f16 v[58:61], v[142:145], v[194:197], v[58:61]
	v_mfma_f32_16x16x32_f16 v[46:49], v[134:137], v[210:213], v[46:49]
	v_mfma_f32_16x16x32_f16 v[42:45], v[142:145], v[210:213], v[42:45]
	v_mfma_f32_16x16x32_f16 v[30:33], v[134:137], v[218:221], v[30:33]
	v_mfma_f32_16x16x32_f16 v[26:29], v[142:145], v[218:221], v[26:29]
	v_mfma_f32_16x16x32_f16 v[14:17], v[134:137], v[226:229], v[14:17]
	v_mfma_f32_16x16x32_f16 v[10:13], v[142:145], v[226:229], v[10:13]
	v_mfma_f32_16x16x32_f16 v[54:57], v[146:149], v[190:193], v[54:57]
	v_mfma_f32_16x16x32_f16 v[50:53], v[182:185], v[190:193], v[50:53]
	v_mfma_f32_16x16x32_f16 v[38:41], v[146:149], v[206:209], v[38:41]
	v_mfma_f32_16x16x32_f16 v[34:37], v[182:185], v[206:209], v[34:37]
	v_mfma_f32_16x16x32_f16 v[22:25], v[146:149], v[214:217], v[22:25]
	v_mfma_f32_16x16x32_f16 v[18:21], v[182:185], v[214:217], v[18:21]
	v_mfma_f32_16x16x32_f16 v[6:9], v[146:149], v[222:225], v[6:9]
	v_mfma_f32_16x16x32_f16 v[2:5], v[182:185], v[222:225], v[2:5]
	v_mfma_f32_16x16x32_f16 v[54:57], v[150:153], v[194:197], v[54:57]
	v_mfma_f32_16x16x32_f16 v[50:53], v[186:189], v[194:197], v[50:53]
	v_mfma_f32_16x16x32_f16 v[38:41], v[150:153], v[210:213], v[38:41]
	v_mfma_f32_16x16x32_f16 v[34:37], v[186:189], v[210:213], v[34:37]
	v_mfma_f32_16x16x32_f16 v[22:25], v[150:153], v[218:221], v[22:25]
	v_mfma_f32_16x16x32_f16 v[18:21], v[186:189], v[218:221], v[18:21]
	v_mfma_f32_16x16x32_f16 v[6:9], v[150:153], v[226:229], v[6:9]
	v_mfma_f32_16x16x32_f16 v[2:5], v[186:189], v[226:229], v[2:5]
	s_barrier
; #define PG8_STAGE(bufoff, gbase, voff) do { _Pragma("unroll") for (int _i = 0; _i < 2; ++_i) \
;         __builtin_amdgcn_global_load_lds((const unsigned*)((const char*)(gbase) + (voff)[_i]), (PG8_LAS unsigned*)(lds + (bufoff) + ldsw + _i * 8192), 16, 0, 0); } while (0)
; #define PG8_LDA(dst, b, h) do { _Pragma("unroll") for (int m = 0; m < 4; ++m) _Pragma("unroll") for (int k = 0; k < 2; ++k) dst[m][k] = *(const PG8_LAS bf16x8*)(lds + PG8_SA(b, h) + aoff + m * 2048 + k * 1024); } while (0)
; #define PG8_LDB(dst, b, h) do { _Pragma("unroll") for (int n = 0; n < 2; ++n) _Pragma("unroll") for (int k = 0; k < 2; ++k) dst[n][k] = *(const PG8_LAS bf16x8*)(lds + PG8_SB(b, h) + boff + n * 2048 + k * 1024); } while (0)
; #define PG8_WAIT_V(n) asm volatile("s_waitcnt vmcnt(" #n ")" ::: "memory")
; #define PG8_BAR __builtin_amdgcn_s_barrier()
; template <class Epi, class Sched, bool ALIGN_EPI = false, bool SP2 = false, bool F16 = false>
; __device__ __forceinline__ void gemm_phase(PG8_LAS unsigned char* lds, const Gemm g, const Sched& S, const Epi& E) {
;     ...
;             const char* a2 = last ? nA : cA + (size_t)(t + 2) * kstep; const char* b2 = last ? nB : cB + (size_t)(t + 2) * kstep;
;             const char* a3 = a2 + kstep; const char* b3 = b2 + kstep;
;             if (last && has_next) S.a_ready(nxt);
;             if constexpr (SP2) {
;             PG8_LDB(B0, 0, 0); PG8_LDB(B1, 0, 1); PG8_SCHED; PG8_LDA(At, 0, 0); PG8_STAGE(PG8_SA(1, 1), a1 + hstepA, voffA);
;             PG8_WAIT_V(8); PG8_WAIT_L(0); PG8_BAR; PG8_MMA(0, 0, At, B0); PG8_MMA(0, 1, At, B1); PG8_BAR; PG8_SCHED;
;             PG8_LDA(At, 0, 1); PG8_STAGE(PG8_SB(0, 0), b2, voffB); PG8_STAGE(PG8_SB(0, 1), b2 + hstepB, voffB); PG8_STAGE(PG8_SA(0, 0), a2, voffA);
;             PG8_WAIT_V(8); PG8_WAIT_L(0); PG8_BAR; PG8_MMA(1, 0, At, B0); PG8_MMA(1, 1, At, B1); PG8_BAR; PG8_SCHED;
;             PG8_LDB(B0, 1, 0); PG8_LDB(B1, 1, 1); PG8_SCHED; PG8_LDA(At, 1, 0); PG8_STAGE(PG8_SA(0, 1), a2 + hstepA, voffA);
;             PG8_WAIT_V(8); PG8_WAIT_L(0); PG8_BAR; PG8_MMA(0, 0, At, B0); PG8_MMA(0, 1, At, B1); PG8_BAR; PG8_SCHED;
;             PG8_LDA(At, 1, 1); PG8_STAGE(PG8_SB(1, 0), b3, voffB); PG8_STAGE(PG8_SB(1, 1), b3 + hstepB, voffB); PG8_STAGE(PG8_SA(1, 0), a3, voffA);
;             PG8_WAIT_V(8); PG8_WAIT_L(0); PG8_BAR; PG8_MMA(1, 0, At, B0); PG8_MMA(1, 1, At, B1); PG8_BAR; PG8_SCHED;
	s_setprio 0
	s_add_i32 s82, 0, 0x18000
	s_add_i32 s83, 0, 0x1c000
	ds_read_b128 v[130:133], v159
	ds_read_b128 v[134:137], v159 offset:1024
	ds_read_b128 v[138:141], v159 offset:2048
	ds_read_b128 v[142:145], v159 offset:3072
	ds_read_b128 v[146:149], v161
	ds_read_b128 v[150:153], v161 offset:1024
	ds_read_b128 v[182:185], v161 offset:2048
	ds_read_b128 v[186:189], v161 offset:3072
	s_add_u32 s52, s52, s8
	s_addc_u32 s53, s53, 0
	s_mov_b32 m0, s22
	ds_read_b128 v[190:193], v204 offset:32768
	ds_read_b128 v[194:197], v204 offset:33792
	ds_read_b128 v[206:209], v204 offset:34816
	ds_read_b128 v[210:213], v204 offset:35840
	ds_read_b128 v[214:217], v204 offset:36864
	ds_read_b128 v[218:221], v204 offset:37888
	ds_read_b128 v[222:225], v204 offset:38912
	ds_read_b128 v[226:229], v204 offset:39936
	global_load_lds_dwordx4 v154, s[52:53]
	s_mov_b32 m0, s23
	s_nop 0
	global_load_lds_dwordx4 v158, s[52:53]
	s_waitcnt vmcnt(8)
	s_waitcnt lgkmcnt(0)
	s_setprio 1
	s_barrier
	v_mfma_f32_16x16x32_f16 v[122:125], v[130:133], v[190:193], v[122:125]
	v_mfma_f32_16x16x32_f16 v[126:129], v[138:141], v[190:193], v[126:129]
	v_mfma_f32_16x16x32_f16 v[110:113], v[130:133], v[206:209], v[110:113]
	v_mfma_f32_16x16x32_f16 v[106:109], v[138:141], v[206:209], v[106:109]
	v_mfma_f32_16x16x32_f16 v[94:97], v[130:133], v[214:217], v[94:97]
	v_mfma_f32_16x16x32_f16 v[90:93], v[138:141], v[214:217], v[90:93]
	v_mfma_f32_16x16x32_f16 v[78:81], v[130:133], v[222:225], v[78:81]
	v_mfma_f32_16x16x32_f16 v[74:77], v[138:141], v[222:225], v[74:77]
	v_mfma_f32_16x16x32_f16 v[122:125], v[134:137], v[194:197], v[122:125]
	v_mfma_f32_16x16x32_f16 v[126:129], v[142:145], v[194:197], v[126:129]
	v_mfma_f32_16x16x32_f16 v[110:113], v[134:137], v[210:213], v[110:113]
	v_mfma_f32_16x16x32_f16 v[106:109], v[142:145], v[210:213], v[106:109]
	v_mfma_f32_16x16x32_f16 v[94:97], v[134:137], v[218:221], v[94:97]
	v_mfma_f32_16x16x32_f16 v[90:93], v[142:145], v[218:221], v[90:93]
	v_mfma_f32_16x16x32_f16 v[78:81], v[134:137], v[226:229], v[78:81]
	v_mfma_f32_16x16x32_f16 v[74:77], v[142:145], v[226:229], v[74:77]
	v_mfma_f32_16x16x32_f16 v[118:121], v[146:149], v[190:193], v[118:121]
	v_mfma_f32_16x16x32_f16 v[114:117], v[182:185], v[190:193], v[114:117]
	v_mfma_f32_16x16x32_f16 v[102:105], v[146:149], v[206:209], v[102:105]
	v_mfma_f32_16x16x32_f16 v[98:101], v[182:185], v[206:209], v[98:101]
	v_mfma_f32_16x16x32_f16 v[86:89], v[146:149], v[214:217], v[86:89]
	v_mfma_f32_16x16x32_f16 v[82:85], v[182:185], v[214:217], v[82:85]
	v_mfma_f32_16x16x32_f16 v[70:73], v[146:149], v[222:225], v[70:73]
	v_mfma_f32_16x16x32_f16 v[66:69], v[182:185], v[222:225], v[66:69]
	v_mfma_f32_16x16x32_f16 v[118:121], v[150:153], v[194:197], v[118:121]
	v_mfma_f32_16x16x32_f16 v[114:117], v[186:189], v[194:197], v[114:117]
	v_mfma_f32_16x16x32_f16 v[102:105], v[150:153], v[210:213], v[102:105]
	v_mfma_f32_16x16x32_f16 v[98:101], v[186:189], v[210:213], v[98:101]
	v_mfma_f32_16x16x32_f16 v[86:89], v[150:153], v[218:221], v[86:89]
	v_mfma_f32_16x16x32_f16 v[82:85], v[186:189], v[218:221], v[82:85]
	v_mfma_f32_16x16x32_f16 v[70:73], v[150:153], v[226:229], v[70:73]
	v_mfma_f32_16x16x32_f16 v[66:69], v[186:189], v[226:229], v[66:69]
	s_barrier
	s_setprio 0
	s_add_i32 s52, s82, s75
	s_add_i32 vcc_hi, s73, -2
	s_cmp_eq_u32 s74, vcc_hi
	s_cselect_b32 s99, s55, s72
	s_cselect_b32 s98, s54, s24
	s_add_u32 s98, s98, s92
	s_addc_u32 s99, s99, s93
	s_mov_b32 m0, s52
	s_nop 0
	global_load_lds_dwordx4 v156, s[98:99]
	ds_read_b128 v[190:193], v204 offset:49152
	ds_read_b128 v[194:197], v204 offset:50176
	ds_read_b128 v[206:209], v204 offset:51200
	ds_read_b128 v[210:213], v204 offset:52224
	ds_read_b128 v[214:217], v204 offset:53248
	ds_read_b128 v[218:221], v204 offset:54272
	ds_read_b128 v[222:225], v204 offset:55296
	ds_read_b128 v[226:229], v204 offset:56320
	s_add_i32 m0, s52, 0x2000
	s_nop 0
	global_load_lds_dwordx4 v160, s[98:99]
	s_add_i32 s52, s83, s75
	s_add_u32 s98, s98, s48
	s_addc_u32 s99, s99, 0
	s_mov_b32 m0, s52
	s_nop 0
	global_load_lds_dwordx4 v156, s[98:99]
	s_add_i32 m0, s52, 0x2000
	s_nop 0
	global_load_lds_dwordx4 v160, s[98:99]
	s_add_u32 s98, s44, 0x80
	s_addc_u32 s99, s45, 0
	s_cmp_eq_u32 s74, vcc_hi
	s_cselect_b32 s99, s79, s99
	s_cselect_b32 s98, s78, s98
	s_add_u32 s98, s98, s92
	s_addc_u32 s99, s99, s93
	s_mov_b32 m0, s61
	s_nop 0
	global_load_lds_dwordx4 v154, s[98:99]
	s_mov_b32 m0, s18
	s_nop 0
	global_load_lds_dwordx4 v158, s[98:99]
	s_waitcnt vmcnt(8)
	s_waitcnt lgkmcnt(0)
	s_setprio 1
	s_barrier
	v_mfma_f32_16x16x32_f16 v[62:65], v[130:133], v[190:193], v[62:65]
	v_mfma_f32_16x16x32_f16 v[58:61], v[138:141], v[190:193], v[58:61]
	v_mfma_f32_16x16x32_f16 v[46:49], v[130:133], v[206:209], v[46:49]
	v_mfma_f32_16x16x32_f16 v[42:45], v[138:141], v[206:209], v[42:45]
	v_mfma_f32_16x16x32_f16 v[30:33], v[130:133], v[214:217], v[30:33]
	v_mfma_f32_16x16x32_f16 v[26:29], v[138:141], v[214:217], v[26:29]
	v_mfma_f32_16x16x32_f16 v[14:17], v[130:133], v[222:225], v[14:17]
	v_mfma_f32_16x16x32_f16 v[10:13], v[138:141], v[222:225], v[10:13]
	v_mfma_f32_16x16x32_f16 v[62:65], v[134:137], v[194:197], v[62:65]
	v_mfma_f32_16x16x32_f16 v[58:61], v[142:145], v[194:197], v[58:61]
	v_mfma_f32_16x16x32_f16 v[46:49], v[134:137], v[210:213], v[46:49]
	v_mfma_f32_16x16x32_f16 v[42:45], v[142:145], v[210:213], v[42:45]
	v_mfma_f32_16x16x32_f16 v[30:33], v[134:137], v[218:221], v[30:33]
	v_mfma_f32_16x16x32_f16 v[26:29], v[142:145], v[218:221], v[26:29]
	v_mfma_f32_16x16x32_f16 v[14:17], v[134:137], v[226:229], v[14:17]
	v_mfma_f32_16x16x32_f16 v[10:13], v[142:145], v[226:229], v[10:13]
	v_mfma_f32_16x16x32_f16 v[54:57], v[146:149], v[190:193], v[54:57]
	v_mfma_f32_16x16x32_f16 v[50:53], v[182:185], v[190:193], v[50:53]
	v_mfma_f32_16x16x32_f16 v[38:41], v[146:149], v[206:209], v[38:41]
	v_mfma_f32_16x16x32_f16 v[34:37], v[182:185], v[206:209], v[34:37]
	v_mfma_f32_16x16x32_f16 v[22:25], v[146:149], v[214:217], v[22:25]
	v_mfma_f32_16x16x32_f16 v[18:21], v[182:185], v[214:217], v[18:21]
	v_mfma_f32_16x16x32_f16 v[6:9], v[146:149], v[222:225], v[6:9]
	v_mfma_f32_16x16x32_f16 v[2:5], v[182:185], v[222:225], v[2:5]
	v_mfma_f32_16x16x32_f16 v[54:57], v[150:153], v[194:197], v[54:57]
	v_mfma_f32_16x16x32_f16 v[50:53], v[186:189], v[194:197], v[50:53]
	v_mfma_f32_16x16x32_f16 v[38:41], v[150:153], v[210:213], v[38:41]
	v_mfma_f32_16x16x32_f16 v[34:37], v[186:189], v[210:213], v[34:37]
	v_mfma_f32_16x16x32_f16 v[22:25], v[150:153], v[218:221], v[22:25]
	v_mfma_f32_16x16x32_f16 v[18:21], v[186:189], v[218:221], v[18:21]
	v_mfma_f32_16x16x32_f16 v[6:9], v[150:153], v[226:229], v[6:9]
	v_mfma_f32_16x16x32_f16 v[2:5], v[186:189], v[226:229], v[2:5]
	s_barrier
	s_setprio 0
	s_add_u32 s44, s44, 0x100
	s_addc_u32 s45, s45, 0
	s_add_u32 s24, s24, 0x100
	s_addc_u32 s72, s72, 0
	s_cmp_ge_u32 s73, s65
	s_mov_b32 s52, s73
	s_cbranch_scc0 .LBB0_564
